# GEMM mainloop with a priority drop every 8 MFMAs instead of one per segment, on top of mixing edits
# baseline (speedup 1.0000x reference)
.LBB0_41:
	s_add_u32 s40, s36, 0xfffc0080
	s_addc_u32 s41, s37, -1
	s_add_i32 s97, 0, 0x10000
	s_cmp_eq_u32 s90, 12
	s_cselect_b32 s47, s17, s41
	s_cselect_b32 s46, s68, s40
	v_add_u32_e32 v140, s97, v142
	s_cselect_b32 s45, s15, s89
	s_cselect_b32 s44, s69, s88
	s_add_i32 s40, 0, 0x14000
	ds_read_b128 v[146:149], v140
	ds_read_b128 v[150:153], v140 offset:1024
	ds_read_b128 v[154:157], v140 offset:2048
	ds_read_b128 v[158:161], v140 offset:3072
	v_add_u32_e32 v140, s40, v142
	ds_read_b128 v[162:165], v140
	ds_read_b128 v[166:169], v140 offset:1024
	ds_read_b128 v[170:173], v140 offset:2048
	ds_read_b128 v[174:177], v140 offset:3072
	v_lshl_add_u64 v[140:141], s[36:37], 0, v[136:137]
	s_add_i32 m0, s51, 0xc000
	ds_read_b128 v[190:193], v145
	ds_read_b128 v[194:197], v145 offset:1024
	ds_read_b128 v[198:201], v145 offset:2048
	ds_read_b128 v[202:205], v145 offset:3072
	ds_read_b128 v[206:209], v145 offset:4096
	ds_read_b128 v[228:231], v145 offset:5120
	ds_read_b128 v[232:235], v145 offset:6144
	ds_read_b128 v[236:239], v145 offset:7168
	global_load_lds_dwordx4 v[140:141], off
	v_lshl_add_u64 v[140:141], s[36:37], 0, v[138:139]
	s_add_i32 m0, s51, 0xe000
	s_nop 0
	global_load_lds_dwordx4 v[140:141], off
	s_waitcnt vmcnt(8)
	s_waitcnt lgkmcnt(0)
	s_barrier
	s_setprio 1
	s_waitcnt lgkmcnt(0)
	v_mfma_f32_16x16x32_bf16 v[124:127], v[146:149], v[190:193], v[124:127]
	v_mfma_f32_16x16x32_bf16 v[116:119], v[154:157], v[190:193], v[116:119]
	v_mfma_f32_16x16x32_bf16 v[108:111], v[146:149], v[198:201], v[108:111]
	v_mfma_f32_16x16x32_bf16 v[100:103], v[154:157], v[198:201], v[100:103]
	v_mfma_f32_16x16x32_bf16 v[92:95], v[146:149], v[206:209], v[92:95]
	v_mfma_f32_16x16x32_bf16 v[84:87], v[154:157], v[206:209], v[84:87]
	v_mfma_f32_16x16x32_bf16 v[76:79], v[146:149], v[232:235], v[76:79]
	v_mfma_f32_16x16x32_bf16 v[68:71], v[154:157], v[232:235], v[68:71]
	s_setprio 0
	s_setprio 1
	v_mfma_f32_16x16x32_bf16 v[124:127], v[150:153], v[194:197], v[124:127]
	v_mfma_f32_16x16x32_bf16 v[116:119], v[158:161], v[194:197], v[116:119]
	v_mfma_f32_16x16x32_bf16 v[108:111], v[150:153], v[202:205], v[108:111]
	v_mfma_f32_16x16x32_bf16 v[100:103], v[158:161], v[202:205], v[100:103]
	v_mfma_f32_16x16x32_bf16 v[92:95], v[150:153], v[228:231], v[92:95]
	v_mfma_f32_16x16x32_bf16 v[84:87], v[158:161], v[228:231], v[84:87]
	v_mfma_f32_16x16x32_bf16 v[76:79], v[150:153], v[236:239], v[76:79]
	v_mfma_f32_16x16x32_bf16 v[68:71], v[158:161], v[236:239], v[68:71]
	s_setprio 0
	s_setprio 1
	v_mfma_f32_16x16x32_bf16 v[128:131], v[162:165], v[190:193], v[128:131]
	v_mfma_f32_16x16x32_bf16 v[120:123], v[170:173], v[190:193], v[120:123]
	v_mfma_f32_16x16x32_bf16 v[112:115], v[162:165], v[198:201], v[112:115]
	v_mfma_f32_16x16x32_bf16 v[104:107], v[170:173], v[198:201], v[104:107]
	v_mfma_f32_16x16x32_bf16 v[96:99], v[162:165], v[206:209], v[96:99]
	v_mfma_f32_16x16x32_bf16 v[88:91], v[170:173], v[206:209], v[88:91]
	v_mfma_f32_16x16x32_bf16 v[80:83], v[162:165], v[232:235], v[80:83]
	v_mfma_f32_16x16x32_bf16 v[72:75], v[170:173], v[232:235], v[72:75]
	s_setprio 0
	s_setprio 1
	v_mfma_f32_16x16x32_bf16 v[128:131], v[166:169], v[194:197], v[128:131]
	v_mfma_f32_16x16x32_bf16 v[120:123], v[174:177], v[194:197], v[120:123]
	v_mfma_f32_16x16x32_bf16 v[112:115], v[166:169], v[202:205], v[112:115]
	v_mfma_f32_16x16x32_bf16 v[104:107], v[174:177], v[202:205], v[104:107]
	v_mfma_f32_16x16x32_bf16 v[96:99], v[166:169], v[228:231], v[96:99]
	v_mfma_f32_16x16x32_bf16 v[88:91], v[174:177], v[228:231], v[88:91]
	v_mfma_f32_16x16x32_bf16 v[80:83], v[166:169], v[236:239], v[80:83]
	v_mfma_f32_16x16x32_bf16 v[72:75], v[174:177], v[236:239], v[72:75]
	s_setprio 0
	s_barrier
	s_add_i32 s41, s97, s50
	v_lshl_add_u64 v[140:141], s[44:45], 0, v[180:181]
	s_mov_b32 m0, s41
	ds_read_b128 v[190:193], v145 offset:16384
	ds_read_b128 v[194:197], v145 offset:17408
	ds_read_b128 v[198:201], v145 offset:18432
	ds_read_b128 v[202:205], v145 offset:19456
	ds_read_b128 v[206:209], v145 offset:20480
	ds_read_b128 v[228:231], v145 offset:21504
	ds_read_b128 v[232:235], v145 offset:22528
	ds_read_b128 v[236:239], v145 offset:23552
	global_load_lds_dwordx4 v[140:141], off
	s_add_i32 m0, s41, 0x2000
	s_add_u32 vcc_lo, s44, 0x40000
	v_lshl_add_u64 v[178:179], s[44:45], 0, v[134:135]
	s_addc_u32 vcc_hi, s45, 0
	s_add_i32 s40, s40, s50
	global_load_lds_dwordx4 v[178:179], off
	v_lshl_add_u64 v[210:211], vcc, 0, v[180:181]
	s_mov_b32 m0, s40
	v_lshl_add_u64 v[218:219], s[46:47], 0, v[132:133]
	global_load_lds_dwordx4 v[210:211], off
	v_lshl_add_u64 v[210:211], vcc, 0, v[134:135]
	s_add_i32 m0, s40, 0x2000
	s_nop 0
	global_load_lds_dwordx4 v[210:211], off
	v_lshl_add_u64 v[210:211], s[46:47], 0, v[0:1]
	s_mov_b32 m0, s51
	s_nop 0
	global_load_lds_dwordx4 v[210:211], off
	s_mov_b32 m0, s52
	s_nop 0
	global_load_lds_dwordx4 v[218:219], off
	s_waitcnt vmcnt(8)
	s_waitcnt lgkmcnt(0)
	s_barrier
	s_setprio 1
	s_waitcnt lgkmcnt(0)
	v_mfma_f32_16x16x32_bf16 v[60:63], v[146:149], v[190:193], v[60:63]
	v_mfma_f32_16x16x32_bf16 v[52:55], v[154:157], v[190:193], v[52:55]
	v_mfma_f32_16x16x32_bf16 v[44:47], v[146:149], v[198:201], v[44:47]
	v_mfma_f32_16x16x32_bf16 v[36:39], v[154:157], v[198:201], v[36:39]
	v_mfma_f32_16x16x32_bf16 v[28:31], v[146:149], v[206:209], v[28:31]
	v_mfma_f32_16x16x32_bf16 v[20:23], v[154:157], v[206:209], v[20:23]
	v_mfma_f32_16x16x32_bf16 v[12:15], v[146:149], v[232:235], v[12:15]
	v_mfma_f32_16x16x32_bf16 v[8:11], v[154:157], v[232:235], v[8:11]
	s_setprio 0
	s_setprio 1
	v_mfma_f32_16x16x32_bf16 v[60:63], v[150:153], v[194:197], v[60:63]
	v_mfma_f32_16x16x32_bf16 v[52:55], v[158:161], v[194:197], v[52:55]
	v_mfma_f32_16x16x32_bf16 v[44:47], v[150:153], v[202:205], v[44:47]
	v_mfma_f32_16x16x32_bf16 v[36:39], v[158:161], v[202:205], v[36:39]
	v_mfma_f32_16x16x32_bf16 v[28:31], v[150:153], v[228:231], v[28:31]
	v_mfma_f32_16x16x32_bf16 v[20:23], v[158:161], v[228:231], v[20:23]
	v_mfma_f32_16x16x32_bf16 v[12:15], v[150:153], v[236:239], v[12:15]
	v_mfma_f32_16x16x32_bf16 v[8:11], v[158:161], v[236:239], v[8:11]
	s_setprio 0
	s_setprio 1
	v_mfma_f32_16x16x32_bf16 v[64:67], v[162:165], v[190:193], v[64:67]
	v_mfma_f32_16x16x32_bf16 v[56:59], v[170:173], v[190:193], v[56:59]
	v_mfma_f32_16x16x32_bf16 v[48:51], v[162:165], v[198:201], v[48:51]
	v_mfma_f32_16x16x32_bf16 v[40:43], v[170:173], v[198:201], v[40:43]
	v_mfma_f32_16x16x32_bf16 v[32:35], v[162:165], v[206:209], v[32:35]
	v_mfma_f32_16x16x32_bf16 v[24:27], v[170:173], v[206:209], v[24:27]
	v_mfma_f32_16x16x32_bf16 v[16:19], v[162:165], v[232:235], v[16:19]
	v_mfma_f32_16x16x32_bf16 v[4:7], v[170:173], v[232:235], v[4:7]
	s_setprio 0
	s_setprio 1
	v_mfma_f32_16x16x32_bf16 v[64:67], v[166:169], v[194:197], v[64:67]
	v_mfma_f32_16x16x32_bf16 v[56:59], v[174:177], v[194:197], v[56:59]
	v_mfma_f32_16x16x32_bf16 v[48:51], v[166:169], v[202:205], v[48:51]
	v_mfma_f32_16x16x32_bf16 v[40:43], v[174:177], v[202:205], v[40:43]
	v_mfma_f32_16x16x32_bf16 v[32:35], v[166:169], v[228:231], v[32:35]
	v_mfma_f32_16x16x32_bf16 v[24:27], v[174:177], v[228:231], v[24:27]
	v_mfma_f32_16x16x32_bf16 v[16:19], v[166:169], v[236:239], v[16:19]
	v_mfma_f32_16x16x32_bf16 v[4:7], v[174:177], v[236:239], v[4:7]
	s_setprio 0
	s_barrier
	s_add_i32 s40, 0, 0x18000
	s_add_i32 s41, 0, 0x1c000
	v_add_u32_e32 v158, s40, v142
	v_add_u32_e32 v174, s41, v142
	ds_read_b128 v[146:149], v158
	ds_read_b128 v[150:153], v158 offset:1024
	ds_read_b128 v[154:157], v158 offset:2048
	ds_read_b128 v[158:161], v158 offset:3072
	ds_read_b128 v[162:165], v174
	ds_read_b128 v[166:169], v174 offset:1024
	ds_read_b128 v[170:173], v174 offset:2048
	ds_read_b128 v[174:177], v174 offset:3072
	s_add_u32 s46, s46, 0x40000
	s_addc_u32 s47, s47, 0
	s_mov_b32 m0, s53
	v_lshl_add_u64 v[220:221], s[46:47], 0, v[0:1]
	ds_read_b128 v[190:193], v145 offset:32768
	ds_read_b128 v[194:197], v145 offset:33792
	ds_read_b128 v[198:201], v145 offset:34816
	ds_read_b128 v[202:205], v145 offset:35840
	ds_read_b128 v[206:209], v145 offset:36864
	ds_read_b128 v[228:231], v145 offset:37888
	ds_read_b128 v[232:235], v145 offset:38912
	ds_read_b128 v[236:239], v145 offset:39936
	global_load_lds_dwordx4 v[220:221], off
	v_lshl_add_u64 v[220:221], s[46:47], 0, v[132:133]
	s_mov_b32 m0, s54
	s_nop 0
	global_load_lds_dwordx4 v[220:221], off
	s_waitcnt vmcnt(8)
	s_waitcnt lgkmcnt(0)
	s_barrier
	s_setprio 1
	s_waitcnt lgkmcnt(0)
	v_mfma_f32_16x16x32_bf16 v[124:127], v[146:149], v[190:193], v[124:127]
	v_mfma_f32_16x16x32_bf16 v[116:119], v[154:157], v[190:193], v[116:119]
	v_mfma_f32_16x16x32_bf16 v[108:111], v[146:149], v[198:201], v[108:111]
	v_mfma_f32_16x16x32_bf16 v[100:103], v[154:157], v[198:201], v[100:103]
	v_mfma_f32_16x16x32_bf16 v[92:95], v[146:149], v[206:209], v[92:95]
	v_mfma_f32_16x16x32_bf16 v[84:87], v[154:157], v[206:209], v[84:87]
	v_mfma_f32_16x16x32_bf16 v[76:79], v[146:149], v[232:235], v[76:79]
	v_mfma_f32_16x16x32_bf16 v[68:71], v[154:157], v[232:235], v[68:71]
	s_setprio 0
	s_setprio 1
	v_mfma_f32_16x16x32_bf16 v[124:127], v[150:153], v[194:197], v[124:127]
	v_mfma_f32_16x16x32_bf16 v[116:119], v[158:161], v[194:197], v[116:119]
	v_mfma_f32_16x16x32_bf16 v[108:111], v[150:153], v[202:205], v[108:111]
	v_mfma_f32_16x16x32_bf16 v[100:103], v[158:161], v[202:205], v[100:103]
	v_mfma_f32_16x16x32_bf16 v[92:95], v[150:153], v[228:231], v[92:95]
	v_mfma_f32_16x16x32_bf16 v[84:87], v[158:161], v[228:231], v[84:87]
	v_mfma_f32_16x16x32_bf16 v[76:79], v[150:153], v[236:239], v[76:79]
	v_mfma_f32_16x16x32_bf16 v[68:71], v[158:161], v[236:239], v[68:71]
	s_setprio 0
	s_setprio 1
	v_mfma_f32_16x16x32_bf16 v[128:131], v[162:165], v[190:193], v[128:131]
	v_mfma_f32_16x16x32_bf16 v[120:123], v[170:173], v[190:193], v[120:123]
	v_mfma_f32_16x16x32_bf16 v[112:115], v[162:165], v[198:201], v[112:115]
	v_mfma_f32_16x16x32_bf16 v[104:107], v[170:173], v[198:201], v[104:107]
	v_mfma_f32_16x16x32_bf16 v[96:99], v[162:165], v[206:209], v[96:99]
	v_mfma_f32_16x16x32_bf16 v[88:91], v[170:173], v[206:209], v[88:91]
	v_mfma_f32_16x16x32_bf16 v[80:83], v[162:165], v[232:235], v[80:83]
	v_mfma_f32_16x16x32_bf16 v[72:75], v[170:173], v[232:235], v[72:75]
	s_setprio 0
	s_setprio 1
	v_mfma_f32_16x16x32_bf16 v[128:131], v[166:169], v[194:197], v[128:131]
	v_mfma_f32_16x16x32_bf16 v[120:123], v[174:177], v[194:197], v[120:123]
	v_mfma_f32_16x16x32_bf16 v[112:115], v[166:169], v[202:205], v[112:115]
	v_mfma_f32_16x16x32_bf16 v[104:107], v[174:177], v[202:205], v[104:107]
	v_mfma_f32_16x16x32_bf16 v[96:99], v[166:169], v[228:231], v[96:99]
	v_mfma_f32_16x16x32_bf16 v[88:91], v[174:177], v[228:231], v[88:91]
	v_mfma_f32_16x16x32_bf16 v[80:83], v[166:169], v[236:239], v[80:83]
	v_mfma_f32_16x16x32_bf16 v[72:75], v[174:177], v[236:239], v[72:75]
	s_setprio 0
	s_barrier
	s_add_i32 s40, s40, s50
	v_lshl_add_u64 v[140:141], v[140:141], 0, s[94:95]
	s_mov_b32 m0, s40
	ds_read_b128 v[190:193], v145 offset:49152
	ds_read_b128 v[194:197], v145 offset:50176
	ds_read_b128 v[198:201], v145 offset:51200
	ds_read_b128 v[202:205], v145 offset:52224
	ds_read_b128 v[206:209], v145 offset:53248
	ds_read_b128 v[228:231], v145 offset:54272
	ds_read_b128 v[232:235], v145 offset:55296
	ds_read_b128 v[236:239], v145 offset:56320
	global_load_lds_dwordx4 v[140:141], off
	s_add_i32 m0, s40, 0x2000
	s_add_u32 s44, s44, 0x40080
	v_lshl_add_u64 v[140:141], v[178:179], 0, s[94:95]
	s_addc_u32 s45, s45, 0
	s_add_i32 s40, s41, s50
	global_load_lds_dwordx4 v[140:141], off
	v_lshl_add_u64 v[140:141], s[44:45], 0, v[180:181]
	s_mov_b32 m0, s40
	s_nop 0
	global_load_lds_dwordx4 v[140:141], off
	v_lshl_add_u64 v[140:141], s[44:45], 0, v[134:135]
	s_add_i32 m0, s40, 0x2000
	s_nop 0
	global_load_lds_dwordx4 v[140:141], off
	v_lshl_add_u64 v[140:141], v[210:211], 0, s[94:95]
	s_mov_b32 m0, s55
	s_nop 0
	global_load_lds_dwordx4 v[140:141], off
	v_lshl_add_u64 v[140:141], v[218:219], 0, s[94:95]
	s_mov_b32 m0, s58
	s_nop 0
	global_load_lds_dwordx4 v[140:141], off
	s_waitcnt vmcnt(8)
	s_waitcnt lgkmcnt(0)
	s_barrier
	s_setprio 1
	s_waitcnt lgkmcnt(0)
	v_mfma_f32_16x16x32_bf16 v[60:63], v[146:149], v[190:193], v[60:63]
	v_mfma_f32_16x16x32_bf16 v[52:55], v[154:157], v[190:193], v[52:55]
	v_mfma_f32_16x16x32_bf16 v[44:47], v[146:149], v[198:201], v[44:47]
	v_mfma_f32_16x16x32_bf16 v[36:39], v[154:157], v[198:201], v[36:39]
	v_mfma_f32_16x16x32_bf16 v[28:31], v[146:149], v[206:209], v[28:31]
	v_mfma_f32_16x16x32_bf16 v[20:23], v[154:157], v[206:209], v[20:23]
	v_mfma_f32_16x16x32_bf16 v[12:15], v[146:149], v[232:235], v[12:15]
	v_mfma_f32_16x16x32_bf16 v[8:11], v[154:157], v[232:235], v[8:11]
	s_setprio 0
	s_setprio 1
	v_mfma_f32_16x16x32_bf16 v[60:63], v[150:153], v[194:197], v[60:63]
	v_mfma_f32_16x16x32_bf16 v[52:55], v[158:161], v[194:197], v[52:55]
	v_mfma_f32_16x16x32_bf16 v[44:47], v[150:153], v[202:205], v[44:47]
	v_mfma_f32_16x16x32_bf16 v[36:39], v[158:161], v[202:205], v[36:39]
	v_mfma_f32_16x16x32_bf16 v[28:31], v[150:153], v[228:231], v[28:31]
	v_mfma_f32_16x16x32_bf16 v[20:23], v[158:161], v[228:231], v[20:23]
	v_mfma_f32_16x16x32_bf16 v[12:15], v[150:153], v[236:239], v[12:15]
	v_mfma_f32_16x16x32_bf16 v[8:11], v[158:161], v[236:239], v[8:11]
	s_setprio 0
	s_setprio 1
	v_mfma_f32_16x16x32_bf16 v[64:67], v[162:165], v[190:193], v[64:67]
	v_mfma_f32_16x16x32_bf16 v[56:59], v[170:173], v[190:193], v[56:59]
	v_mfma_f32_16x16x32_bf16 v[48:51], v[162:165], v[198:201], v[48:51]
	v_mfma_f32_16x16x32_bf16 v[40:43], v[170:173], v[198:201], v[40:43]
	v_mfma_f32_16x16x32_bf16 v[32:35], v[162:165], v[206:209], v[32:35]
	v_mfma_f32_16x16x32_bf16 v[24:27], v[170:173], v[206:209], v[24:27]
	v_mfma_f32_16x16x32_bf16 v[16:19], v[162:165], v[232:235], v[16:19]
	v_mfma_f32_16x16x32_bf16 v[4:7], v[170:173], v[232:235], v[4:7]
	s_setprio 0
	s_setprio 1
	v_mfma_f32_16x16x32_bf16 v[64:67], v[166:169], v[194:197], v[64:67]
	v_mfma_f32_16x16x32_bf16 v[56:59], v[174:177], v[194:197], v[56:59]
	v_mfma_f32_16x16x32_bf16 v[48:51], v[166:169], v[202:205], v[48:51]
	v_mfma_f32_16x16x32_bf16 v[40:43], v[174:177], v[202:205], v[40:43]
	v_mfma_f32_16x16x32_bf16 v[32:35], v[166:169], v[228:231], v[32:35]
	v_mfma_f32_16x16x32_bf16 v[24:27], v[174:177], v[228:231], v[24:27]
	v_mfma_f32_16x16x32_bf16 v[16:19], v[166:169], v[236:239], v[16:19]
	v_mfma_f32_16x16x32_bf16 v[4:7], v[174:177], v[236:239], v[4:7]
	s_setprio 0
	s_barrier
	s_add_i32 s90, s90, 2
	s_add_u32 s36, s36, 0x100
	s_addc_u32 s37, s37, 0
	s_add_u32 s88, s88, 0x100
	s_addc_u32 s89, s89, 0
	s_cmp_gt_u32 s90, 13
	s_cbranch_scc0 .LBB0_41
	s_and_b64 vcc, exec, s[10:11]
	s_cbranch_vccz .LBB0_44
	s_barrier

.LBB0_83:
	s_add_u32 s10, s8, 0xfffc0080
	s_addc_u32 s11, s9, -1
	s_add_i32 s40, 0, 0x10000
	s_cmp_eq_u32 vcc_hi, 12
	s_cselect_b32 s53, s27, s11
	s_cselect_b32 s52, s89, s10
	s_cselect_b32 s11, s19, vcc_lo
	s_cselect_b32 s10, s90, s97
	s_add_i32 s25, 0, 0x14000
	v_add_u32_e32 v144, s40, v159
	v_add_u32_e32 v158, s25, v159
	ds_read_b128 v[132:135], v144
	ds_read_b128 v[136:139], v144 offset:1024
	ds_read_b128 v[140:143], v144 offset:2048
	ds_read_b128 v[144:147], v144 offset:3072
	ds_read_b128 v[190:193], v158
	ds_read_b128 v[194:197], v158 offset:1024
	ds_read_b128 v[198:201], v158 offset:2048
	ds_read_b128 v[202:205], v158 offset:3072
	v_lshl_add_u64 v[174:175], s[8:9], 0, v[154:155]
	s_add_i32 m0, s49, 0xc000
	ds_read_b128 v[206:209], v179
	ds_read_b128 v[228:231], v179 offset:1024
	ds_read_b128 v[232:235], v179 offset:2048
	ds_read_b128 v[236:239], v179 offset:3072
	ds_read_b128 v[240:243], v179 offset:4096
	ds_read_b128 v[244:247], v179 offset:5120
	ds_read_b128 v[224:227], v179 offset:6144
	ds_read_b128 v[218:221], v179 offset:7168
	global_load_lds_dwordx4 v[174:175], off
	v_lshl_add_u64 v[174:175], s[8:9], 0, v[156:157]
	s_add_i32 m0, s49, 0xe000
	s_nop 0
	global_load_lds_dwordx4 v[174:175], off
	s_waitcnt vmcnt(8)
	s_waitcnt lgkmcnt(0)
	s_barrier
	s_setprio 1
	s_waitcnt lgkmcnt(0)
	v_mfma_f32_16x16x32_bf16 v[128:131], v[132:135], v[206:209], v[128:131]
	v_mfma_f32_16x16x32_bf16 v[124:127], v[140:143], v[206:209], v[124:127]
	v_mfma_f32_16x16x32_bf16 v[112:115], v[132:135], v[232:235], v[112:115]
	v_mfma_f32_16x16x32_bf16 v[108:111], v[140:143], v[232:235], v[108:111]
	v_mfma_f32_16x16x32_bf16 v[96:99], v[132:135], v[240:243], v[96:99]
	v_mfma_f32_16x16x32_bf16 v[92:95], v[140:143], v[240:243], v[92:95]
	v_mfma_f32_16x16x32_bf16 v[80:83], v[132:135], v[224:227], v[80:83]
	v_mfma_f32_16x16x32_bf16 v[76:79], v[140:143], v[224:227], v[76:79]
	s_setprio 0
	s_setprio 1
	v_mfma_f32_16x16x32_bf16 v[128:131], v[136:139], v[228:231], v[128:131]
	v_mfma_f32_16x16x32_bf16 v[124:127], v[144:147], v[228:231], v[124:127]
	v_mfma_f32_16x16x32_bf16 v[112:115], v[136:139], v[236:239], v[112:115]
	v_mfma_f32_16x16x32_bf16 v[108:111], v[144:147], v[236:239], v[108:111]
	v_mfma_f32_16x16x32_bf16 v[96:99], v[136:139], v[244:247], v[96:99]
	v_mfma_f32_16x16x32_bf16 v[92:95], v[144:147], v[244:247], v[92:95]
	v_mfma_f32_16x16x32_bf16 v[80:83], v[136:139], v[218:221], v[80:83]
	v_mfma_f32_16x16x32_bf16 v[76:79], v[144:147], v[218:221], v[76:79]
	s_setprio 0
	s_setprio 1
	v_mfma_f32_16x16x32_bf16 v[120:123], v[190:193], v[206:209], v[120:123]
	v_mfma_f32_16x16x32_bf16 v[116:119], v[198:201], v[206:209], v[116:119]
	v_mfma_f32_16x16x32_bf16 v[104:107], v[190:193], v[232:235], v[104:107]
	v_mfma_f32_16x16x32_bf16 v[100:103], v[198:201], v[232:235], v[100:103]
	v_mfma_f32_16x16x32_bf16 v[88:91], v[190:193], v[240:243], v[88:91]
	v_mfma_f32_16x16x32_bf16 v[84:87], v[198:201], v[240:243], v[84:87]
	v_mfma_f32_16x16x32_bf16 v[72:75], v[190:193], v[224:227], v[72:75]
	v_mfma_f32_16x16x32_bf16 v[68:71], v[198:201], v[224:227], v[68:71]
	s_setprio 0
	s_setprio 1
	v_mfma_f32_16x16x32_bf16 v[120:123], v[194:197], v[228:231], v[120:123]
	v_mfma_f32_16x16x32_bf16 v[116:119], v[202:205], v[228:231], v[116:119]
	v_mfma_f32_16x16x32_bf16 v[104:107], v[194:197], v[236:239], v[104:107]
	v_mfma_f32_16x16x32_bf16 v[100:103], v[202:205], v[236:239], v[100:103]
	v_mfma_f32_16x16x32_bf16 v[88:91], v[194:197], v[244:247], v[88:91]
	v_mfma_f32_16x16x32_bf16 v[84:87], v[202:205], v[244:247], v[84:87]
	v_mfma_f32_16x16x32_bf16 v[72:75], v[194:197], v[218:221], v[72:75]
	v_mfma_f32_16x16x32_bf16 v[68:71], v[202:205], v[218:221], v[68:71]
	s_setprio 0
	s_barrier
	s_add_i32 s40, s40, s55
	v_lshl_add_u64 v[174:175], s[10:11], 0, v[180:181]
	s_mov_b32 m0, s40
	ds_read_b128 v[206:209], v179 offset:16384
	ds_read_b128 v[218:221], v179 offset:17408
	ds_read_b128 v[224:227], v179 offset:18432
	ds_read_b128 v[228:231], v179 offset:19456
	ds_read_b128 v[232:235], v179 offset:20480
	ds_read_b128 v[236:239], v179 offset:21504
	ds_read_b128 v[240:243], v179 offset:22528
	ds_read_b128 v[244:247], v179 offset:23552
	global_load_lds_dwordx4 v[174:175], off
	s_add_i32 m0, s40, 0x2000
	s_add_u32 s40, s10, 0x40000
	v_lshl_add_u64 v[210:211], s[10:11], 0, v[150:151]
	s_addc_u32 s41, s11, 0
	s_add_i32 s25, s25, s55
	global_load_lds_dwordx4 v[210:211], off
	v_lshl_add_u64 v[248:249], s[40:41], 0, v[180:181]
	s_mov_b32 m0, s25
	v_lshl_add_u64 v[182:183], s[52:53], 0, v[148:149]
	global_load_lds_dwordx4 v[248:249], off
	v_lshl_add_u64 v[248:249], s[40:41], 0, v[150:151]
	s_add_i32 m0, s25, 0x2000
	s_nop 0
	global_load_lds_dwordx4 v[248:249], off
	v_lshl_add_u64 v[248:249], s[52:53], 0, v[0:1]
	s_mov_b32 m0, s49
	s_nop 0
	global_load_lds_dwordx4 v[248:249], off
	s_mov_b32 m0, s51
	s_nop 0
	global_load_lds_dwordx4 v[182:183], off
	s_waitcnt vmcnt(8)
	s_waitcnt lgkmcnt(0)
	s_barrier
	s_setprio 1
	s_waitcnt lgkmcnt(0)
	v_mfma_f32_16x16x32_bf16 v[64:67], v[132:135], v[206:209], v[64:67]
	v_mfma_f32_16x16x32_bf16 v[60:63], v[140:143], v[206:209], v[60:63]
	v_mfma_f32_16x16x32_bf16 v[48:51], v[132:135], v[224:227], v[48:51]
	v_mfma_f32_16x16x32_bf16 v[44:47], v[140:143], v[224:227], v[44:47]
	v_mfma_f32_16x16x32_bf16 v[32:35], v[132:135], v[232:235], v[32:35]
	v_mfma_f32_16x16x32_bf16 v[28:31], v[140:143], v[232:235], v[28:31]
	v_mfma_f32_16x16x32_bf16 v[16:19], v[132:135], v[240:243], v[16:19]
	v_mfma_f32_16x16x32_bf16 v[12:15], v[140:143], v[240:243], v[12:15]
	s_setprio 0
	s_setprio 1
	v_mfma_f32_16x16x32_bf16 v[64:67], v[136:139], v[218:221], v[64:67]
	v_mfma_f32_16x16x32_bf16 v[60:63], v[144:147], v[218:221], v[60:63]
	v_mfma_f32_16x16x32_bf16 v[48:51], v[136:139], v[228:231], v[48:51]
	v_mfma_f32_16x16x32_bf16 v[44:47], v[144:147], v[228:231], v[44:47]
	v_mfma_f32_16x16x32_bf16 v[32:35], v[136:139], v[236:239], v[32:35]
	v_mfma_f32_16x16x32_bf16 v[28:31], v[144:147], v[236:239], v[28:31]
	v_mfma_f32_16x16x32_bf16 v[16:19], v[136:139], v[244:247], v[16:19]
	v_mfma_f32_16x16x32_bf16 v[12:15], v[144:147], v[244:247], v[12:15]
	s_setprio 0
	s_setprio 1
	v_mfma_f32_16x16x32_bf16 v[56:59], v[190:193], v[206:209], v[56:59]
	v_mfma_f32_16x16x32_bf16 v[52:55], v[198:201], v[206:209], v[52:55]
	v_mfma_f32_16x16x32_bf16 v[40:43], v[190:193], v[224:227], v[40:43]
	v_mfma_f32_16x16x32_bf16 v[36:39], v[198:201], v[224:227], v[36:39]
	v_mfma_f32_16x16x32_bf16 v[24:27], v[190:193], v[232:235], v[24:27]
	v_mfma_f32_16x16x32_bf16 v[20:23], v[198:201], v[232:235], v[20:23]
	v_mfma_f32_16x16x32_bf16 v[8:11], v[190:193], v[240:243], v[8:11]
	v_mfma_f32_16x16x32_bf16 v[4:7], v[198:201], v[240:243], v[4:7]
	s_setprio 0
	s_setprio 1
	v_mfma_f32_16x16x32_bf16 v[56:59], v[194:197], v[218:221], v[56:59]
	v_mfma_f32_16x16x32_bf16 v[52:55], v[202:205], v[218:221], v[52:55]
	v_mfma_f32_16x16x32_bf16 v[40:43], v[194:197], v[228:231], v[40:43]
	v_mfma_f32_16x16x32_bf16 v[36:39], v[202:205], v[228:231], v[36:39]
	v_mfma_f32_16x16x32_bf16 v[24:27], v[194:197], v[236:239], v[24:27]
	v_mfma_f32_16x16x32_bf16 v[20:23], v[202:205], v[236:239], v[20:23]
	v_mfma_f32_16x16x32_bf16 v[8:11], v[194:197], v[244:247], v[8:11]
	v_mfma_f32_16x16x32_bf16 v[4:7], v[202:205], v[244:247], v[4:7]
	s_setprio 0
	s_barrier
	s_add_i32 s25, 0, 0x18000
	s_add_i32 s70, 0, 0x1c000
	v_add_u32_e32 v144, s25, v159
	v_add_u32_e32 v158, s70, v159
	ds_read_b128 v[132:135], v144
	ds_read_b128 v[136:139], v144 offset:1024
	ds_read_b128 v[140:143], v144 offset:2048
	ds_read_b128 v[144:147], v144 offset:3072
	ds_read_b128 v[190:193], v158
	ds_read_b128 v[194:197], v158 offset:1024
	ds_read_b128 v[198:201], v158 offset:2048
	ds_read_b128 v[202:205], v158 offset:3072
	s_add_u32 s40, s52, 0x40000
	s_addc_u32 s41, s53, 0
	s_mov_b32 m0, s58
	v_lshl_add_u64 v[184:185], s[40:41], 0, v[0:1]
	ds_read_b128 v[206:209], v179 offset:32768
	ds_read_b128 v[218:221], v179 offset:33792
	ds_read_b128 v[224:227], v179 offset:34816
	ds_read_b128 v[228:231], v179 offset:35840
	ds_read_b128 v[232:235], v179 offset:36864
	ds_read_b128 v[236:239], v179 offset:37888
	ds_read_b128 v[240:243], v179 offset:38912
	ds_read_b128 v[244:247], v179 offset:39936
	global_load_lds_dwordx4 v[184:185], off
	v_lshl_add_u64 v[184:185], s[40:41], 0, v[148:149]
	s_mov_b32 m0, s59
	s_nop 0
	global_load_lds_dwordx4 v[184:185], off
	s_waitcnt vmcnt(8)
	s_waitcnt lgkmcnt(0)
	s_barrier
	s_setprio 1
	s_waitcnt lgkmcnt(0)
	v_mfma_f32_16x16x32_bf16 v[128:131], v[132:135], v[206:209], v[128:131]
	v_mfma_f32_16x16x32_bf16 v[124:127], v[140:143], v[206:209], v[124:127]
	v_mfma_f32_16x16x32_bf16 v[112:115], v[132:135], v[224:227], v[112:115]
	v_mfma_f32_16x16x32_bf16 v[108:111], v[140:143], v[224:227], v[108:111]
	v_mfma_f32_16x16x32_bf16 v[96:99], v[132:135], v[232:235], v[96:99]
	v_mfma_f32_16x16x32_bf16 v[92:95], v[140:143], v[232:235], v[92:95]
	v_mfma_f32_16x16x32_bf16 v[80:83], v[132:135], v[240:243], v[80:83]
	v_mfma_f32_16x16x32_bf16 v[76:79], v[140:143], v[240:243], v[76:79]
	s_setprio 0
	s_setprio 1
	v_mfma_f32_16x16x32_bf16 v[128:131], v[136:139], v[218:221], v[128:131]
	v_mfma_f32_16x16x32_bf16 v[124:127], v[144:147], v[218:221], v[124:127]
	v_mfma_f32_16x16x32_bf16 v[112:115], v[136:139], v[228:231], v[112:115]
	v_mfma_f32_16x16x32_bf16 v[108:111], v[144:147], v[228:231], v[108:111]
	v_mfma_f32_16x16x32_bf16 v[96:99], v[136:139], v[236:239], v[96:99]
	v_mfma_f32_16x16x32_bf16 v[92:95], v[144:147], v[236:239], v[92:95]
	v_mfma_f32_16x16x32_bf16 v[80:83], v[136:139], v[244:247], v[80:83]
	v_mfma_f32_16x16x32_bf16 v[76:79], v[144:147], v[244:247], v[76:79]
	s_setprio 0
	s_setprio 1
	v_mfma_f32_16x16x32_bf16 v[120:123], v[190:193], v[206:209], v[120:123]
	v_mfma_f32_16x16x32_bf16 v[116:119], v[198:201], v[206:209], v[116:119]
	v_mfma_f32_16x16x32_bf16 v[104:107], v[190:193], v[224:227], v[104:107]
	v_mfma_f32_16x16x32_bf16 v[100:103], v[198:201], v[224:227], v[100:103]
	v_mfma_f32_16x16x32_bf16 v[88:91], v[190:193], v[232:235], v[88:91]
	v_mfma_f32_16x16x32_bf16 v[84:87], v[198:201], v[232:235], v[84:87]
	v_mfma_f32_16x16x32_bf16 v[72:75], v[190:193], v[240:243], v[72:75]
	v_mfma_f32_16x16x32_bf16 v[68:71], v[198:201], v[240:243], v[68:71]
	s_setprio 0
	s_setprio 1
	v_mfma_f32_16x16x32_bf16 v[120:123], v[194:197], v[218:221], v[120:123]
	v_mfma_f32_16x16x32_bf16 v[116:119], v[202:205], v[218:221], v[116:119]
	v_mfma_f32_16x16x32_bf16 v[104:107], v[194:197], v[228:231], v[104:107]
	v_mfma_f32_16x16x32_bf16 v[100:103], v[202:205], v[228:231], v[100:103]
	v_mfma_f32_16x16x32_bf16 v[88:91], v[194:197], v[236:239], v[88:91]
	v_mfma_f32_16x16x32_bf16 v[84:87], v[202:205], v[236:239], v[84:87]
	v_mfma_f32_16x16x32_bf16 v[72:75], v[194:197], v[244:247], v[72:75]
	v_mfma_f32_16x16x32_bf16 v[68:71], v[202:205], v[244:247], v[68:71]
	s_setprio 0
	s_barrier
	s_add_i32 s25, s25, s55
	v_lshl_add_u64 v[174:175], v[174:175], 0, s[94:95]
	s_mov_b32 m0, s25
	ds_read_b128 v[206:209], v179 offset:49152
	ds_read_b128 v[218:221], v179 offset:50176
	ds_read_b128 v[224:227], v179 offset:51200
	ds_read_b128 v[228:231], v179 offset:52224
	ds_read_b128 v[232:235], v179 offset:53248
	ds_read_b128 v[236:239], v179 offset:54272
	ds_read_b128 v[240:243], v179 offset:55296
	ds_read_b128 v[244:247], v179 offset:56320
	global_load_lds_dwordx4 v[174:175], off
	s_add_i32 m0, s25, 0x2000
	s_add_u32 s10, s10, 0x40080
	v_lshl_add_u64 v[174:175], v[210:211], 0, s[94:95]
	s_addc_u32 s11, s11, 0
	s_add_i32 s25, s70, s55
	global_load_lds_dwordx4 v[174:175], off
	v_lshl_add_u64 v[174:175], s[10:11], 0, v[180:181]
	s_mov_b32 m0, s25
	s_nop 0
	global_load_lds_dwordx4 v[174:175], off
	v_lshl_add_u64 v[174:175], s[10:11], 0, v[150:151]
	s_add_i32 m0, s25, 0x2000
	s_nop 0
	global_load_lds_dwordx4 v[174:175], off
	v_lshl_add_u64 v[174:175], v[248:249], 0, s[94:95]
	s_mov_b32 m0, s64
	s_nop 0
	global_load_lds_dwordx4 v[174:175], off
	v_lshl_add_u64 v[174:175], v[182:183], 0, s[94:95]
	s_mov_b32 m0, s65
	s_nop 0
	global_load_lds_dwordx4 v[174:175], off
	s_waitcnt vmcnt(8)
	s_waitcnt lgkmcnt(0)
	s_barrier
	s_setprio 1
	s_waitcnt lgkmcnt(0)
	v_mfma_f32_16x16x32_bf16 v[64:67], v[132:135], v[206:209], v[64:67]
	v_mfma_f32_16x16x32_bf16 v[60:63], v[140:143], v[206:209], v[60:63]
	v_mfma_f32_16x16x32_bf16 v[48:51], v[132:135], v[224:227], v[48:51]
	v_mfma_f32_16x16x32_bf16 v[44:47], v[140:143], v[224:227], v[44:47]
	v_mfma_f32_16x16x32_bf16 v[32:35], v[132:135], v[232:235], v[32:35]
	v_mfma_f32_16x16x32_bf16 v[28:31], v[140:143], v[232:235], v[28:31]
	v_mfma_f32_16x16x32_bf16 v[16:19], v[132:135], v[240:243], v[16:19]
	v_mfma_f32_16x16x32_bf16 v[12:15], v[140:143], v[240:243], v[12:15]
	s_setprio 0
	s_setprio 1
	v_mfma_f32_16x16x32_bf16 v[64:67], v[136:139], v[218:221], v[64:67]
	v_mfma_f32_16x16x32_bf16 v[60:63], v[144:147], v[218:221], v[60:63]
	v_mfma_f32_16x16x32_bf16 v[48:51], v[136:139], v[228:231], v[48:51]
	v_mfma_f32_16x16x32_bf16 v[44:47], v[144:147], v[228:231], v[44:47]
	v_mfma_f32_16x16x32_bf16 v[32:35], v[136:139], v[236:239], v[32:35]
	v_mfma_f32_16x16x32_bf16 v[28:31], v[144:147], v[236:239], v[28:31]
	v_mfma_f32_16x16x32_bf16 v[16:19], v[136:139], v[244:247], v[16:19]
	v_mfma_f32_16x16x32_bf16 v[12:15], v[144:147], v[244:247], v[12:15]
	s_setprio 0
	s_setprio 1
	v_mfma_f32_16x16x32_bf16 v[56:59], v[190:193], v[206:209], v[56:59]
	v_mfma_f32_16x16x32_bf16 v[52:55], v[198:201], v[206:209], v[52:55]
	v_mfma_f32_16x16x32_bf16 v[40:43], v[190:193], v[224:227], v[40:43]
	v_mfma_f32_16x16x32_bf16 v[36:39], v[198:201], v[224:227], v[36:39]
	v_mfma_f32_16x16x32_bf16 v[24:27], v[190:193], v[232:235], v[24:27]
	v_mfma_f32_16x16x32_bf16 v[20:23], v[198:201], v[232:235], v[20:23]
	v_mfma_f32_16x16x32_bf16 v[8:11], v[190:193], v[240:243], v[8:11]
	v_mfma_f32_16x16x32_bf16 v[4:7], v[198:201], v[240:243], v[4:7]
	s_setprio 0
	s_setprio 1
	v_mfma_f32_16x16x32_bf16 v[56:59], v[194:197], v[218:221], v[56:59]
	v_mfma_f32_16x16x32_bf16 v[52:55], v[202:205], v[218:221], v[52:55]
	v_mfma_f32_16x16x32_bf16 v[40:43], v[194:197], v[228:231], v[40:43]
	v_mfma_f32_16x16x32_bf16 v[36:39], v[202:205], v[228:231], v[36:39]
	v_mfma_f32_16x16x32_bf16 v[24:27], v[194:197], v[236:239], v[24:27]
	v_mfma_f32_16x16x32_bf16 v[20:23], v[202:205], v[236:239], v[20:23]
	v_mfma_f32_16x16x32_bf16 v[8:11], v[194:197], v[244:247], v[8:11]
	v_mfma_f32_16x16x32_bf16 v[4:7], v[202:205], v[244:247], v[4:7]
	s_setprio 0
	s_barrier
	s_add_i32 vcc_hi, vcc_hi, 2
	s_add_u32 s8, s8, 0x100
	s_addc_u32 s9, s9, 0
	s_add_u32 s97, s97, 0x100
	s_addc_u32 vcc_lo, vcc_lo, 0
	s_cmp_gt_u32 vcc_hi, 13
	s_cbranch_scc0 .LBB0_83
	s_and_b64 vcc, exec, s[16:17]
	s_cbranch_vccz .LBB0_86
	s_barrier

.LBB0_142:
	s_add_u32 s25, s36, 0xfffc0080
	s_addc_u32 s40, s37, -1
	s_add_i32 s41, 0, 0x10000
	s_cmp_eq_u32 s88, 12
	s_cselect_b32 s47, s17, s40
	s_cselect_b32 s46, s64, s25
	s_cselect_b32 s45, s15, s69
	s_cselect_b32 s44, s65, s68
	s_add_i32 s25, 0, 0x14000
	v_add_u32_e32 v156, s41, v140
	v_add_u32_e32 v172, s25, v140
	ds_read_b128 v[144:147], v156
	ds_read_b128 v[148:151], v156 offset:1024
	ds_read_b128 v[152:155], v156 offset:2048
	ds_read_b128 v[156:159], v156 offset:3072
	ds_read_b128 v[160:163], v172
	ds_read_b128 v[164:167], v172 offset:1024
	ds_read_b128 v[168:171], v172 offset:2048
	ds_read_b128 v[172:175], v172 offset:3072
	v_lshl_add_u64 v[182:183], s[36:37], 0, v[136:137]
	s_add_i32 m0, s49, 0xc000
	ds_read_b128 v[176:179], v143
	ds_read_b128 v[190:193], v143 offset:1024
	ds_read_b128 v[194:197], v143 offset:2048
	ds_read_b128 v[198:201], v143 offset:3072
	ds_read_b128 v[202:205], v143 offset:4096
	ds_read_b128 v[206:209], v143 offset:5120
	ds_read_b128 v[218:221], v143 offset:6144
	ds_read_b128 v[224:227], v143 offset:7168
	global_load_lds_dwordx4 v[182:183], off
	v_lshl_add_u64 v[182:183], s[36:37], 0, v[138:139]
	s_add_i32 m0, s49, 0xe000
	s_nop 0
	global_load_lds_dwordx4 v[182:183], off
	s_waitcnt vmcnt(8)
	s_waitcnt lgkmcnt(0)
	s_barrier
	s_setprio 1
	s_waitcnt lgkmcnt(0)
	v_mfma_f32_16x16x32_bf16 v[128:131], v[144:147], v[176:179], v[128:131]
	v_mfma_f32_16x16x32_bf16 v[124:127], v[152:155], v[176:179], v[124:127]
	v_mfma_f32_16x16x32_bf16 v[120:123], v[144:147], v[194:197], v[120:123]
	v_mfma_f32_16x16x32_bf16 v[112:115], v[152:155], v[194:197], v[112:115]
	v_mfma_f32_16x16x32_bf16 v[96:99], v[144:147], v[202:205], v[96:99]
	v_mfma_f32_16x16x32_bf16 v[92:95], v[152:155], v[202:205], v[92:95]
	v_mfma_f32_16x16x32_bf16 v[88:91], v[144:147], v[218:221], v[88:91]
	v_mfma_f32_16x16x32_bf16 v[80:83], v[152:155], v[218:221], v[80:83]
	s_setprio 0
	s_setprio 1
	v_mfma_f32_16x16x32_bf16 v[128:131], v[148:151], v[190:193], v[128:131]
	v_mfma_f32_16x16x32_bf16 v[124:127], v[156:159], v[190:193], v[124:127]
	v_mfma_f32_16x16x32_bf16 v[120:123], v[148:151], v[198:201], v[120:123]
	v_mfma_f32_16x16x32_bf16 v[112:115], v[156:159], v[198:201], v[112:115]
	v_mfma_f32_16x16x32_bf16 v[96:99], v[148:151], v[206:209], v[96:99]
	v_mfma_f32_16x16x32_bf16 v[92:95], v[156:159], v[206:209], v[92:95]
	v_mfma_f32_16x16x32_bf16 v[88:91], v[148:151], v[224:227], v[88:91]
	v_mfma_f32_16x16x32_bf16 v[80:83], v[156:159], v[224:227], v[80:83]
	s_setprio 0
	s_setprio 1
	v_mfma_f32_16x16x32_bf16 v[116:119], v[160:163], v[176:179], v[116:119]
	v_mfma_f32_16x16x32_bf16 v[108:111], v[168:171], v[176:179], v[108:111]
	v_mfma_f32_16x16x32_bf16 v[104:107], v[160:163], v[194:197], v[104:107]
	v_mfma_f32_16x16x32_bf16 v[100:103], v[168:171], v[194:197], v[100:103]
	v_mfma_f32_16x16x32_bf16 v[84:87], v[160:163], v[202:205], v[84:87]
	v_mfma_f32_16x16x32_bf16 v[76:79], v[168:171], v[202:205], v[76:79]
	v_mfma_f32_16x16x32_bf16 v[72:75], v[160:163], v[218:221], v[72:75]
	v_mfma_f32_16x16x32_bf16 v[68:71], v[168:171], v[218:221], v[68:71]
	s_setprio 0
	s_setprio 1
	v_mfma_f32_16x16x32_bf16 v[116:119], v[164:167], v[190:193], v[116:119]
	v_mfma_f32_16x16x32_bf16 v[108:111], v[172:175], v[190:193], v[108:111]
	v_mfma_f32_16x16x32_bf16 v[104:107], v[164:167], v[198:201], v[104:107]
	v_mfma_f32_16x16x32_bf16 v[100:103], v[172:175], v[198:201], v[100:103]
	v_mfma_f32_16x16x32_bf16 v[84:87], v[164:167], v[206:209], v[84:87]
	v_mfma_f32_16x16x32_bf16 v[76:79], v[172:175], v[206:209], v[76:79]
	v_mfma_f32_16x16x32_bf16 v[72:75], v[164:167], v[224:227], v[72:75]
	v_mfma_f32_16x16x32_bf16 v[68:71], v[172:175], v[224:227], v[68:71]
	s_setprio 0
	s_barrier
	s_add_i32 s40, s41, s48
	v_lshl_add_u64 v[182:183], s[44:45], 0, v[180:181]
	s_mov_b32 m0, s40
	ds_read_b128 v[176:179], v143 offset:16384
	ds_read_b128 v[190:193], v143 offset:17408
	ds_read_b128 v[194:197], v143 offset:18432
	ds_read_b128 v[198:201], v143 offset:19456
	ds_read_b128 v[202:205], v143 offset:20480
	ds_read_b128 v[206:209], v143 offset:21504
	ds_read_b128 v[218:221], v143 offset:22528
	ds_read_b128 v[224:227], v143 offset:23552
	global_load_lds_dwordx4 v[182:183], off
	s_add_i32 m0, s40, 0x2000
	s_add_u32 s40, s44, 0x40000
	v_lshl_add_u64 v[184:185], s[44:45], 0, v[134:135]
	s_addc_u32 s41, s45, 0
	s_add_i32 s25, s25, s48
	global_load_lds_dwordx4 v[184:185], off
	v_lshl_add_u64 v[210:211], s[40:41], 0, v[180:181]
	s_mov_b32 m0, s25
	v_lshl_add_u64 v[228:229], s[46:47], 0, v[132:133]
	global_load_lds_dwordx4 v[210:211], off
	v_lshl_add_u64 v[210:211], s[40:41], 0, v[134:135]
	s_add_i32 m0, s25, 0x2000
	s_nop 0
	global_load_lds_dwordx4 v[210:211], off
	v_lshl_add_u64 v[210:211], s[46:47], 0, v[0:1]
	s_mov_b32 m0, s49
	s_nop 0
	global_load_lds_dwordx4 v[210:211], off
	s_mov_b32 m0, s50
	s_nop 0
	global_load_lds_dwordx4 v[228:229], off
	s_waitcnt vmcnt(8)
	s_waitcnt lgkmcnt(0)
	s_barrier
	s_setprio 1
	s_waitcnt lgkmcnt(0)
	v_mfma_f32_16x16x32_bf16 v[64:67], v[144:147], v[176:179], v[64:67]
	v_mfma_f32_16x16x32_bf16 v[60:63], v[152:155], v[176:179], v[60:63]
	v_mfma_f32_16x16x32_bf16 v[56:59], v[144:147], v[194:197], v[56:59]
	v_mfma_f32_16x16x32_bf16 v[48:51], v[152:155], v[194:197], v[48:51]
	v_mfma_f32_16x16x32_bf16 v[32:35], v[144:147], v[202:205], v[32:35]
	v_mfma_f32_16x16x32_bf16 v[28:31], v[152:155], v[202:205], v[28:31]
	v_mfma_f32_16x16x32_bf16 v[24:27], v[144:147], v[218:221], v[24:27]
	v_mfma_f32_16x16x32_bf16 v[16:19], v[152:155], v[218:221], v[16:19]
	s_setprio 0
	s_setprio 1
	v_mfma_f32_16x16x32_bf16 v[64:67], v[148:151], v[190:193], v[64:67]
	v_mfma_f32_16x16x32_bf16 v[60:63], v[156:159], v[190:193], v[60:63]
	v_mfma_f32_16x16x32_bf16 v[56:59], v[148:151], v[198:201], v[56:59]
	v_mfma_f32_16x16x32_bf16 v[48:51], v[156:159], v[198:201], v[48:51]
	v_mfma_f32_16x16x32_bf16 v[32:35], v[148:151], v[206:209], v[32:35]
	v_mfma_f32_16x16x32_bf16 v[28:31], v[156:159], v[206:209], v[28:31]
	v_mfma_f32_16x16x32_bf16 v[24:27], v[148:151], v[224:227], v[24:27]
	v_mfma_f32_16x16x32_bf16 v[16:19], v[156:159], v[224:227], v[16:19]
	s_setprio 0
	s_setprio 1
	v_mfma_f32_16x16x32_bf16 v[52:55], v[160:163], v[176:179], v[52:55]
	v_mfma_f32_16x16x32_bf16 v[44:47], v[168:171], v[176:179], v[44:47]
	v_mfma_f32_16x16x32_bf16 v[40:43], v[160:163], v[194:197], v[40:43]
	v_mfma_f32_16x16x32_bf16 v[36:39], v[168:171], v[194:197], v[36:39]
	v_mfma_f32_16x16x32_bf16 v[20:23], v[160:163], v[202:205], v[20:23]
	v_mfma_f32_16x16x32_bf16 v[12:15], v[168:171], v[202:205], v[12:15]
	v_mfma_f32_16x16x32_bf16 v[8:11], v[160:163], v[218:221], v[8:11]
	v_mfma_f32_16x16x32_bf16 v[4:7], v[168:171], v[218:221], v[4:7]
	s_setprio 0
	s_setprio 1
	v_mfma_f32_16x16x32_bf16 v[52:55], v[164:167], v[190:193], v[52:55]
	v_mfma_f32_16x16x32_bf16 v[44:47], v[172:175], v[190:193], v[44:47]
	v_mfma_f32_16x16x32_bf16 v[40:43], v[164:167], v[198:201], v[40:43]
	v_mfma_f32_16x16x32_bf16 v[36:39], v[172:175], v[198:201], v[36:39]
	v_mfma_f32_16x16x32_bf16 v[20:23], v[164:167], v[206:209], v[20:23]
	v_mfma_f32_16x16x32_bf16 v[12:15], v[172:175], v[206:209], v[12:15]
	v_mfma_f32_16x16x32_bf16 v[8:11], v[164:167], v[224:227], v[8:11]
	v_mfma_f32_16x16x32_bf16 v[4:7], v[172:175], v[224:227], v[4:7]
	s_setprio 0
	s_barrier
	s_add_i32 s25, 0, 0x18000
	s_add_i32 s70, 0, 0x1c000
	v_add_u32_e32 v156, s25, v140
	v_add_u32_e32 v172, s70, v140
	ds_read_b128 v[144:147], v156
	ds_read_b128 v[148:151], v156 offset:1024
	ds_read_b128 v[152:155], v156 offset:2048
	ds_read_b128 v[156:159], v156 offset:3072
	ds_read_b128 v[160:163], v172
	ds_read_b128 v[164:167], v172 offset:1024
	ds_read_b128 v[168:171], v172 offset:2048
	ds_read_b128 v[172:175], v172 offset:3072
	s_add_u32 s40, s46, 0x40000
	s_addc_u32 s41, s47, 0
	s_mov_b32 m0, s51
	v_lshl_add_u64 v[230:231], s[40:41], 0, v[0:1]
	ds_read_b128 v[176:179], v143 offset:32768
	ds_read_b128 v[190:193], v143 offset:33792
	ds_read_b128 v[194:197], v143 offset:34816
	ds_read_b128 v[198:201], v143 offset:35840
	ds_read_b128 v[202:205], v143 offset:36864
	ds_read_b128 v[206:209], v143 offset:37888
	ds_read_b128 v[218:221], v143 offset:38912
	ds_read_b128 v[224:227], v143 offset:39936
	global_load_lds_dwordx4 v[230:231], off
	v_lshl_add_u64 v[230:231], s[40:41], 0, v[132:133]
	s_mov_b32 m0, s52
	s_nop 0
	global_load_lds_dwordx4 v[230:231], off
	s_waitcnt vmcnt(8)
	s_waitcnt lgkmcnt(0)
	s_barrier
	s_setprio 1
	s_waitcnt lgkmcnt(0)
	v_mfma_f32_16x16x32_bf16 v[128:131], v[144:147], v[176:179], v[128:131]
	v_mfma_f32_16x16x32_bf16 v[124:127], v[152:155], v[176:179], v[124:127]
	v_mfma_f32_16x16x32_bf16 v[120:123], v[144:147], v[194:197], v[120:123]
	v_mfma_f32_16x16x32_bf16 v[112:115], v[152:155], v[194:197], v[112:115]
	v_mfma_f32_16x16x32_bf16 v[96:99], v[144:147], v[202:205], v[96:99]
	v_mfma_f32_16x16x32_bf16 v[92:95], v[152:155], v[202:205], v[92:95]
	v_mfma_f32_16x16x32_bf16 v[88:91], v[144:147], v[218:221], v[88:91]
	v_mfma_f32_16x16x32_bf16 v[80:83], v[152:155], v[218:221], v[80:83]
	s_setprio 0
	s_setprio 1
	v_mfma_f32_16x16x32_bf16 v[128:131], v[148:151], v[190:193], v[128:131]
	v_mfma_f32_16x16x32_bf16 v[124:127], v[156:159], v[190:193], v[124:127]
	v_mfma_f32_16x16x32_bf16 v[120:123], v[148:151], v[198:201], v[120:123]
	v_mfma_f32_16x16x32_bf16 v[112:115], v[156:159], v[198:201], v[112:115]
	v_mfma_f32_16x16x32_bf16 v[96:99], v[148:151], v[206:209], v[96:99]
	v_mfma_f32_16x16x32_bf16 v[92:95], v[156:159], v[206:209], v[92:95]
	v_mfma_f32_16x16x32_bf16 v[88:91], v[148:151], v[224:227], v[88:91]
	v_mfma_f32_16x16x32_bf16 v[80:83], v[156:159], v[224:227], v[80:83]
	s_setprio 0
	s_setprio 1
	v_mfma_f32_16x16x32_bf16 v[116:119], v[160:163], v[176:179], v[116:119]
	v_mfma_f32_16x16x32_bf16 v[108:111], v[168:171], v[176:179], v[108:111]
	v_mfma_f32_16x16x32_bf16 v[104:107], v[160:163], v[194:197], v[104:107]
	v_mfma_f32_16x16x32_bf16 v[100:103], v[168:171], v[194:197], v[100:103]
	v_mfma_f32_16x16x32_bf16 v[84:87], v[160:163], v[202:205], v[84:87]
	v_mfma_f32_16x16x32_bf16 v[76:79], v[168:171], v[202:205], v[76:79]
	v_mfma_f32_16x16x32_bf16 v[72:75], v[160:163], v[218:221], v[72:75]
	v_mfma_f32_16x16x32_bf16 v[68:71], v[168:171], v[218:221], v[68:71]
	s_setprio 0
	s_setprio 1
	v_mfma_f32_16x16x32_bf16 v[116:119], v[164:167], v[190:193], v[116:119]
	v_mfma_f32_16x16x32_bf16 v[108:111], v[172:175], v[190:193], v[108:111]
	v_mfma_f32_16x16x32_bf16 v[104:107], v[164:167], v[198:201], v[104:107]
	v_mfma_f32_16x16x32_bf16 v[100:103], v[172:175], v[198:201], v[100:103]
	v_mfma_f32_16x16x32_bf16 v[84:87], v[164:167], v[206:209], v[84:87]
	v_mfma_f32_16x16x32_bf16 v[76:79], v[172:175], v[206:209], v[76:79]
	v_mfma_f32_16x16x32_bf16 v[72:75], v[164:167], v[224:227], v[72:75]
	v_mfma_f32_16x16x32_bf16 v[68:71], v[172:175], v[224:227], v[68:71]
	s_setprio 0
	s_barrier
	s_add_i32 s25, s25, s48
	v_lshl_add_u64 v[182:183], v[182:183], 0, s[94:95]
	s_mov_b32 m0, s25
	ds_read_b128 v[176:179], v143 offset:49152
	ds_read_b128 v[190:193], v143 offset:50176
	ds_read_b128 v[194:197], v143 offset:51200
	ds_read_b128 v[198:201], v143 offset:52224
	ds_read_b128 v[202:205], v143 offset:53248
	ds_read_b128 v[206:209], v143 offset:54272
	ds_read_b128 v[218:221], v143 offset:55296
	ds_read_b128 v[224:227], v143 offset:56320
	global_load_lds_dwordx4 v[182:183], off
	s_add_i32 m0, s25, 0x2000
	s_add_u32 s40, s44, 0x40080
	v_lshl_add_u64 v[182:183], v[184:185], 0, s[94:95]
	s_addc_u32 s41, s45, 0
	s_add_i32 s25, s70, s48
	global_load_lds_dwordx4 v[182:183], off
	v_lshl_add_u64 v[182:183], s[40:41], 0, v[180:181]
	s_mov_b32 m0, s25
	s_nop 0
	global_load_lds_dwordx4 v[182:183], off
	v_lshl_add_u64 v[182:183], s[40:41], 0, v[134:135]
	s_add_i32 m0, s25, 0x2000
	s_nop 0
	global_load_lds_dwordx4 v[182:183], off
	v_lshl_add_u64 v[182:183], v[210:211], 0, s[94:95]
	s_mov_b32 m0, s53
	s_nop 0
	global_load_lds_dwordx4 v[182:183], off
	v_lshl_add_u64 v[182:183], v[228:229], 0, s[94:95]
	s_mov_b32 m0, s54
	s_nop 0
	global_load_lds_dwordx4 v[182:183], off
	s_waitcnt vmcnt(8)
	s_waitcnt lgkmcnt(0)
	s_barrier
	s_setprio 1
	s_waitcnt lgkmcnt(0)
	v_mfma_f32_16x16x32_bf16 v[64:67], v[144:147], v[176:179], v[64:67]
	v_mfma_f32_16x16x32_bf16 v[60:63], v[152:155], v[176:179], v[60:63]
	v_mfma_f32_16x16x32_bf16 v[56:59], v[144:147], v[194:197], v[56:59]
	v_mfma_f32_16x16x32_bf16 v[48:51], v[152:155], v[194:197], v[48:51]
	v_mfma_f32_16x16x32_bf16 v[32:35], v[144:147], v[202:205], v[32:35]
	v_mfma_f32_16x16x32_bf16 v[28:31], v[152:155], v[202:205], v[28:31]
	v_mfma_f32_16x16x32_bf16 v[24:27], v[144:147], v[218:221], v[24:27]
	v_mfma_f32_16x16x32_bf16 v[16:19], v[152:155], v[218:221], v[16:19]
	s_setprio 0
	s_setprio 1
	v_mfma_f32_16x16x32_bf16 v[64:67], v[148:151], v[190:193], v[64:67]
	v_mfma_f32_16x16x32_bf16 v[60:63], v[156:159], v[190:193], v[60:63]
	v_mfma_f32_16x16x32_bf16 v[56:59], v[148:151], v[198:201], v[56:59]
	v_mfma_f32_16x16x32_bf16 v[48:51], v[156:159], v[198:201], v[48:51]
	v_mfma_f32_16x16x32_bf16 v[32:35], v[148:151], v[206:209], v[32:35]
	v_mfma_f32_16x16x32_bf16 v[28:31], v[156:159], v[206:209], v[28:31]
	v_mfma_f32_16x16x32_bf16 v[24:27], v[148:151], v[224:227], v[24:27]
	v_mfma_f32_16x16x32_bf16 v[16:19], v[156:159], v[224:227], v[16:19]
	s_setprio 0
	s_setprio 1
	v_mfma_f32_16x16x32_bf16 v[52:55], v[160:163], v[176:179], v[52:55]
	v_mfma_f32_16x16x32_bf16 v[44:47], v[168:171], v[176:179], v[44:47]
	v_mfma_f32_16x16x32_bf16 v[40:43], v[160:163], v[194:197], v[40:43]
	v_mfma_f32_16x16x32_bf16 v[36:39], v[168:171], v[194:197], v[36:39]
	v_mfma_f32_16x16x32_bf16 v[20:23], v[160:163], v[202:205], v[20:23]
	v_mfma_f32_16x16x32_bf16 v[12:15], v[168:171], v[202:205], v[12:15]
	v_mfma_f32_16x16x32_bf16 v[8:11], v[160:163], v[218:221], v[8:11]
	v_mfma_f32_16x16x32_bf16 v[4:7], v[168:171], v[218:221], v[4:7]
	s_setprio 0
	s_setprio 1
	v_mfma_f32_16x16x32_bf16 v[52:55], v[164:167], v[190:193], v[52:55]
	v_mfma_f32_16x16x32_bf16 v[44:47], v[172:175], v[190:193], v[44:47]
	v_mfma_f32_16x16x32_bf16 v[40:43], v[164:167], v[198:201], v[40:43]
	v_mfma_f32_16x16x32_bf16 v[36:39], v[172:175], v[198:201], v[36:39]
	v_mfma_f32_16x16x32_bf16 v[20:23], v[164:167], v[206:209], v[20:23]
	v_mfma_f32_16x16x32_bf16 v[12:15], v[172:175], v[206:209], v[12:15]
	v_mfma_f32_16x16x32_bf16 v[8:11], v[164:167], v[224:227], v[8:11]
	v_mfma_f32_16x16x32_bf16 v[4:7], v[172:175], v[224:227], v[4:7]
	s_setprio 0
	s_barrier
	s_add_i32 s88, s88, 2
	s_add_u32 s36, s36, 0x100
	s_addc_u32 s37, s37, 0
	s_add_u32 s68, s68, 0x100
	s_addc_u32 s69, s69, 0
	s_cmp_gt_u32 s88, 13
	s_cbranch_scc0 .LBB0_142
	s_and_b64 vcc, exec, s[12:13]
	s_cbranch_vccz .LBB0_145
	s_barrier

.LBB0_181:
	s_add_u32 s25, s10, 0xfffc0080
	s_addc_u32 s40, s11, -1
	s_add_i32 s41, 0, 0x10000
	s_cmp_eq_u32 s68, 12
	s_cselect_b32 s49, s37, s40
	s_cselect_b32 s48, s36, s25
	s_cselect_b32 s47, s19, s65
	s_cselect_b32 s46, s27, s64
	s_add_i32 s25, 0, 0x14000
	v_add_u32_e32 v144, s41, v187
	v_add_u32_e32 v170, s25, v187
	ds_read_b128 v[132:135], v144
	ds_read_b128 v[136:139], v144 offset:1024
	ds_read_b128 v[140:143], v144 offset:2048
	ds_read_b128 v[144:147], v144 offset:3072
	ds_read_b128 v[148:151], v170
	ds_read_b128 v[152:155], v170 offset:1024
	ds_read_b128 v[156:159], v170 offset:2048
	ds_read_b128 v[170:173], v170 offset:3072
	v_lshl_add_u64 v[178:179], s[10:11], 0, v[166:167]
	s_add_i32 m0, s51, 0xc000
	ds_read_b128 v[174:177], v194
	ds_read_b128 v[196:199], v194 offset:1024
	ds_read_b128 v[200:203], v194 offset:2048
	ds_read_b128 v[204:207], v194 offset:3072
	ds_read_b128 v[208:211], v194 offset:4096
	ds_read_b128 v[218:221], v194 offset:5120
	ds_read_b128 v[224:227], v194 offset:6144
	ds_read_b128 v[228:231], v194 offset:7168
	global_load_lds_dwordx4 v[178:179], off
	v_lshl_add_u64 v[178:179], s[10:11], 0, v[168:169]
	s_add_i32 m0, s51, 0xe000
	s_nop 0
	global_load_lds_dwordx4 v[178:179], off
	s_waitcnt vmcnt(8)
	s_waitcnt lgkmcnt(0)
	s_barrier
	s_setprio 1
	s_waitcnt lgkmcnt(0)
	v_mfma_f32_16x16x32_bf16 v[128:131], v[132:135], v[174:177], v[128:131]
	v_mfma_f32_16x16x32_bf16 v[124:127], v[140:143], v[174:177], v[124:127]
	v_mfma_f32_16x16x32_bf16 v[112:115], v[132:135], v[200:203], v[112:115]
	v_mfma_f32_16x16x32_bf16 v[108:111], v[140:143], v[200:203], v[108:111]
	v_mfma_f32_16x16x32_bf16 v[96:99], v[132:135], v[208:211], v[96:99]
	v_mfma_f32_16x16x32_bf16 v[92:95], v[140:143], v[208:211], v[92:95]
	v_mfma_f32_16x16x32_bf16 v[80:83], v[132:135], v[224:227], v[80:83]
	v_mfma_f32_16x16x32_bf16 v[76:79], v[140:143], v[224:227], v[76:79]
	s_setprio 0
	s_setprio 1
	v_mfma_f32_16x16x32_bf16 v[128:131], v[136:139], v[196:199], v[128:131]
	v_mfma_f32_16x16x32_bf16 v[124:127], v[144:147], v[196:199], v[124:127]
	v_mfma_f32_16x16x32_bf16 v[112:115], v[136:139], v[204:207], v[112:115]
	v_mfma_f32_16x16x32_bf16 v[108:111], v[144:147], v[204:207], v[108:111]
	v_mfma_f32_16x16x32_bf16 v[96:99], v[136:139], v[218:221], v[96:99]
	v_mfma_f32_16x16x32_bf16 v[92:95], v[144:147], v[218:221], v[92:95]
	v_mfma_f32_16x16x32_bf16 v[80:83], v[136:139], v[228:231], v[80:83]
	v_mfma_f32_16x16x32_bf16 v[76:79], v[144:147], v[228:231], v[76:79]
	s_setprio 0
	s_setprio 1
	v_mfma_f32_16x16x32_bf16 v[120:123], v[148:151], v[174:177], v[120:123]
	v_mfma_f32_16x16x32_bf16 v[116:119], v[156:159], v[174:177], v[116:119]
	v_mfma_f32_16x16x32_bf16 v[104:107], v[148:151], v[200:203], v[104:107]
	v_mfma_f32_16x16x32_bf16 v[100:103], v[156:159], v[200:203], v[100:103]
	v_mfma_f32_16x16x32_bf16 v[88:91], v[148:151], v[208:211], v[88:91]
	v_mfma_f32_16x16x32_bf16 v[84:87], v[156:159], v[208:211], v[84:87]
	v_mfma_f32_16x16x32_bf16 v[72:75], v[148:151], v[224:227], v[72:75]
	v_mfma_f32_16x16x32_bf16 v[68:71], v[156:159], v[224:227], v[68:71]
	s_setprio 0
	s_setprio 1
	v_mfma_f32_16x16x32_bf16 v[120:123], v[152:155], v[196:199], v[120:123]
	v_mfma_f32_16x16x32_bf16 v[116:119], v[170:173], v[196:199], v[116:119]
	v_mfma_f32_16x16x32_bf16 v[104:107], v[152:155], v[204:207], v[104:107]
	v_mfma_f32_16x16x32_bf16 v[100:103], v[170:173], v[204:207], v[100:103]
	v_mfma_f32_16x16x32_bf16 v[88:91], v[152:155], v[218:221], v[88:91]
	v_mfma_f32_16x16x32_bf16 v[84:87], v[170:173], v[218:221], v[84:87]
	v_mfma_f32_16x16x32_bf16 v[72:75], v[152:155], v[228:231], v[72:75]
	v_mfma_f32_16x16x32_bf16 v[68:71], v[170:173], v[228:231], v[68:71]
	s_setprio 0
	s_barrier
	s_add_i32 s40, s41, s50
	v_lshl_add_u64 v[178:179], s[46:47], 0, v[162:163]
	s_mov_b32 m0, s40
	ds_read_b128 v[174:177], v194 offset:16384
	ds_read_b128 v[196:199], v194 offset:17408
	ds_read_b128 v[200:203], v194 offset:18432
	ds_read_b128 v[204:207], v194 offset:19456
	ds_read_b128 v[208:211], v194 offset:20480
	ds_read_b128 v[218:221], v194 offset:21504
	ds_read_b128 v[224:227], v194 offset:22528
	ds_read_b128 v[228:231], v194 offset:23552
	global_load_lds_dwordx4 v[178:179], off
	s_add_i32 m0, s40, 0x2000
	s_add_u32 s40, s46, 0x40000
	v_lshl_add_u64 v[182:183], s[46:47], 0, v[0:1]
	s_addc_u32 s41, s47, 0
	s_add_i32 s25, s25, s50
	global_load_lds_dwordx4 v[182:183], off
	v_lshl_add_u64 v[184:185], s[40:41], 0, v[162:163]
	s_mov_b32 m0, s25
	v_lshl_add_u64 v[190:191], s[48:49], 0, v[160:161]
	global_load_lds_dwordx4 v[184:185], off
	v_lshl_add_u64 v[184:185], s[40:41], 0, v[0:1]
	s_add_i32 m0, s25, 0x2000
	s_nop 0
	global_load_lds_dwordx4 v[184:185], off
	v_lshl_add_u64 v[184:185], s[48:49], 0, v[164:165]
	s_mov_b32 m0, s51
	s_nop 0
	global_load_lds_dwordx4 v[184:185], off
	s_mov_b32 m0, s52
	s_nop 0
	global_load_lds_dwordx4 v[190:191], off
	s_waitcnt vmcnt(8)
	s_waitcnt lgkmcnt(0)
	s_barrier
	s_setprio 1
	s_waitcnt lgkmcnt(0)
	v_mfma_f32_16x16x32_bf16 v[64:67], v[132:135], v[174:177], v[64:67]
	v_mfma_f32_16x16x32_bf16 v[60:63], v[140:143], v[174:177], v[60:63]
	v_mfma_f32_16x16x32_bf16 v[48:51], v[132:135], v[200:203], v[48:51]
	v_mfma_f32_16x16x32_bf16 v[44:47], v[140:143], v[200:203], v[44:47]
	v_mfma_f32_16x16x32_bf16 v[32:35], v[132:135], v[208:211], v[32:35]
	v_mfma_f32_16x16x32_bf16 v[28:31], v[140:143], v[208:211], v[28:31]
	v_mfma_f32_16x16x32_bf16 v[16:19], v[132:135], v[224:227], v[16:19]
	v_mfma_f32_16x16x32_bf16 v[12:15], v[140:143], v[224:227], v[12:15]
	s_setprio 0
	s_setprio 1
	v_mfma_f32_16x16x32_bf16 v[64:67], v[136:139], v[196:199], v[64:67]
	v_mfma_f32_16x16x32_bf16 v[60:63], v[144:147], v[196:199], v[60:63]
	v_mfma_f32_16x16x32_bf16 v[48:51], v[136:139], v[204:207], v[48:51]
	v_mfma_f32_16x16x32_bf16 v[44:47], v[144:147], v[204:207], v[44:47]
	v_mfma_f32_16x16x32_bf16 v[32:35], v[136:139], v[218:221], v[32:35]
	v_mfma_f32_16x16x32_bf16 v[28:31], v[144:147], v[218:221], v[28:31]
	v_mfma_f32_16x16x32_bf16 v[16:19], v[136:139], v[228:231], v[16:19]
	v_mfma_f32_16x16x32_bf16 v[12:15], v[144:147], v[228:231], v[12:15]
	s_setprio 0
	s_setprio 1
	v_mfma_f32_16x16x32_bf16 v[56:59], v[148:151], v[174:177], v[56:59]
	v_mfma_f32_16x16x32_bf16 v[52:55], v[156:159], v[174:177], v[52:55]
	v_mfma_f32_16x16x32_bf16 v[40:43], v[148:151], v[200:203], v[40:43]
	v_mfma_f32_16x16x32_bf16 v[36:39], v[156:159], v[200:203], v[36:39]
	v_mfma_f32_16x16x32_bf16 v[24:27], v[148:151], v[208:211], v[24:27]
	v_mfma_f32_16x16x32_bf16 v[20:23], v[156:159], v[208:211], v[20:23]
	v_mfma_f32_16x16x32_bf16 v[8:11], v[148:151], v[224:227], v[8:11]
	v_mfma_f32_16x16x32_bf16 v[4:7], v[156:159], v[224:227], v[4:7]
	s_setprio 0
	s_setprio 1
	v_mfma_f32_16x16x32_bf16 v[56:59], v[152:155], v[196:199], v[56:59]
	v_mfma_f32_16x16x32_bf16 v[52:55], v[170:173], v[196:199], v[52:55]
	v_mfma_f32_16x16x32_bf16 v[40:43], v[152:155], v[204:207], v[40:43]
	v_mfma_f32_16x16x32_bf16 v[36:39], v[170:173], v[204:207], v[36:39]
	v_mfma_f32_16x16x32_bf16 v[24:27], v[152:155], v[218:221], v[24:27]
	v_mfma_f32_16x16x32_bf16 v[20:23], v[170:173], v[218:221], v[20:23]
	v_mfma_f32_16x16x32_bf16 v[8:11], v[152:155], v[228:231], v[8:11]
	v_mfma_f32_16x16x32_bf16 v[4:7], v[170:173], v[228:231], v[4:7]
	s_setprio 0
	s_barrier
	s_add_i32 s25, 0, 0x18000
	s_add_i32 s69, 0, 0x1c000
	v_add_u32_e32 v144, s25, v187
	v_add_u32_e32 v170, s69, v187
	ds_read_b128 v[132:135], v144
	ds_read_b128 v[136:139], v144 offset:1024
	ds_read_b128 v[140:143], v144 offset:2048
	ds_read_b128 v[144:147], v144 offset:3072
	ds_read_b128 v[148:151], v170
	ds_read_b128 v[152:155], v170 offset:1024
	ds_read_b128 v[156:159], v170 offset:2048
	ds_read_b128 v[170:173], v170 offset:3072
	s_add_u32 s40, s48, 0x40000
	s_addc_u32 s41, s49, 0
	s_mov_b32 m0, s53
	v_lshl_add_u64 v[232:233], s[40:41], 0, v[164:165]
	ds_read_b128 v[174:177], v194 offset:32768
	ds_read_b128 v[196:199], v194 offset:33792
	ds_read_b128 v[200:203], v194 offset:34816
	ds_read_b128 v[204:207], v194 offset:35840
	ds_read_b128 v[208:211], v194 offset:36864
	ds_read_b128 v[218:221], v194 offset:37888
	ds_read_b128 v[224:227], v194 offset:38912
	ds_read_b128 v[228:231], v194 offset:39936
	global_load_lds_dwordx4 v[232:233], off
	v_lshl_add_u64 v[232:233], s[40:41], 0, v[160:161]
	s_mov_b32 m0, s54
	s_nop 0
	global_load_lds_dwordx4 v[232:233], off
	s_waitcnt vmcnt(8)
	s_waitcnt lgkmcnt(0)
	s_barrier
	s_setprio 1
	s_waitcnt lgkmcnt(0)
	v_mfma_f32_16x16x32_bf16 v[128:131], v[132:135], v[174:177], v[128:131]
	v_mfma_f32_16x16x32_bf16 v[124:127], v[140:143], v[174:177], v[124:127]
	v_mfma_f32_16x16x32_bf16 v[112:115], v[132:135], v[200:203], v[112:115]
	v_mfma_f32_16x16x32_bf16 v[108:111], v[140:143], v[200:203], v[108:111]
	v_mfma_f32_16x16x32_bf16 v[96:99], v[132:135], v[208:211], v[96:99]
	v_mfma_f32_16x16x32_bf16 v[92:95], v[140:143], v[208:211], v[92:95]
	v_mfma_f32_16x16x32_bf16 v[80:83], v[132:135], v[224:227], v[80:83]
	v_mfma_f32_16x16x32_bf16 v[76:79], v[140:143], v[224:227], v[76:79]
	s_setprio 0
	s_setprio 1
	v_mfma_f32_16x16x32_bf16 v[128:131], v[136:139], v[196:199], v[128:131]
	v_mfma_f32_16x16x32_bf16 v[124:127], v[144:147], v[196:199], v[124:127]
	v_mfma_f32_16x16x32_bf16 v[112:115], v[136:139], v[204:207], v[112:115]
	v_mfma_f32_16x16x32_bf16 v[108:111], v[144:147], v[204:207], v[108:111]
	v_mfma_f32_16x16x32_bf16 v[96:99], v[136:139], v[218:221], v[96:99]
	v_mfma_f32_16x16x32_bf16 v[92:95], v[144:147], v[218:221], v[92:95]
	v_mfma_f32_16x16x32_bf16 v[80:83], v[136:139], v[228:231], v[80:83]
	v_mfma_f32_16x16x32_bf16 v[76:79], v[144:147], v[228:231], v[76:79]
	s_setprio 0
	s_setprio 1
	v_mfma_f32_16x16x32_bf16 v[120:123], v[148:151], v[174:177], v[120:123]
	v_mfma_f32_16x16x32_bf16 v[116:119], v[156:159], v[174:177], v[116:119]
	v_mfma_f32_16x16x32_bf16 v[104:107], v[148:151], v[200:203], v[104:107]
	v_mfma_f32_16x16x32_bf16 v[100:103], v[156:159], v[200:203], v[100:103]
	v_mfma_f32_16x16x32_bf16 v[88:91], v[148:151], v[208:211], v[88:91]
	v_mfma_f32_16x16x32_bf16 v[84:87], v[156:159], v[208:211], v[84:87]
	v_mfma_f32_16x16x32_bf16 v[72:75], v[148:151], v[224:227], v[72:75]
	v_mfma_f32_16x16x32_bf16 v[68:71], v[156:159], v[224:227], v[68:71]
	s_setprio 0
	s_setprio 1
	v_mfma_f32_16x16x32_bf16 v[120:123], v[152:155], v[196:199], v[120:123]
	v_mfma_f32_16x16x32_bf16 v[116:119], v[170:173], v[196:199], v[116:119]
	v_mfma_f32_16x16x32_bf16 v[104:107], v[152:155], v[204:207], v[104:107]
	v_mfma_f32_16x16x32_bf16 v[100:103], v[170:173], v[204:207], v[100:103]
	v_mfma_f32_16x16x32_bf16 v[88:91], v[152:155], v[218:221], v[88:91]
	v_mfma_f32_16x16x32_bf16 v[84:87], v[170:173], v[218:221], v[84:87]
	v_mfma_f32_16x16x32_bf16 v[72:75], v[152:155], v[228:231], v[72:75]
	v_mfma_f32_16x16x32_bf16 v[68:71], v[170:173], v[228:231], v[68:71]
	s_setprio 0
	s_barrier
	s_add_i32 s25, s25, s50
	v_lshl_add_u64 v[178:179], v[178:179], 0, s[94:95]
	s_mov_b32 m0, s25
	ds_read_b128 v[174:177], v194 offset:49152
	ds_read_b128 v[196:199], v194 offset:50176
	ds_read_b128 v[200:203], v194 offset:51200
	ds_read_b128 v[204:207], v194 offset:52224
	ds_read_b128 v[208:211], v194 offset:53248
	ds_read_b128 v[218:221], v194 offset:54272
	ds_read_b128 v[224:227], v194 offset:55296
	ds_read_b128 v[228:231], v194 offset:56320
	global_load_lds_dwordx4 v[178:179], off
	s_add_i32 m0, s25, 0x2000
	s_add_u32 s40, s46, 0x40080
	v_lshl_add_u64 v[178:179], v[182:183], 0, s[94:95]
	s_addc_u32 s41, s47, 0
	s_add_i32 s25, s69, s50
	global_load_lds_dwordx4 v[178:179], off
	v_lshl_add_u64 v[178:179], s[40:41], 0, v[162:163]
	s_mov_b32 m0, s25
	s_nop 0
	global_load_lds_dwordx4 v[178:179], off
	v_lshl_add_u64 v[178:179], s[40:41], 0, v[0:1]
	s_add_i32 m0, s25, 0x2000
	s_nop 0
	global_load_lds_dwordx4 v[178:179], off
	v_lshl_add_u64 v[178:179], v[184:185], 0, s[94:95]
	s_mov_b32 m0, s55
	s_nop 0
	global_load_lds_dwordx4 v[178:179], off
	v_lshl_add_u64 v[178:179], v[190:191], 0, s[94:95]
	s_mov_b32 m0, s58
	s_nop 0
	global_load_lds_dwordx4 v[178:179], off
	s_waitcnt vmcnt(8)
	s_waitcnt lgkmcnt(0)
	s_barrier
	s_setprio 1
	s_waitcnt lgkmcnt(0)
	v_mfma_f32_16x16x32_bf16 v[64:67], v[132:135], v[174:177], v[64:67]
	v_mfma_f32_16x16x32_bf16 v[60:63], v[140:143], v[174:177], v[60:63]
	v_mfma_f32_16x16x32_bf16 v[48:51], v[132:135], v[200:203], v[48:51]
	v_mfma_f32_16x16x32_bf16 v[44:47], v[140:143], v[200:203], v[44:47]
	v_mfma_f32_16x16x32_bf16 v[32:35], v[132:135], v[208:211], v[32:35]
	v_mfma_f32_16x16x32_bf16 v[28:31], v[140:143], v[208:211], v[28:31]
	v_mfma_f32_16x16x32_bf16 v[16:19], v[132:135], v[224:227], v[16:19]
	v_mfma_f32_16x16x32_bf16 v[12:15], v[140:143], v[224:227], v[12:15]
	s_setprio 0
	s_setprio 1
	v_mfma_f32_16x16x32_bf16 v[64:67], v[136:139], v[196:199], v[64:67]
	v_mfma_f32_16x16x32_bf16 v[60:63], v[144:147], v[196:199], v[60:63]
	v_mfma_f32_16x16x32_bf16 v[48:51], v[136:139], v[204:207], v[48:51]
	v_mfma_f32_16x16x32_bf16 v[44:47], v[144:147], v[204:207], v[44:47]
	v_mfma_f32_16x16x32_bf16 v[32:35], v[136:139], v[218:221], v[32:35]
	v_mfma_f32_16x16x32_bf16 v[28:31], v[144:147], v[218:221], v[28:31]
	v_mfma_f32_16x16x32_bf16 v[16:19], v[136:139], v[228:231], v[16:19]
	v_mfma_f32_16x16x32_bf16 v[12:15], v[144:147], v[228:231], v[12:15]
	s_setprio 0
	s_setprio 1
	v_mfma_f32_16x16x32_bf16 v[56:59], v[148:151], v[174:177], v[56:59]
	v_mfma_f32_16x16x32_bf16 v[52:55], v[156:159], v[174:177], v[52:55]
	v_mfma_f32_16x16x32_bf16 v[40:43], v[148:151], v[200:203], v[40:43]
	v_mfma_f32_16x16x32_bf16 v[36:39], v[156:159], v[200:203], v[36:39]
	v_mfma_f32_16x16x32_bf16 v[24:27], v[148:151], v[208:211], v[24:27]
	v_mfma_f32_16x16x32_bf16 v[20:23], v[156:159], v[208:211], v[20:23]
	v_mfma_f32_16x16x32_bf16 v[8:11], v[148:151], v[224:227], v[8:11]
	v_mfma_f32_16x16x32_bf16 v[4:7], v[156:159], v[224:227], v[4:7]
	s_setprio 0
	s_setprio 1
	v_mfma_f32_16x16x32_bf16 v[56:59], v[152:155], v[196:199], v[56:59]
	v_mfma_f32_16x16x32_bf16 v[52:55], v[170:173], v[196:199], v[52:55]
	v_mfma_f32_16x16x32_bf16 v[40:43], v[152:155], v[204:207], v[40:43]
	v_mfma_f32_16x16x32_bf16 v[36:39], v[170:173], v[204:207], v[36:39]
	v_mfma_f32_16x16x32_bf16 v[24:27], v[152:155], v[218:221], v[24:27]
	v_mfma_f32_16x16x32_bf16 v[20:23], v[170:173], v[218:221], v[20:23]
	v_mfma_f32_16x16x32_bf16 v[8:11], v[152:155], v[228:231], v[8:11]
	v_mfma_f32_16x16x32_bf16 v[4:7], v[170:173], v[228:231], v[4:7]
	s_setprio 0
	s_barrier
	s_add_i32 s68, s68, 2
	s_add_u32 s10, s10, 0x100
	s_addc_u32 s11, s11, 0
	s_add_u32 s64, s64, 0x100
	s_addc_u32 s65, s65, 0
	s_cmp_gt_u32 s68, 13
	s_cbranch_scc0 .LBB0_181
	s_and_b64 vcc, exec, s[14:15]
	s_cbranch_vccz .LBB0_184
	s_barrier

.LBB0_231:
	s_add_u32 s12, s10, 0xfffc0080
	s_addc_u32 s13, s11, -1
	s_add_i32 s25, 0, 0x10000
	s_cmp_eq_u32 s97, 12
	s_cselect_b32 s47, s27, s13
	s_cselect_b32 s46, s69, s12
	s_cselect_b32 s13, s19, s90
	s_cselect_b32 s12, s88, s89
	s_add_i32 s50, 0, 0x14000
	v_add_u32_e32 v144, s25, v159
	v_add_u32_e32 v158, s50, v159
	ds_read_b128 v[132:135], v144
	ds_read_b128 v[136:139], v144 offset:1024
	ds_read_b128 v[140:143], v144 offset:2048
	ds_read_b128 v[144:147], v144 offset:3072
	ds_read_b128 v[190:193], v158
	ds_read_b128 v[194:197], v158 offset:1024
	ds_read_b128 v[198:201], v158 offset:2048
	ds_read_b128 v[202:205], v158 offset:3072
	v_lshl_add_u64 v[174:175], s[10:11], 0, v[154:155]
	s_add_i32 m0, s49, 0xc000
	ds_read_b128 v[206:209], v179
	ds_read_b128 v[218:221], v179 offset:1024
	ds_read_b128 v[224:227], v179 offset:2048
	ds_read_b128 v[228:231], v179 offset:3072
	ds_read_b128 v[232:235], v179 offset:4096
	ds_read_b128 v[236:239], v179 offset:5120
	ds_read_b128 v[240:243], v179 offset:6144
	ds_read_b128 v[244:247], v179 offset:7168
	global_load_lds_dwordx4 v[174:175], off
	v_lshl_add_u64 v[174:175], s[10:11], 0, v[156:157]
	s_add_i32 m0, s49, 0xe000
	s_nop 0
	global_load_lds_dwordx4 v[174:175], off
	s_waitcnt vmcnt(8)
	s_waitcnt lgkmcnt(0)
	s_barrier
	s_setprio 1
	s_waitcnt lgkmcnt(0)
	v_mfma_f32_16x16x32_bf16 v[128:131], v[132:135], v[206:209], v[128:131]
	v_mfma_f32_16x16x32_bf16 v[124:127], v[140:143], v[206:209], v[124:127]
	v_mfma_f32_16x16x32_bf16 v[112:115], v[132:135], v[224:227], v[112:115]
	v_mfma_f32_16x16x32_bf16 v[108:111], v[140:143], v[224:227], v[108:111]
	v_mfma_f32_16x16x32_bf16 v[96:99], v[132:135], v[232:235], v[96:99]
	v_mfma_f32_16x16x32_bf16 v[92:95], v[140:143], v[232:235], v[92:95]
	v_mfma_f32_16x16x32_bf16 v[80:83], v[132:135], v[240:243], v[80:83]
	v_mfma_f32_16x16x32_bf16 v[76:79], v[140:143], v[240:243], v[76:79]
	s_setprio 0
	s_setprio 1
	v_mfma_f32_16x16x32_bf16 v[128:131], v[136:139], v[218:221], v[128:131]
	v_mfma_f32_16x16x32_bf16 v[124:127], v[144:147], v[218:221], v[124:127]
	v_mfma_f32_16x16x32_bf16 v[112:115], v[136:139], v[228:231], v[112:115]
	v_mfma_f32_16x16x32_bf16 v[108:111], v[144:147], v[228:231], v[108:111]
	v_mfma_f32_16x16x32_bf16 v[96:99], v[136:139], v[236:239], v[96:99]
	v_mfma_f32_16x16x32_bf16 v[92:95], v[144:147], v[236:239], v[92:95]
	v_mfma_f32_16x16x32_bf16 v[80:83], v[136:139], v[244:247], v[80:83]
	v_mfma_f32_16x16x32_bf16 v[76:79], v[144:147], v[244:247], v[76:79]
	s_setprio 0
	s_setprio 1
	v_mfma_f32_16x16x32_bf16 v[120:123], v[190:193], v[206:209], v[120:123]
	v_mfma_f32_16x16x32_bf16 v[116:119], v[198:201], v[206:209], v[116:119]
	v_mfma_f32_16x16x32_bf16 v[104:107], v[190:193], v[224:227], v[104:107]
	v_mfma_f32_16x16x32_bf16 v[100:103], v[198:201], v[224:227], v[100:103]
	v_mfma_f32_16x16x32_bf16 v[88:91], v[190:193], v[232:235], v[88:91]
	v_mfma_f32_16x16x32_bf16 v[84:87], v[198:201], v[232:235], v[84:87]
	v_mfma_f32_16x16x32_bf16 v[72:75], v[190:193], v[240:243], v[72:75]
	v_mfma_f32_16x16x32_bf16 v[68:71], v[198:201], v[240:243], v[68:71]
	s_setprio 0
	s_setprio 1
	v_mfma_f32_16x16x32_bf16 v[120:123], v[194:197], v[218:221], v[120:123]
	v_mfma_f32_16x16x32_bf16 v[116:119], v[202:205], v[218:221], v[116:119]
	v_mfma_f32_16x16x32_bf16 v[104:107], v[194:197], v[228:231], v[104:107]
	v_mfma_f32_16x16x32_bf16 v[100:103], v[202:205], v[228:231], v[100:103]
	v_mfma_f32_16x16x32_bf16 v[88:91], v[194:197], v[236:239], v[88:91]
	v_mfma_f32_16x16x32_bf16 v[84:87], v[202:205], v[236:239], v[84:87]
	v_mfma_f32_16x16x32_bf16 v[72:75], v[194:197], v[244:247], v[72:75]
	v_mfma_f32_16x16x32_bf16 v[68:71], v[202:205], v[244:247], v[68:71]
	s_setprio 0
	s_barrier
	s_add_i32 s25, s25, s48
	v_lshl_add_u64 v[174:175], s[12:13], 0, v[180:181]
	s_mov_b32 m0, s25
	ds_read_b128 v[206:209], v179 offset:16384
	ds_read_b128 v[218:221], v179 offset:17408
	ds_read_b128 v[224:227], v179 offset:18432
	ds_read_b128 v[228:231], v179 offset:19456
	ds_read_b128 v[232:235], v179 offset:20480
	ds_read_b128 v[236:239], v179 offset:21504
	ds_read_b128 v[240:243], v179 offset:22528
	ds_read_b128 v[244:247], v179 offset:23552
	global_load_lds_dwordx4 v[174:175], off
	s_add_i32 m0, s25, 0x2000
	s_add_u32 s40, s12, 0x40000
	v_lshl_add_u64 v[182:183], s[12:13], 0, v[150:151]
	s_addc_u32 s41, s13, 0
	s_add_i32 s25, s50, s48
	global_load_lds_dwordx4 v[182:183], off
	v_lshl_add_u64 v[184:185], s[40:41], 0, v[180:181]
	s_mov_b32 m0, s25
	v_lshl_add_u64 v[210:211], s[46:47], 0, v[148:149]
	global_load_lds_dwordx4 v[184:185], off
	v_lshl_add_u64 v[184:185], s[40:41], 0, v[150:151]
	s_add_i32 m0, s25, 0x2000
	s_nop 0
	global_load_lds_dwordx4 v[184:185], off
	v_lshl_add_u64 v[184:185], s[46:47], 0, v[0:1]
	s_mov_b32 m0, s49
	s_nop 0
	global_load_lds_dwordx4 v[184:185], off
	s_mov_b32 m0, s52
	s_nop 0
	global_load_lds_dwordx4 v[210:211], off
	s_waitcnt vmcnt(8)
	s_waitcnt lgkmcnt(0)
	s_barrier
	s_setprio 1
	s_waitcnt lgkmcnt(0)
	v_mfma_f32_16x16x32_bf16 v[64:67], v[132:135], v[206:209], v[64:67]
	v_mfma_f32_16x16x32_bf16 v[60:63], v[140:143], v[206:209], v[60:63]
	v_mfma_f32_16x16x32_bf16 v[48:51], v[132:135], v[224:227], v[48:51]
	v_mfma_f32_16x16x32_bf16 v[44:47], v[140:143], v[224:227], v[44:47]
	v_mfma_f32_16x16x32_bf16 v[32:35], v[132:135], v[232:235], v[32:35]
	v_mfma_f32_16x16x32_bf16 v[28:31], v[140:143], v[232:235], v[28:31]
	v_mfma_f32_16x16x32_bf16 v[16:19], v[132:135], v[240:243], v[16:19]
	v_mfma_f32_16x16x32_bf16 v[12:15], v[140:143], v[240:243], v[12:15]
	s_setprio 0
	s_setprio 1
	v_mfma_f32_16x16x32_bf16 v[64:67], v[136:139], v[218:221], v[64:67]
	v_mfma_f32_16x16x32_bf16 v[60:63], v[144:147], v[218:221], v[60:63]
	v_mfma_f32_16x16x32_bf16 v[48:51], v[136:139], v[228:231], v[48:51]
	v_mfma_f32_16x16x32_bf16 v[44:47], v[144:147], v[228:231], v[44:47]
	v_mfma_f32_16x16x32_bf16 v[32:35], v[136:139], v[236:239], v[32:35]
	v_mfma_f32_16x16x32_bf16 v[28:31], v[144:147], v[236:239], v[28:31]
	v_mfma_f32_16x16x32_bf16 v[16:19], v[136:139], v[244:247], v[16:19]
	v_mfma_f32_16x16x32_bf16 v[12:15], v[144:147], v[244:247], v[12:15]
	s_setprio 0
	s_setprio 1
	v_mfma_f32_16x16x32_bf16 v[56:59], v[190:193], v[206:209], v[56:59]
	v_mfma_f32_16x16x32_bf16 v[52:55], v[198:201], v[206:209], v[52:55]
	v_mfma_f32_16x16x32_bf16 v[40:43], v[190:193], v[224:227], v[40:43]
	v_mfma_f32_16x16x32_bf16 v[36:39], v[198:201], v[224:227], v[36:39]
	v_mfma_f32_16x16x32_bf16 v[24:27], v[190:193], v[232:235], v[24:27]
	v_mfma_f32_16x16x32_bf16 v[20:23], v[198:201], v[232:235], v[20:23]
	v_mfma_f32_16x16x32_bf16 v[8:11], v[190:193], v[240:243], v[8:11]
	v_mfma_f32_16x16x32_bf16 v[4:7], v[198:201], v[240:243], v[4:7]
	s_setprio 0
	s_setprio 1
	v_mfma_f32_16x16x32_bf16 v[56:59], v[194:197], v[218:221], v[56:59]
	v_mfma_f32_16x16x32_bf16 v[52:55], v[202:205], v[218:221], v[52:55]
	v_mfma_f32_16x16x32_bf16 v[40:43], v[194:197], v[228:231], v[40:43]
	v_mfma_f32_16x16x32_bf16 v[36:39], v[202:205], v[228:231], v[36:39]
	v_mfma_f32_16x16x32_bf16 v[24:27], v[194:197], v[236:239], v[24:27]
	v_mfma_f32_16x16x32_bf16 v[20:23], v[202:205], v[236:239], v[20:23]
	v_mfma_f32_16x16x32_bf16 v[8:11], v[194:197], v[244:247], v[8:11]
	v_mfma_f32_16x16x32_bf16 v[4:7], v[202:205], v[244:247], v[4:7]
	s_setprio 0
	s_barrier
	s_add_i32 s25, 0, 0x18000
	s_add_i32 s50, 0, 0x1c000
	v_add_u32_e32 v144, s25, v159
	v_add_u32_e32 v158, s50, v159
	ds_read_b128 v[132:135], v144
	ds_read_b128 v[136:139], v144 offset:1024
	ds_read_b128 v[140:143], v144 offset:2048
	ds_read_b128 v[144:147], v144 offset:3072
	ds_read_b128 v[190:193], v158
	ds_read_b128 v[194:197], v158 offset:1024
	ds_read_b128 v[198:201], v158 offset:2048
	ds_read_b128 v[202:205], v158 offset:3072
	s_add_u32 s40, s46, 0x40000
	s_addc_u32 s41, s47, 0
	s_mov_b32 m0, s53
	v_lshl_add_u64 v[248:249], s[40:41], 0, v[0:1]
	ds_read_b128 v[206:209], v179 offset:32768
	ds_read_b128 v[218:221], v179 offset:33792
	ds_read_b128 v[224:227], v179 offset:34816
	ds_read_b128 v[228:231], v179 offset:35840
	ds_read_b128 v[232:235], v179 offset:36864
	ds_read_b128 v[236:239], v179 offset:37888
	ds_read_b128 v[240:243], v179 offset:38912
	ds_read_b128 v[244:247], v179 offset:39936
	global_load_lds_dwordx4 v[248:249], off
	v_lshl_add_u64 v[248:249], s[40:41], 0, v[148:149]
	s_mov_b32 m0, s54
	s_nop 0
	global_load_lds_dwordx4 v[248:249], off
	s_waitcnt vmcnt(8)
	s_waitcnt lgkmcnt(0)
	s_barrier
	s_setprio 1
	s_waitcnt lgkmcnt(0)
	v_mfma_f32_16x16x32_bf16 v[128:131], v[132:135], v[206:209], v[128:131]
	v_mfma_f32_16x16x32_bf16 v[124:127], v[140:143], v[206:209], v[124:127]
	v_mfma_f32_16x16x32_bf16 v[112:115], v[132:135], v[224:227], v[112:115]
	v_mfma_f32_16x16x32_bf16 v[108:111], v[140:143], v[224:227], v[108:111]
	v_mfma_f32_16x16x32_bf16 v[96:99], v[132:135], v[232:235], v[96:99]
	v_mfma_f32_16x16x32_bf16 v[92:95], v[140:143], v[232:235], v[92:95]
	v_mfma_f32_16x16x32_bf16 v[80:83], v[132:135], v[240:243], v[80:83]
	v_mfma_f32_16x16x32_bf16 v[76:79], v[140:143], v[240:243], v[76:79]
	s_setprio 0
	s_setprio 1
	v_mfma_f32_16x16x32_bf16 v[128:131], v[136:139], v[218:221], v[128:131]
	v_mfma_f32_16x16x32_bf16 v[124:127], v[144:147], v[218:221], v[124:127]
	v_mfma_f32_16x16x32_bf16 v[112:115], v[136:139], v[228:231], v[112:115]
	v_mfma_f32_16x16x32_bf16 v[108:111], v[144:147], v[228:231], v[108:111]
	v_mfma_f32_16x16x32_bf16 v[96:99], v[136:139], v[236:239], v[96:99]
	v_mfma_f32_16x16x32_bf16 v[92:95], v[144:147], v[236:239], v[92:95]
	v_mfma_f32_16x16x32_bf16 v[80:83], v[136:139], v[244:247], v[80:83]
	v_mfma_f32_16x16x32_bf16 v[76:79], v[144:147], v[244:247], v[76:79]
	s_setprio 0
	s_setprio 1
	v_mfma_f32_16x16x32_bf16 v[120:123], v[190:193], v[206:209], v[120:123]
	v_mfma_f32_16x16x32_bf16 v[116:119], v[198:201], v[206:209], v[116:119]
	v_mfma_f32_16x16x32_bf16 v[104:107], v[190:193], v[224:227], v[104:107]
	v_mfma_f32_16x16x32_bf16 v[100:103], v[198:201], v[224:227], v[100:103]
	v_mfma_f32_16x16x32_bf16 v[88:91], v[190:193], v[232:235], v[88:91]
	v_mfma_f32_16x16x32_bf16 v[84:87], v[198:201], v[232:235], v[84:87]
	v_mfma_f32_16x16x32_bf16 v[72:75], v[190:193], v[240:243], v[72:75]
	v_mfma_f32_16x16x32_bf16 v[68:71], v[198:201], v[240:243], v[68:71]
	s_setprio 0
	s_setprio 1
	v_mfma_f32_16x16x32_bf16 v[120:123], v[194:197], v[218:221], v[120:123]
	v_mfma_f32_16x16x32_bf16 v[116:119], v[202:205], v[218:221], v[116:119]
	v_mfma_f32_16x16x32_bf16 v[104:107], v[194:197], v[228:231], v[104:107]
	v_mfma_f32_16x16x32_bf16 v[100:103], v[202:205], v[228:231], v[100:103]
	v_mfma_f32_16x16x32_bf16 v[88:91], v[194:197], v[236:239], v[88:91]
	v_mfma_f32_16x16x32_bf16 v[84:87], v[202:205], v[236:239], v[84:87]
	v_mfma_f32_16x16x32_bf16 v[72:75], v[194:197], v[244:247], v[72:75]
	v_mfma_f32_16x16x32_bf16 v[68:71], v[202:205], v[244:247], v[68:71]
	s_setprio 0
	s_barrier
	s_add_i32 s25, s25, s48
	v_lshl_add_u64 v[174:175], v[174:175], 0, s[94:95]
	s_mov_b32 m0, s25
	ds_read_b128 v[206:209], v179 offset:49152
	ds_read_b128 v[218:221], v179 offset:50176
	ds_read_b128 v[224:227], v179 offset:51200
	ds_read_b128 v[228:231], v179 offset:52224
	ds_read_b128 v[232:235], v179 offset:53248
	ds_read_b128 v[236:239], v179 offset:54272
	ds_read_b128 v[240:243], v179 offset:55296
	ds_read_b128 v[244:247], v179 offset:56320
	global_load_lds_dwordx4 v[174:175], off
	s_add_i32 m0, s25, 0x2000
	s_add_u32 s12, s12, 0x40080
	v_lshl_add_u64 v[174:175], v[182:183], 0, s[94:95]
	s_addc_u32 s13, s13, 0
	s_add_i32 s25, s50, s48
	global_load_lds_dwordx4 v[174:175], off
	v_lshl_add_u64 v[174:175], s[12:13], 0, v[180:181]
	s_mov_b32 m0, s25
	s_nop 0
	global_load_lds_dwordx4 v[174:175], off
	v_lshl_add_u64 v[174:175], s[12:13], 0, v[150:151]
	s_add_i32 m0, s25, 0x2000
	s_nop 0
	global_load_lds_dwordx4 v[174:175], off
	v_lshl_add_u64 v[174:175], v[184:185], 0, s[94:95]
	s_mov_b32 m0, s55
	s_nop 0
	global_load_lds_dwordx4 v[174:175], off
	v_lshl_add_u64 v[174:175], v[210:211], 0, s[94:95]
	s_mov_b32 m0, s58
	s_nop 0
	global_load_lds_dwordx4 v[174:175], off
	s_waitcnt vmcnt(8)
	s_waitcnt lgkmcnt(0)
	s_barrier
	s_setprio 1
	s_waitcnt lgkmcnt(0)
	v_mfma_f32_16x16x32_bf16 v[64:67], v[132:135], v[206:209], v[64:67]
	v_mfma_f32_16x16x32_bf16 v[60:63], v[140:143], v[206:209], v[60:63]
	v_mfma_f32_16x16x32_bf16 v[48:51], v[132:135], v[224:227], v[48:51]
	v_mfma_f32_16x16x32_bf16 v[44:47], v[140:143], v[224:227], v[44:47]
	v_mfma_f32_16x16x32_bf16 v[32:35], v[132:135], v[232:235], v[32:35]
	v_mfma_f32_16x16x32_bf16 v[28:31], v[140:143], v[232:235], v[28:31]
	v_mfma_f32_16x16x32_bf16 v[16:19], v[132:135], v[240:243], v[16:19]
	v_mfma_f32_16x16x32_bf16 v[12:15], v[140:143], v[240:243], v[12:15]
	s_setprio 0
	s_setprio 1
	v_mfma_f32_16x16x32_bf16 v[64:67], v[136:139], v[218:221], v[64:67]
	v_mfma_f32_16x16x32_bf16 v[60:63], v[144:147], v[218:221], v[60:63]
	v_mfma_f32_16x16x32_bf16 v[48:51], v[136:139], v[228:231], v[48:51]
	v_mfma_f32_16x16x32_bf16 v[44:47], v[144:147], v[228:231], v[44:47]
	v_mfma_f32_16x16x32_bf16 v[32:35], v[136:139], v[236:239], v[32:35]
	v_mfma_f32_16x16x32_bf16 v[28:31], v[144:147], v[236:239], v[28:31]
	v_mfma_f32_16x16x32_bf16 v[16:19], v[136:139], v[244:247], v[16:19]
	v_mfma_f32_16x16x32_bf16 v[12:15], v[144:147], v[244:247], v[12:15]
	s_setprio 0
	s_setprio 1
	v_mfma_f32_16x16x32_bf16 v[56:59], v[190:193], v[206:209], v[56:59]
	v_mfma_f32_16x16x32_bf16 v[52:55], v[198:201], v[206:209], v[52:55]
	v_mfma_f32_16x16x32_bf16 v[40:43], v[190:193], v[224:227], v[40:43]
	v_mfma_f32_16x16x32_bf16 v[36:39], v[198:201], v[224:227], v[36:39]
	v_mfma_f32_16x16x32_bf16 v[24:27], v[190:193], v[232:235], v[24:27]
	v_mfma_f32_16x16x32_bf16 v[20:23], v[198:201], v[232:235], v[20:23]
	v_mfma_f32_16x16x32_bf16 v[8:11], v[190:193], v[240:243], v[8:11]
	v_mfma_f32_16x16x32_bf16 v[4:7], v[198:201], v[240:243], v[4:7]
	s_setprio 0
	s_setprio 1
	v_mfma_f32_16x16x32_bf16 v[56:59], v[194:197], v[218:221], v[56:59]
	v_mfma_f32_16x16x32_bf16 v[52:55], v[202:205], v[218:221], v[52:55]
	v_mfma_f32_16x16x32_bf16 v[40:43], v[194:197], v[228:231], v[40:43]
	v_mfma_f32_16x16x32_bf16 v[36:39], v[202:205], v[228:231], v[36:39]
	v_mfma_f32_16x16x32_bf16 v[24:27], v[194:197], v[236:239], v[24:27]
	v_mfma_f32_16x16x32_bf16 v[20:23], v[202:205], v[236:239], v[20:23]
	v_mfma_f32_16x16x32_bf16 v[8:11], v[194:197], v[244:247], v[8:11]
	v_mfma_f32_16x16x32_bf16 v[4:7], v[202:205], v[244:247], v[4:7]
	s_setprio 0
	s_barrier
	s_add_i32 s97, s97, 2
	s_add_u32 s10, s10, 0x100
	s_addc_u32 s11, s11, 0
	s_add_u32 s89, s89, 0x100
	s_addc_u32 s90, s90, 0
	s_cmp_gt_u32 s97, 13
	s_cbranch_scc0 .LBB0_231
	s_and_b64 vcc, exec, s[16:17]
	s_cbranch_vccz .LBB0_234
	s_barrier

.LBB0_293:
	s_add_u32 s25, s36, s44
	s_addc_u32 s40, s37, s45
	s_add_u32 s25, s25, 0x100
	s_addc_u32 s40, s40, 0
	s_add_u32 s41, s97, s44
	s_addc_u32 s46, s50, s45
	s_add_i32 s70, 0, 0x10000
	s_cmpk_eq_i32 s44, 0x700
	s_cselect_b32 s49, s17, s40
	s_cselect_b32 s48, vcc_lo, s25
	v_add_u32_e32 v147, s70, v145
	s_cselect_b32 s47, s15, s46
	s_cselect_b32 s46, vcc_hi, s41
	s_add_i32 s25, 0, 0x14000
	ds_read_b128 v[152:155], v147
	ds_read_b128 v[156:159], v147 offset:1024
	ds_read_b128 v[160:163], v147 offset:2048
	ds_read_b128 v[164:167], v147 offset:3072
	v_add_u32_e32 v147, s25, v145
	ds_read_b128 v[168:171], v147
	ds_read_b128 v[172:175], v147 offset:1024
	ds_read_b128 v[176:179], v147 offset:2048
	ds_read_b128 v[190:193], v147 offset:3072
	v_lshl_add_u64 v[182:183], v[140:141], 0, s[44:45]
	s_add_i32 m0, s59, 0xc000
	ds_read_b128 v[194:197], v146
	ds_read_b128 v[198:201], v146 offset:1024
	ds_read_b128 v[202:205], v146 offset:2048
	ds_read_b128 v[206:209], v146 offset:3072
	ds_read_b128 v[218:221], v146 offset:4096
	ds_read_b128 v[224:227], v146 offset:5120
	ds_read_b128 v[228:231], v146 offset:6144
	ds_read_b128 v[232:235], v146 offset:7168
	global_load_lds_dwordx4 v[182:183], off
	v_lshl_add_u64 v[182:183], v[142:143], 0, s[44:45]
	s_add_i32 m0, s59, 0xe000
	s_nop 0
	global_load_lds_dwordx4 v[182:183], off
	s_waitcnt vmcnt(8)
	s_waitcnt lgkmcnt(0)
	s_barrier
	s_setprio 1
	s_waitcnt lgkmcnt(0)
	v_mfma_f32_16x16x32_bf16 v[128:131], v[152:155], v[194:197], v[128:131]
	v_mfma_f32_16x16x32_bf16 v[124:127], v[160:163], v[194:197], v[124:127]
	v_mfma_f32_16x16x32_bf16 v[112:115], v[152:155], v[202:205], v[112:115]
	v_mfma_f32_16x16x32_bf16 v[108:111], v[160:163], v[202:205], v[108:111]
	v_mfma_f32_16x16x32_bf16 v[104:107], v[152:155], v[218:221], v[104:107]
	v_mfma_f32_16x16x32_bf16 v[96:99], v[160:163], v[218:221], v[96:99]
	v_mfma_f32_16x16x32_bf16 v[88:91], v[152:155], v[228:231], v[88:91]
	v_mfma_f32_16x16x32_bf16 v[80:83], v[160:163], v[228:231], v[80:83]
	s_setprio 0
	s_setprio 1
	v_mfma_f32_16x16x32_bf16 v[128:131], v[156:159], v[198:201], v[128:131]
	v_mfma_f32_16x16x32_bf16 v[124:127], v[164:167], v[198:201], v[124:127]
	v_mfma_f32_16x16x32_bf16 v[112:115], v[156:159], v[206:209], v[112:115]
	v_mfma_f32_16x16x32_bf16 v[108:111], v[164:167], v[206:209], v[108:111]
	v_mfma_f32_16x16x32_bf16 v[104:107], v[156:159], v[224:227], v[104:107]
	v_mfma_f32_16x16x32_bf16 v[96:99], v[164:167], v[224:227], v[96:99]
	v_mfma_f32_16x16x32_bf16 v[88:91], v[156:159], v[232:235], v[88:91]
	v_mfma_f32_16x16x32_bf16 v[80:83], v[164:167], v[232:235], v[80:83]
	s_setprio 0
	s_setprio 1
	v_mfma_f32_16x16x32_bf16 v[120:123], v[168:171], v[194:197], v[120:123]
	v_mfma_f32_16x16x32_bf16 v[116:119], v[176:179], v[194:197], v[116:119]
	v_mfma_f32_16x16x32_bf16 v[100:103], v[168:171], v[202:205], v[100:103]
	v_mfma_f32_16x16x32_bf16 v[92:95], v[176:179], v[202:205], v[92:95]
	v_mfma_f32_16x16x32_bf16 v[84:87], v[168:171], v[218:221], v[84:87]
	v_mfma_f32_16x16x32_bf16 v[76:79], v[176:179], v[218:221], v[76:79]
	v_mfma_f32_16x16x32_bf16 v[72:75], v[168:171], v[228:231], v[72:75]
	v_mfma_f32_16x16x32_bf16 v[68:71], v[176:179], v[228:231], v[68:71]
	s_setprio 0
	s_setprio 1
	v_mfma_f32_16x16x32_bf16 v[120:123], v[172:175], v[198:201], v[120:123]
	v_mfma_f32_16x16x32_bf16 v[116:119], v[190:193], v[198:201], v[116:119]
	v_mfma_f32_16x16x32_bf16 v[100:103], v[172:175], v[206:209], v[100:103]
	v_mfma_f32_16x16x32_bf16 v[92:95], v[190:193], v[206:209], v[92:95]
	v_mfma_f32_16x16x32_bf16 v[84:87], v[172:175], v[224:227], v[84:87]
	v_mfma_f32_16x16x32_bf16 v[76:79], v[190:193], v[224:227], v[76:79]
	v_mfma_f32_16x16x32_bf16 v[72:75], v[172:175], v[232:235], v[72:75]
	v_mfma_f32_16x16x32_bf16 v[68:71], v[190:193], v[232:235], v[68:71]
	s_setprio 0
	s_barrier
	s_add_i32 s40, s70, s58
	v_lshl_add_u64 v[182:183], s[46:47], 0, v[180:181]
	s_mov_b32 m0, s40
	ds_read_b128 v[194:197], v146 offset:16384
	ds_read_b128 v[198:201], v146 offset:17408
	ds_read_b128 v[202:205], v146 offset:18432
	ds_read_b128 v[206:209], v146 offset:19456
	ds_read_b128 v[218:221], v146 offset:20480
	ds_read_b128 v[224:227], v146 offset:21504
	ds_read_b128 v[228:231], v146 offset:22528
	ds_read_b128 v[232:235], v146 offset:23552
	global_load_lds_dwordx4 v[182:183], off
	s_add_i32 m0, s40, 0x2000
	s_add_u32 s40, s46, 0x40000
	v_lshl_add_u64 v[184:185], s[46:47], 0, v[134:135]
	s_addc_u32 s41, s47, 0
	s_add_i32 s25, s25, s58
	global_load_lds_dwordx4 v[184:185], off
	v_lshl_add_u64 v[210:211], s[40:41], 0, v[180:181]
	s_mov_b32 m0, s25
	v_lshl_add_u64 v[236:237], s[48:49], 0, v[132:133]
	global_load_lds_dwordx4 v[210:211], off
	v_lshl_add_u64 v[210:211], s[40:41], 0, v[134:135]
	s_add_i32 m0, s25, 0x2000
	s_nop 0
	global_load_lds_dwordx4 v[210:211], off
	v_lshl_add_u64 v[210:211], s[48:49], 0, v[0:1]
	s_mov_b32 m0, s59
	s_nop 0
	global_load_lds_dwordx4 v[210:211], off
	s_mov_b32 m0, s64
	s_nop 0
	global_load_lds_dwordx4 v[236:237], off
	s_waitcnt vmcnt(8)
	s_waitcnt lgkmcnt(0)
	s_barrier
	s_setprio 1
	s_waitcnt lgkmcnt(0)
	v_mfma_f32_16x16x32_bf16 v[64:67], v[152:155], v[194:197], v[64:67]
	v_mfma_f32_16x16x32_bf16 v[4:7], v[160:163], v[194:197], v[4:7]
	v_mfma_f32_16x16x32_bf16 v[60:63], v[152:155], v[202:205], v[60:63]
	v_mfma_f32_16x16x32_bf16 v[56:59], v[160:163], v[202:205], v[56:59]
	v_mfma_f32_16x16x32_bf16 v[52:55], v[152:155], v[218:221], v[52:55]
	v_mfma_f32_16x16x32_bf16 v[48:51], v[160:163], v[218:221], v[48:51]
	v_mfma_f32_16x16x32_bf16 v[44:47], v[152:155], v[228:231], v[44:47]
	v_mfma_f32_16x16x32_bf16 v[40:43], v[160:163], v[228:231], v[40:43]
	s_setprio 0
	s_setprio 1
	v_mfma_f32_16x16x32_bf16 v[64:67], v[156:159], v[198:201], v[64:67]
	v_mfma_f32_16x16x32_bf16 v[4:7], v[164:167], v[198:201], v[4:7]
	v_mfma_f32_16x16x32_bf16 v[60:63], v[156:159], v[206:209], v[60:63]
	v_mfma_f32_16x16x32_bf16 v[56:59], v[164:167], v[206:209], v[56:59]
	v_mfma_f32_16x16x32_bf16 v[52:55], v[156:159], v[224:227], v[52:55]
	v_mfma_f32_16x16x32_bf16 v[48:51], v[164:167], v[224:227], v[48:51]
	v_mfma_f32_16x16x32_bf16 v[44:47], v[156:159], v[232:235], v[44:47]
	v_mfma_f32_16x16x32_bf16 v[40:43], v[164:167], v[232:235], v[40:43]
	s_setprio 0
	s_setprio 1
	v_mfma_f32_16x16x32_bf16 v[12:15], v[168:171], v[194:197], v[12:15]
	v_mfma_f32_16x16x32_bf16 v[8:11], v[176:179], v[194:197], v[8:11]
	v_mfma_f32_16x16x32_bf16 v[20:23], v[168:171], v[202:205], v[20:23]
	v_mfma_f32_16x16x32_bf16 v[16:19], v[176:179], v[202:205], v[16:19]
	v_mfma_f32_16x16x32_bf16 v[28:31], v[168:171], v[218:221], v[28:31]
	v_mfma_f32_16x16x32_bf16 v[24:27], v[176:179], v[218:221], v[24:27]
	v_mfma_f32_16x16x32_bf16 v[36:39], v[168:171], v[228:231], v[36:39]
	v_mfma_f32_16x16x32_bf16 v[32:35], v[176:179], v[228:231], v[32:35]
	s_setprio 0
	s_setprio 1
	v_mfma_f32_16x16x32_bf16 v[12:15], v[172:175], v[198:201], v[12:15]
	v_mfma_f32_16x16x32_bf16 v[8:11], v[190:193], v[198:201], v[8:11]
	v_mfma_f32_16x16x32_bf16 v[20:23], v[172:175], v[206:209], v[20:23]
	v_mfma_f32_16x16x32_bf16 v[16:19], v[190:193], v[206:209], v[16:19]
	v_mfma_f32_16x16x32_bf16 v[28:31], v[172:175], v[224:227], v[28:31]
	v_mfma_f32_16x16x32_bf16 v[24:27], v[190:193], v[224:227], v[24:27]
	v_mfma_f32_16x16x32_bf16 v[36:39], v[172:175], v[232:235], v[36:39]
	v_mfma_f32_16x16x32_bf16 v[32:35], v[190:193], v[232:235], v[32:35]
	s_setprio 0
	s_barrier
	s_add_i32 s25, 0, 0x18000
	v_add_u32_e32 v147, s25, v145
	s_add_i32 s70, 0, 0x1c000
	ds_read_b128 v[152:155], v147
	ds_read_b128 v[156:159], v147 offset:1024
	ds_read_b128 v[160:163], v147 offset:2048
	ds_read_b128 v[164:167], v147 offset:3072
	v_add_u32_e32 v147, s70, v145
	ds_read_b128 v[168:171], v147
	ds_read_b128 v[172:175], v147 offset:1024
	ds_read_b128 v[176:179], v147 offset:2048
	ds_read_b128 v[190:193], v147 offset:3072
	s_add_u32 s40, s48, 0x40000
	s_addc_u32 s41, s49, 0
	s_mov_b32 m0, s65
	v_lshl_add_u64 v[238:239], s[40:41], 0, v[0:1]
	ds_read_b128 v[194:197], v146 offset:32768
	ds_read_b128 v[198:201], v146 offset:33792
	ds_read_b128 v[202:205], v146 offset:34816
	ds_read_b128 v[206:209], v146 offset:35840
	ds_read_b128 v[218:221], v146 offset:36864
	ds_read_b128 v[224:227], v146 offset:37888
	ds_read_b128 v[228:231], v146 offset:38912
	ds_read_b128 v[232:235], v146 offset:39936
	global_load_lds_dwordx4 v[238:239], off
	v_lshl_add_u64 v[238:239], s[40:41], 0, v[132:133]
	s_mov_b32 m0, s68
	s_nop 0
	global_load_lds_dwordx4 v[238:239], off
	s_waitcnt vmcnt(8)
	s_waitcnt lgkmcnt(0)
	s_barrier
	s_setprio 1
	s_waitcnt lgkmcnt(0)
	v_mfma_f32_16x16x32_bf16 v[128:131], v[152:155], v[194:197], v[128:131]
	v_mfma_f32_16x16x32_bf16 v[124:127], v[160:163], v[194:197], v[124:127]
	v_mfma_f32_16x16x32_bf16 v[112:115], v[152:155], v[202:205], v[112:115]
	v_mfma_f32_16x16x32_bf16 v[108:111], v[160:163], v[202:205], v[108:111]
	v_mfma_f32_16x16x32_bf16 v[104:107], v[152:155], v[218:221], v[104:107]
	v_mfma_f32_16x16x32_bf16 v[96:99], v[160:163], v[218:221], v[96:99]
	v_mfma_f32_16x16x32_bf16 v[88:91], v[152:155], v[228:231], v[88:91]
	v_mfma_f32_16x16x32_bf16 v[80:83], v[160:163], v[228:231], v[80:83]
	s_setprio 0
	s_setprio 1
	v_mfma_f32_16x16x32_bf16 v[128:131], v[156:159], v[198:201], v[128:131]
	v_mfma_f32_16x16x32_bf16 v[124:127], v[164:167], v[198:201], v[124:127]
	v_mfma_f32_16x16x32_bf16 v[112:115], v[156:159], v[206:209], v[112:115]
	v_mfma_f32_16x16x32_bf16 v[108:111], v[164:167], v[206:209], v[108:111]
	v_mfma_f32_16x16x32_bf16 v[104:107], v[156:159], v[224:227], v[104:107]
	v_mfma_f32_16x16x32_bf16 v[96:99], v[164:167], v[224:227], v[96:99]
	v_mfma_f32_16x16x32_bf16 v[88:91], v[156:159], v[232:235], v[88:91]
	v_mfma_f32_16x16x32_bf16 v[80:83], v[164:167], v[232:235], v[80:83]
	s_setprio 0
	s_setprio 1
	v_mfma_f32_16x16x32_bf16 v[120:123], v[168:171], v[194:197], v[120:123]
	v_mfma_f32_16x16x32_bf16 v[116:119], v[176:179], v[194:197], v[116:119]
	v_mfma_f32_16x16x32_bf16 v[100:103], v[168:171], v[202:205], v[100:103]
	v_mfma_f32_16x16x32_bf16 v[92:95], v[176:179], v[202:205], v[92:95]
	v_mfma_f32_16x16x32_bf16 v[84:87], v[168:171], v[218:221], v[84:87]
	v_mfma_f32_16x16x32_bf16 v[76:79], v[176:179], v[218:221], v[76:79]
	v_mfma_f32_16x16x32_bf16 v[72:75], v[168:171], v[228:231], v[72:75]
	v_mfma_f32_16x16x32_bf16 v[68:71], v[176:179], v[228:231], v[68:71]
	s_setprio 0
	s_setprio 1
	v_mfma_f32_16x16x32_bf16 v[120:123], v[172:175], v[198:201], v[120:123]
	v_mfma_f32_16x16x32_bf16 v[116:119], v[190:193], v[198:201], v[116:119]
	v_mfma_f32_16x16x32_bf16 v[100:103], v[172:175], v[206:209], v[100:103]
	v_mfma_f32_16x16x32_bf16 v[92:95], v[190:193], v[206:209], v[92:95]
	v_mfma_f32_16x16x32_bf16 v[84:87], v[172:175], v[224:227], v[84:87]
	v_mfma_f32_16x16x32_bf16 v[76:79], v[190:193], v[224:227], v[76:79]
	v_mfma_f32_16x16x32_bf16 v[72:75], v[172:175], v[232:235], v[72:75]
	v_mfma_f32_16x16x32_bf16 v[68:71], v[190:193], v[232:235], v[68:71]
	s_setprio 0
	s_barrier
	s_add_i32 s25, s25, s58
	v_lshl_add_u64 v[182:183], v[182:183], 0, s[94:95]
	s_mov_b32 m0, s25
	ds_read_b128 v[194:197], v146 offset:49152
	ds_read_b128 v[198:201], v146 offset:50176
	ds_read_b128 v[202:205], v146 offset:51200
	ds_read_b128 v[206:209], v146 offset:52224
	ds_read_b128 v[218:221], v146 offset:53248
	ds_read_b128 v[224:227], v146 offset:54272
	ds_read_b128 v[228:231], v146 offset:55296
	ds_read_b128 v[232:235], v146 offset:56320
	global_load_lds_dwordx4 v[182:183], off
	s_add_i32 m0, s25, 0x2000
	s_add_u32 s40, s46, 0x40080
	v_lshl_add_u64 v[182:183], v[184:185], 0, s[94:95]
	s_addc_u32 s41, s47, 0
	s_add_i32 s25, s70, s58
	global_load_lds_dwordx4 v[182:183], off
	v_lshl_add_u64 v[182:183], s[40:41], 0, v[180:181]
	s_mov_b32 m0, s25
	s_nop 0
	global_load_lds_dwordx4 v[182:183], off
	v_lshl_add_u64 v[182:183], s[40:41], 0, v[134:135]
	s_add_i32 m0, s25, 0x2000
	s_nop 0
	global_load_lds_dwordx4 v[182:183], off
	v_lshl_add_u64 v[182:183], v[210:211], 0, s[94:95]
	s_mov_b32 m0, s69
	s_nop 0
	global_load_lds_dwordx4 v[182:183], off
	v_lshl_add_u64 v[182:183], v[236:237], 0, s[94:95]
	s_mov_b32 m0, s88
	s_nop 0
	global_load_lds_dwordx4 v[182:183], off
	s_waitcnt vmcnt(8)
	s_waitcnt lgkmcnt(0)
	s_barrier
	s_setprio 1
	s_waitcnt lgkmcnt(0)
	v_mfma_f32_16x16x32_bf16 v[64:67], v[152:155], v[194:197], v[64:67]
	v_mfma_f32_16x16x32_bf16 v[4:7], v[160:163], v[194:197], v[4:7]
	v_mfma_f32_16x16x32_bf16 v[60:63], v[152:155], v[202:205], v[60:63]
	v_mfma_f32_16x16x32_bf16 v[56:59], v[160:163], v[202:205], v[56:59]
	v_mfma_f32_16x16x32_bf16 v[52:55], v[152:155], v[218:221], v[52:55]
	v_mfma_f32_16x16x32_bf16 v[48:51], v[160:163], v[218:221], v[48:51]
	v_mfma_f32_16x16x32_bf16 v[44:47], v[152:155], v[228:231], v[44:47]
	v_mfma_f32_16x16x32_bf16 v[40:43], v[160:163], v[228:231], v[40:43]
	s_setprio 0
	s_setprio 1
	v_mfma_f32_16x16x32_bf16 v[64:67], v[156:159], v[198:201], v[64:67]
	v_mfma_f32_16x16x32_bf16 v[4:7], v[164:167], v[198:201], v[4:7]
	v_mfma_f32_16x16x32_bf16 v[60:63], v[156:159], v[206:209], v[60:63]
	v_mfma_f32_16x16x32_bf16 v[56:59], v[164:167], v[206:209], v[56:59]
	v_mfma_f32_16x16x32_bf16 v[52:55], v[156:159], v[224:227], v[52:55]
	v_mfma_f32_16x16x32_bf16 v[48:51], v[164:167], v[224:227], v[48:51]
	v_mfma_f32_16x16x32_bf16 v[44:47], v[156:159], v[232:235], v[44:47]
	v_mfma_f32_16x16x32_bf16 v[40:43], v[164:167], v[232:235], v[40:43]
	s_setprio 0
	s_setprio 1
	v_mfma_f32_16x16x32_bf16 v[12:15], v[168:171], v[194:197], v[12:15]
	v_mfma_f32_16x16x32_bf16 v[8:11], v[176:179], v[194:197], v[8:11]
	v_mfma_f32_16x16x32_bf16 v[20:23], v[168:171], v[202:205], v[20:23]
	v_mfma_f32_16x16x32_bf16 v[16:19], v[176:179], v[202:205], v[16:19]
	v_mfma_f32_16x16x32_bf16 v[28:31], v[168:171], v[218:221], v[28:31]
	v_mfma_f32_16x16x32_bf16 v[24:27], v[176:179], v[218:221], v[24:27]
	v_mfma_f32_16x16x32_bf16 v[36:39], v[168:171], v[228:231], v[36:39]
	v_mfma_f32_16x16x32_bf16 v[32:35], v[176:179], v[228:231], v[32:35]
	s_setprio 0
	s_setprio 1
	v_mfma_f32_16x16x32_bf16 v[12:15], v[172:175], v[198:201], v[12:15]
	v_mfma_f32_16x16x32_bf16 v[8:11], v[190:193], v[198:201], v[8:11]
	v_mfma_f32_16x16x32_bf16 v[20:23], v[172:175], v[206:209], v[20:23]
	v_mfma_f32_16x16x32_bf16 v[16:19], v[190:193], v[206:209], v[16:19]
	v_mfma_f32_16x16x32_bf16 v[28:31], v[172:175], v[224:227], v[28:31]
	v_mfma_f32_16x16x32_bf16 v[24:27], v[190:193], v[224:227], v[24:27]
	v_mfma_f32_16x16x32_bf16 v[36:39], v[172:175], v[232:235], v[36:39]
	v_mfma_f32_16x16x32_bf16 v[32:35], v[190:193], v[232:235], v[32:35]
	s_setprio 0
	s_barrier
	s_add_i32 s51, s51, 2
	s_add_u32 s44, s44, 0x100
	s_addc_u32 s45, s45, 0
	s_cmp_gt_u32 s51, 13
	s_cbranch_scc0 .LBB0_293
	s_and_b64 vcc, exec, s[12:13]
	s_cbranch_vccz .LBB0_296
	s_barrier

.LBB0_334:
	s_add_u32 s25, s44, 0xfffc0080
	s_addc_u32 s40, s45, -1
	s_add_i32 s41, 0, 0x10000
	s_cmp_eq_u32 s88, 12
	s_cselect_b32 s49, s19, s40
	s_cselect_b32 s48, s64, s25
	s_cselect_b32 s47, s17, s69
	s_cselect_b32 s46, s65, s68
	s_add_i32 s25, 0, 0x14000
	v_add_u32_e32 v144, s41, v187
	v_add_u32_e32 v170, s25, v187
	ds_read_b128 v[132:135], v144
	ds_read_b128 v[136:139], v144 offset:1024
	ds_read_b128 v[140:143], v144 offset:2048
	ds_read_b128 v[144:147], v144 offset:3072
	ds_read_b128 v[148:151], v170
	ds_read_b128 v[152:155], v170 offset:1024
	ds_read_b128 v[156:159], v170 offset:2048
	ds_read_b128 v[170:173], v170 offset:3072
	v_lshl_add_u64 v[178:179], s[44:45], 0, v[166:167]
	s_add_i32 m0, s51, 0xc000
	ds_read_b128 v[174:177], v194
	ds_read_b128 v[196:199], v194 offset:1024
	ds_read_b128 v[200:203], v194 offset:2048
	ds_read_b128 v[204:207], v194 offset:3072
	ds_read_b128 v[208:211], v194 offset:4096
	ds_read_b128 v[218:221], v194 offset:5120
	ds_read_b128 v[224:227], v194 offset:6144
	ds_read_b128 v[228:231], v194 offset:7168
	global_load_lds_dwordx4 v[178:179], off
	v_lshl_add_u64 v[178:179], s[44:45], 0, v[168:169]
	s_add_i32 m0, s51, 0xe000
	s_nop 0
	global_load_lds_dwordx4 v[178:179], off
	s_waitcnt vmcnt(8)
	s_waitcnt lgkmcnt(0)
	s_barrier
	s_setprio 1
	s_waitcnt lgkmcnt(0)
	v_mfma_f32_16x16x32_bf16 v[128:131], v[132:135], v[174:177], v[128:131]
	v_mfma_f32_16x16x32_bf16 v[124:127], v[140:143], v[174:177], v[124:127]
	v_mfma_f32_16x16x32_bf16 v[112:115], v[132:135], v[200:203], v[112:115]
	v_mfma_f32_16x16x32_bf16 v[108:111], v[140:143], v[200:203], v[108:111]
	v_mfma_f32_16x16x32_bf16 v[96:99], v[132:135], v[208:211], v[96:99]
	v_mfma_f32_16x16x32_bf16 v[92:95], v[140:143], v[208:211], v[92:95]
	v_mfma_f32_16x16x32_bf16 v[80:83], v[132:135], v[224:227], v[80:83]
	v_mfma_f32_16x16x32_bf16 v[76:79], v[140:143], v[224:227], v[76:79]
	s_setprio 0
	s_setprio 1
	v_mfma_f32_16x16x32_bf16 v[128:131], v[136:139], v[196:199], v[128:131]
	v_mfma_f32_16x16x32_bf16 v[124:127], v[144:147], v[196:199], v[124:127]
	v_mfma_f32_16x16x32_bf16 v[112:115], v[136:139], v[204:207], v[112:115]
	v_mfma_f32_16x16x32_bf16 v[108:111], v[144:147], v[204:207], v[108:111]
	v_mfma_f32_16x16x32_bf16 v[96:99], v[136:139], v[218:221], v[96:99]
	v_mfma_f32_16x16x32_bf16 v[92:95], v[144:147], v[218:221], v[92:95]
	v_mfma_f32_16x16x32_bf16 v[80:83], v[136:139], v[228:231], v[80:83]
	v_mfma_f32_16x16x32_bf16 v[76:79], v[144:147], v[228:231], v[76:79]
	s_setprio 0
	s_setprio 1
	v_mfma_f32_16x16x32_bf16 v[120:123], v[148:151], v[174:177], v[120:123]
	v_mfma_f32_16x16x32_bf16 v[116:119], v[156:159], v[174:177], v[116:119]
	v_mfma_f32_16x16x32_bf16 v[104:107], v[148:151], v[200:203], v[104:107]
	v_mfma_f32_16x16x32_bf16 v[100:103], v[156:159], v[200:203], v[100:103]
	v_mfma_f32_16x16x32_bf16 v[88:91], v[148:151], v[208:211], v[88:91]
	v_mfma_f32_16x16x32_bf16 v[84:87], v[156:159], v[208:211], v[84:87]
	v_mfma_f32_16x16x32_bf16 v[72:75], v[148:151], v[224:227], v[72:75]
	v_mfma_f32_16x16x32_bf16 v[68:71], v[156:159], v[224:227], v[68:71]
	s_setprio 0
	s_setprio 1
	v_mfma_f32_16x16x32_bf16 v[120:123], v[152:155], v[196:199], v[120:123]
	v_mfma_f32_16x16x32_bf16 v[116:119], v[170:173], v[196:199], v[116:119]
	v_mfma_f32_16x16x32_bf16 v[104:107], v[152:155], v[204:207], v[104:107]
	v_mfma_f32_16x16x32_bf16 v[100:103], v[170:173], v[204:207], v[100:103]
	v_mfma_f32_16x16x32_bf16 v[88:91], v[152:155], v[218:221], v[88:91]
	v_mfma_f32_16x16x32_bf16 v[84:87], v[170:173], v[218:221], v[84:87]
	v_mfma_f32_16x16x32_bf16 v[72:75], v[152:155], v[228:231], v[72:75]
	v_mfma_f32_16x16x32_bf16 v[68:71], v[170:173], v[228:231], v[68:71]
	s_setprio 0
	s_barrier
	s_add_i32 s40, s41, s50
	v_lshl_add_u64 v[178:179], s[46:47], 0, v[162:163]
	s_mov_b32 m0, s40
	ds_read_b128 v[174:177], v194 offset:16384
	ds_read_b128 v[196:199], v194 offset:17408
	ds_read_b128 v[200:203], v194 offset:18432
	ds_read_b128 v[204:207], v194 offset:19456
	ds_read_b128 v[208:211], v194 offset:20480
	ds_read_b128 v[218:221], v194 offset:21504
	ds_read_b128 v[224:227], v194 offset:22528
	ds_read_b128 v[228:231], v194 offset:23552
	global_load_lds_dwordx4 v[178:179], off
	s_add_i32 m0, s40, 0x2000
	s_add_u32 s40, s46, 0x40000
	v_lshl_add_u64 v[182:183], s[46:47], 0, v[0:1]
	s_addc_u32 s41, s47, 0
	s_add_i32 s25, s25, s50
	global_load_lds_dwordx4 v[182:183], off
	v_lshl_add_u64 v[184:185], s[40:41], 0, v[162:163]
	s_mov_b32 m0, s25
	v_lshl_add_u64 v[190:191], s[48:49], 0, v[160:161]
	global_load_lds_dwordx4 v[184:185], off
	v_lshl_add_u64 v[184:185], s[40:41], 0, v[0:1]
	s_add_i32 m0, s25, 0x2000
	s_nop 0
	global_load_lds_dwordx4 v[184:185], off
	v_lshl_add_u64 v[184:185], s[48:49], 0, v[164:165]
	s_mov_b32 m0, s51
	s_nop 0
	global_load_lds_dwordx4 v[184:185], off
	s_mov_b32 m0, s52
	s_nop 0
	global_load_lds_dwordx4 v[190:191], off
	s_waitcnt vmcnt(8)
	s_waitcnt lgkmcnt(0)
	s_barrier
	s_setprio 1
	s_waitcnt lgkmcnt(0)
	v_mfma_f32_16x16x32_bf16 v[64:67], v[132:135], v[174:177], v[64:67]
	v_mfma_f32_16x16x32_bf16 v[60:63], v[140:143], v[174:177], v[60:63]
	v_mfma_f32_16x16x32_bf16 v[48:51], v[132:135], v[200:203], v[48:51]
	v_mfma_f32_16x16x32_bf16 v[44:47], v[140:143], v[200:203], v[44:47]
	v_mfma_f32_16x16x32_bf16 v[32:35], v[132:135], v[208:211], v[32:35]
	v_mfma_f32_16x16x32_bf16 v[28:31], v[140:143], v[208:211], v[28:31]
	v_mfma_f32_16x16x32_bf16 v[16:19], v[132:135], v[224:227], v[16:19]
	v_mfma_f32_16x16x32_bf16 v[12:15], v[140:143], v[224:227], v[12:15]
	s_setprio 0
	s_setprio 1
	v_mfma_f32_16x16x32_bf16 v[64:67], v[136:139], v[196:199], v[64:67]
	v_mfma_f32_16x16x32_bf16 v[60:63], v[144:147], v[196:199], v[60:63]
	v_mfma_f32_16x16x32_bf16 v[48:51], v[136:139], v[204:207], v[48:51]
	v_mfma_f32_16x16x32_bf16 v[44:47], v[144:147], v[204:207], v[44:47]
	v_mfma_f32_16x16x32_bf16 v[32:35], v[136:139], v[218:221], v[32:35]
	v_mfma_f32_16x16x32_bf16 v[28:31], v[144:147], v[218:221], v[28:31]
	v_mfma_f32_16x16x32_bf16 v[16:19], v[136:139], v[228:231], v[16:19]
	v_mfma_f32_16x16x32_bf16 v[12:15], v[144:147], v[228:231], v[12:15]
	s_setprio 0
	s_setprio 1
	v_mfma_f32_16x16x32_bf16 v[56:59], v[148:151], v[174:177], v[56:59]
	v_mfma_f32_16x16x32_bf16 v[52:55], v[156:159], v[174:177], v[52:55]
	v_mfma_f32_16x16x32_bf16 v[40:43], v[148:151], v[200:203], v[40:43]
	v_mfma_f32_16x16x32_bf16 v[36:39], v[156:159], v[200:203], v[36:39]
	v_mfma_f32_16x16x32_bf16 v[24:27], v[148:151], v[208:211], v[24:27]
	v_mfma_f32_16x16x32_bf16 v[20:23], v[156:159], v[208:211], v[20:23]
	v_mfma_f32_16x16x32_bf16 v[8:11], v[148:151], v[224:227], v[8:11]
	v_mfma_f32_16x16x32_bf16 v[4:7], v[156:159], v[224:227], v[4:7]
	s_setprio 0
	s_setprio 1
	v_mfma_f32_16x16x32_bf16 v[56:59], v[152:155], v[196:199], v[56:59]
	v_mfma_f32_16x16x32_bf16 v[52:55], v[170:173], v[196:199], v[52:55]
	v_mfma_f32_16x16x32_bf16 v[40:43], v[152:155], v[204:207], v[40:43]
	v_mfma_f32_16x16x32_bf16 v[36:39], v[170:173], v[204:207], v[36:39]
	v_mfma_f32_16x16x32_bf16 v[24:27], v[152:155], v[218:221], v[24:27]
	v_mfma_f32_16x16x32_bf16 v[20:23], v[170:173], v[218:221], v[20:23]
	v_mfma_f32_16x16x32_bf16 v[8:11], v[152:155], v[228:231], v[8:11]
	v_mfma_f32_16x16x32_bf16 v[4:7], v[170:173], v[228:231], v[4:7]
	s_setprio 0
	s_barrier
	s_add_i32 s25, 0, 0x18000
	s_add_i32 s70, 0, 0x1c000
	v_add_u32_e32 v144, s25, v187
	v_add_u32_e32 v170, s70, v187
	ds_read_b128 v[132:135], v144
	ds_read_b128 v[136:139], v144 offset:1024
	ds_read_b128 v[140:143], v144 offset:2048
	ds_read_b128 v[144:147], v144 offset:3072
	ds_read_b128 v[148:151], v170
	ds_read_b128 v[152:155], v170 offset:1024
	ds_read_b128 v[156:159], v170 offset:2048
	ds_read_b128 v[170:173], v170 offset:3072
	s_add_u32 s40, s48, 0x40000
	s_addc_u32 s41, s49, 0
	s_mov_b32 m0, s53
	v_lshl_add_u64 v[232:233], s[40:41], 0, v[164:165]
	ds_read_b128 v[174:177], v194 offset:32768
	ds_read_b128 v[196:199], v194 offset:33792
	ds_read_b128 v[200:203], v194 offset:34816
	ds_read_b128 v[204:207], v194 offset:35840
	ds_read_b128 v[208:211], v194 offset:36864
	ds_read_b128 v[218:221], v194 offset:37888
	ds_read_b128 v[224:227], v194 offset:38912
	ds_read_b128 v[228:231], v194 offset:39936
	global_load_lds_dwordx4 v[232:233], off
	v_lshl_add_u64 v[232:233], s[40:41], 0, v[160:161]
	s_mov_b32 m0, s54
	s_nop 0
	global_load_lds_dwordx4 v[232:233], off
	s_waitcnt vmcnt(8)
	s_waitcnt lgkmcnt(0)
	s_barrier
	s_setprio 1
	s_waitcnt lgkmcnt(0)
	v_mfma_f32_16x16x32_bf16 v[128:131], v[132:135], v[174:177], v[128:131]
	v_mfma_f32_16x16x32_bf16 v[124:127], v[140:143], v[174:177], v[124:127]
	v_mfma_f32_16x16x32_bf16 v[112:115], v[132:135], v[200:203], v[112:115]
	v_mfma_f32_16x16x32_bf16 v[108:111], v[140:143], v[200:203], v[108:111]
	v_mfma_f32_16x16x32_bf16 v[96:99], v[132:135], v[208:211], v[96:99]
	v_mfma_f32_16x16x32_bf16 v[92:95], v[140:143], v[208:211], v[92:95]
	v_mfma_f32_16x16x32_bf16 v[80:83], v[132:135], v[224:227], v[80:83]
	v_mfma_f32_16x16x32_bf16 v[76:79], v[140:143], v[224:227], v[76:79]
	s_setprio 0
	s_setprio 1
	v_mfma_f32_16x16x32_bf16 v[128:131], v[136:139], v[196:199], v[128:131]
	v_mfma_f32_16x16x32_bf16 v[124:127], v[144:147], v[196:199], v[124:127]
	v_mfma_f32_16x16x32_bf16 v[112:115], v[136:139], v[204:207], v[112:115]
	v_mfma_f32_16x16x32_bf16 v[108:111], v[144:147], v[204:207], v[108:111]
	v_mfma_f32_16x16x32_bf16 v[96:99], v[136:139], v[218:221], v[96:99]
	v_mfma_f32_16x16x32_bf16 v[92:95], v[144:147], v[218:221], v[92:95]
	v_mfma_f32_16x16x32_bf16 v[80:83], v[136:139], v[228:231], v[80:83]
	v_mfma_f32_16x16x32_bf16 v[76:79], v[144:147], v[228:231], v[76:79]
	s_setprio 0
	s_setprio 1
	v_mfma_f32_16x16x32_bf16 v[120:123], v[148:151], v[174:177], v[120:123]
	v_mfma_f32_16x16x32_bf16 v[116:119], v[156:159], v[174:177], v[116:119]
	v_mfma_f32_16x16x32_bf16 v[104:107], v[148:151], v[200:203], v[104:107]
	v_mfma_f32_16x16x32_bf16 v[100:103], v[156:159], v[200:203], v[100:103]
	v_mfma_f32_16x16x32_bf16 v[88:91], v[148:151], v[208:211], v[88:91]
	v_mfma_f32_16x16x32_bf16 v[84:87], v[156:159], v[208:211], v[84:87]
	v_mfma_f32_16x16x32_bf16 v[72:75], v[148:151], v[224:227], v[72:75]
	v_mfma_f32_16x16x32_bf16 v[68:71], v[156:159], v[224:227], v[68:71]
	s_setprio 0
	s_setprio 1
	v_mfma_f32_16x16x32_bf16 v[120:123], v[152:155], v[196:199], v[120:123]
	v_mfma_f32_16x16x32_bf16 v[116:119], v[170:173], v[196:199], v[116:119]
	v_mfma_f32_16x16x32_bf16 v[104:107], v[152:155], v[204:207], v[104:107]
	v_mfma_f32_16x16x32_bf16 v[100:103], v[170:173], v[204:207], v[100:103]
	v_mfma_f32_16x16x32_bf16 v[88:91], v[152:155], v[218:221], v[88:91]
	v_mfma_f32_16x16x32_bf16 v[84:87], v[170:173], v[218:221], v[84:87]
	v_mfma_f32_16x16x32_bf16 v[72:75], v[152:155], v[228:231], v[72:75]
	v_mfma_f32_16x16x32_bf16 v[68:71], v[170:173], v[228:231], v[68:71]
	s_setprio 0
	s_barrier
	s_add_i32 s25, s25, s50
	v_lshl_add_u64 v[178:179], v[178:179], 0, s[94:95]
	s_mov_b32 m0, s25
	ds_read_b128 v[174:177], v194 offset:49152
	ds_read_b128 v[196:199], v194 offset:50176
	ds_read_b128 v[200:203], v194 offset:51200
	ds_read_b128 v[204:207], v194 offset:52224
	ds_read_b128 v[208:211], v194 offset:53248
	ds_read_b128 v[218:221], v194 offset:54272
	ds_read_b128 v[224:227], v194 offset:55296
	ds_read_b128 v[228:231], v194 offset:56320
	global_load_lds_dwordx4 v[178:179], off
	s_add_i32 m0, s25, 0x2000
	s_add_u32 s40, s46, 0x40080
	v_lshl_add_u64 v[178:179], v[182:183], 0, s[94:95]
	s_addc_u32 s41, s47, 0
	s_add_i32 s25, s70, s50
	global_load_lds_dwordx4 v[178:179], off
	v_lshl_add_u64 v[178:179], s[40:41], 0, v[162:163]
	s_mov_b32 m0, s25
	s_nop 0
	global_load_lds_dwordx4 v[178:179], off
	v_lshl_add_u64 v[178:179], s[40:41], 0, v[0:1]
	s_add_i32 m0, s25, 0x2000
	s_nop 0
	global_load_lds_dwordx4 v[178:179], off
	v_lshl_add_u64 v[178:179], v[184:185], 0, s[94:95]
	s_mov_b32 m0, s55
	s_nop 0
	global_load_lds_dwordx4 v[178:179], off
	v_lshl_add_u64 v[178:179], v[190:191], 0, s[94:95]
	s_mov_b32 m0, s58
	s_nop 0
	global_load_lds_dwordx4 v[178:179], off
	s_waitcnt vmcnt(8)
	s_waitcnt lgkmcnt(0)
	s_barrier
	s_setprio 1
	s_waitcnt lgkmcnt(0)
	v_mfma_f32_16x16x32_bf16 v[64:67], v[132:135], v[174:177], v[64:67]
	v_mfma_f32_16x16x32_bf16 v[60:63], v[140:143], v[174:177], v[60:63]
	v_mfma_f32_16x16x32_bf16 v[48:51], v[132:135], v[200:203], v[48:51]
	v_mfma_f32_16x16x32_bf16 v[44:47], v[140:143], v[200:203], v[44:47]
	v_mfma_f32_16x16x32_bf16 v[32:35], v[132:135], v[208:211], v[32:35]
	v_mfma_f32_16x16x32_bf16 v[28:31], v[140:143], v[208:211], v[28:31]
	v_mfma_f32_16x16x32_bf16 v[16:19], v[132:135], v[224:227], v[16:19]
	v_mfma_f32_16x16x32_bf16 v[12:15], v[140:143], v[224:227], v[12:15]
	s_setprio 0
	s_setprio 1
	v_mfma_f32_16x16x32_bf16 v[64:67], v[136:139], v[196:199], v[64:67]
	v_mfma_f32_16x16x32_bf16 v[60:63], v[144:147], v[196:199], v[60:63]
	v_mfma_f32_16x16x32_bf16 v[48:51], v[136:139], v[204:207], v[48:51]
	v_mfma_f32_16x16x32_bf16 v[44:47], v[144:147], v[204:207], v[44:47]
	v_mfma_f32_16x16x32_bf16 v[32:35], v[136:139], v[218:221], v[32:35]
	v_mfma_f32_16x16x32_bf16 v[28:31], v[144:147], v[218:221], v[28:31]
	v_mfma_f32_16x16x32_bf16 v[16:19], v[136:139], v[228:231], v[16:19]
	v_mfma_f32_16x16x32_bf16 v[12:15], v[144:147], v[228:231], v[12:15]
	s_setprio 0
	s_setprio 1
	v_mfma_f32_16x16x32_bf16 v[56:59], v[148:151], v[174:177], v[56:59]
	v_mfma_f32_16x16x32_bf16 v[52:55], v[156:159], v[174:177], v[52:55]
	v_mfma_f32_16x16x32_bf16 v[40:43], v[148:151], v[200:203], v[40:43]
	v_mfma_f32_16x16x32_bf16 v[36:39], v[156:159], v[200:203], v[36:39]
	v_mfma_f32_16x16x32_bf16 v[24:27], v[148:151], v[208:211], v[24:27]
	v_mfma_f32_16x16x32_bf16 v[20:23], v[156:159], v[208:211], v[20:23]
	v_mfma_f32_16x16x32_bf16 v[8:11], v[148:151], v[224:227], v[8:11]
	v_mfma_f32_16x16x32_bf16 v[4:7], v[156:159], v[224:227], v[4:7]
	s_setprio 0
	s_setprio 1
	v_mfma_f32_16x16x32_bf16 v[56:59], v[152:155], v[196:199], v[56:59]
	v_mfma_f32_16x16x32_bf16 v[52:55], v[170:173], v[196:199], v[52:55]
	v_mfma_f32_16x16x32_bf16 v[40:43], v[152:155], v[204:207], v[40:43]
	v_mfma_f32_16x16x32_bf16 v[36:39], v[170:173], v[204:207], v[36:39]
	v_mfma_f32_16x16x32_bf16 v[24:27], v[152:155], v[218:221], v[24:27]
	v_mfma_f32_16x16x32_bf16 v[20:23], v[170:173], v[218:221], v[20:23]
	v_mfma_f32_16x16x32_bf16 v[8:11], v[152:155], v[228:231], v[8:11]
	v_mfma_f32_16x16x32_bf16 v[4:7], v[170:173], v[228:231], v[4:7]
	s_setprio 0
	s_barrier
	s_add_i32 s88, s88, 2
	s_add_u32 s44, s44, 0x100
	s_addc_u32 s45, s45, 0
	s_add_u32 s68, s68, 0x100
	s_addc_u32 s69, s69, 0
	s_cmp_gt_u32 s88, 13
	s_cbranch_scc0 .LBB0_334
	s_and_b64 vcc, exec, s[12:13]
	s_cbranch_vccz .LBB0_337
	s_barrier

.LBB0_595:
	s_add_u32 s36, s26, 0x100
	s_addc_u32 s37, s27, 0
	s_add_i32 s40, 0, 0x10000
	s_cmp_eq_u32 s89, 40
	s_cselect_b32 s47, s9, s37
	s_cselect_b32 s46, s8, s36
	s_cselect_b32 s45, s19, s88
	s_cselect_b32 s44, s18, s69
	s_add_i32 s41, 0, 0x14000
	v_add_u32_e32 v144, s40, v170
	v_add_u32_e32 v168, s41, v170
	ds_read_b128 v[132:135], v144
	ds_read_b128 v[136:139], v144 offset:1024
	ds_read_b128 v[140:143], v144 offset:2048
	ds_read_b128 v[144:147], v144 offset:3072
	ds_read_b128 v[148:151], v168
	ds_read_b128 v[160:163], v168 offset:1024
	ds_read_b128 v[164:167], v168 offset:2048
	ds_read_b128 v[174:177], v168 offset:3072
	v_lshl_add_u64 v[168:169], s[26:27], 0, v[156:157]
	s_add_i32 m0, s49, 0xc000
	ds_read_b128 v[190:193], v172
	ds_read_b128 v[194:197], v172 offset:1024
	ds_read_b128 v[198:201], v172 offset:2048
	ds_read_b128 v[202:205], v172 offset:3072
	ds_read_b128 v[206:209], v172 offset:4096
	ds_read_b128 v[218:221], v172 offset:5120
	ds_read_b128 v[224:227], v172 offset:6144
	ds_read_b128 v[228:231], v172 offset:7168
	global_load_lds_dwordx4 v[168:169], off
	v_lshl_add_u64 v[168:169], s[26:27], 0, v[158:159]
	s_add_i32 m0, s49, 0xe000
	s_nop 0
	global_load_lds_dwordx4 v[168:169], off
	s_waitcnt vmcnt(8)
	s_waitcnt lgkmcnt(0)
	s_barrier
	s_setprio 1
	s_waitcnt lgkmcnt(0)
	v_mfma_f32_16x16x32_bf16 v[128:131], v[132:135], v[190:193], v[128:131]
	v_mfma_f32_16x16x32_bf16 v[124:127], v[140:143], v[190:193], v[124:127]
	v_mfma_f32_16x16x32_bf16 v[120:123], v[132:135], v[198:201], v[120:123]
	v_mfma_f32_16x16x32_bf16 v[116:119], v[140:143], v[198:201], v[116:119]
	v_mfma_f32_16x16x32_bf16 v[96:99], v[132:135], v[206:209], v[96:99]
	v_mfma_f32_16x16x32_bf16 v[92:95], v[140:143], v[206:209], v[92:95]
	v_mfma_f32_16x16x32_bf16 v[84:87], v[132:135], v[224:227], v[84:87]
	v_mfma_f32_16x16x32_bf16 v[76:79], v[140:143], v[224:227], v[76:79]
	s_setprio 0
	s_setprio 1
	v_mfma_f32_16x16x32_bf16 v[128:131], v[136:139], v[194:197], v[128:131]
	v_mfma_f32_16x16x32_bf16 v[124:127], v[144:147], v[194:197], v[124:127]
	v_mfma_f32_16x16x32_bf16 v[120:123], v[136:139], v[202:205], v[120:123]
	v_mfma_f32_16x16x32_bf16 v[116:119], v[144:147], v[202:205], v[116:119]
	v_mfma_f32_16x16x32_bf16 v[96:99], v[136:139], v[218:221], v[96:99]
	v_mfma_f32_16x16x32_bf16 v[92:95], v[144:147], v[218:221], v[92:95]
	v_mfma_f32_16x16x32_bf16 v[84:87], v[136:139], v[228:231], v[84:87]
	v_mfma_f32_16x16x32_bf16 v[76:79], v[144:147], v[228:231], v[76:79]
	s_setprio 0
	s_setprio 1
	v_mfma_f32_16x16x32_bf16 v[112:115], v[148:151], v[190:193], v[112:115]
	v_mfma_f32_16x16x32_bf16 v[108:111], v[164:167], v[190:193], v[108:111]
	v_mfma_f32_16x16x32_bf16 v[104:107], v[148:151], v[198:201], v[104:107]
	v_mfma_f32_16x16x32_bf16 v[100:103], v[164:167], v[198:201], v[100:103]
	v_mfma_f32_16x16x32_bf16 v[88:91], v[148:151], v[206:209], v[88:91]
	v_mfma_f32_16x16x32_bf16 v[80:83], v[164:167], v[206:209], v[80:83]
	v_mfma_f32_16x16x32_bf16 v[72:75], v[148:151], v[224:227], v[72:75]
	v_mfma_f32_16x16x32_bf16 v[68:71], v[164:167], v[224:227], v[68:71]
	s_setprio 0
	s_setprio 1
	v_mfma_f32_16x16x32_bf16 v[112:115], v[160:163], v[194:197], v[112:115]
	v_mfma_f32_16x16x32_bf16 v[108:111], v[174:177], v[194:197], v[108:111]
	v_mfma_f32_16x16x32_bf16 v[104:107], v[160:163], v[202:205], v[104:107]
	v_mfma_f32_16x16x32_bf16 v[100:103], v[174:177], v[202:205], v[100:103]
	v_mfma_f32_16x16x32_bf16 v[88:91], v[160:163], v[218:221], v[88:91]
	v_mfma_f32_16x16x32_bf16 v[80:83], v[174:177], v[218:221], v[80:83]
	v_mfma_f32_16x16x32_bf16 v[72:75], v[160:163], v[228:231], v[72:75]
	v_mfma_f32_16x16x32_bf16 v[68:71], v[174:177], v[228:231], v[68:71]
	s_setprio 0
	s_barrier
	s_add_i32 s26, s40, s48
	v_lshl_add_u64 v[168:169], s[44:45], 0, v[180:181]
	s_mov_b32 m0, s26
	ds_read_b128 v[190:193], v172 offset:16384
	ds_read_b128 v[194:197], v172 offset:17408
	ds_read_b128 v[198:201], v172 offset:18432
	ds_read_b128 v[202:205], v172 offset:19456
	ds_read_b128 v[206:209], v172 offset:20480
	ds_read_b128 v[218:221], v172 offset:21504
	ds_read_b128 v[224:227], v172 offset:22528
	ds_read_b128 v[228:231], v172 offset:23552
	global_load_lds_dwordx4 v[168:169], off
	s_add_i32 m0, s26, 0x2000
	s_add_u32 s26, s44, 0xb0000
	v_lshl_add_u64 v[178:179], s[44:45], 0, v[0:1]
	s_addc_u32 s27, s45, 0
	s_add_i32 s40, s41, s48
	global_load_lds_dwordx4 v[178:179], off
	v_lshl_add_u64 v[182:183], s[26:27], 0, v[180:181]
	s_mov_b32 m0, s40
	v_lshl_add_u64 v[184:185], s[46:47], 0, v[152:153]
	global_load_lds_dwordx4 v[182:183], off
	v_lshl_add_u64 v[182:183], s[26:27], 0, v[0:1]
	s_add_i32 m0, s40, 0x2000
	s_nop 0
	global_load_lds_dwordx4 v[182:183], off
	v_lshl_add_u64 v[182:183], s[46:47], 0, v[154:155]
	s_mov_b32 m0, s49
	s_nop 0
	global_load_lds_dwordx4 v[182:183], off
	s_mov_b32 m0, s50
	s_nop 0
	global_load_lds_dwordx4 v[184:185], off
	s_waitcnt vmcnt(8)
	s_waitcnt lgkmcnt(0)
	s_barrier
	s_setprio 1
	s_waitcnt lgkmcnt(0)
	v_mfma_f32_16x16x32_bf16 v[64:67], v[132:135], v[190:193], v[64:67]
	v_mfma_f32_16x16x32_bf16 v[60:63], v[140:143], v[190:193], v[60:63]
	v_mfma_f32_16x16x32_bf16 v[52:55], v[132:135], v[198:201], v[52:55]
	v_mfma_f32_16x16x32_bf16 v[44:47], v[140:143], v[198:201], v[44:47]
	v_mfma_f32_16x16x32_bf16 v[36:39], v[132:135], v[206:209], v[36:39]
	v_mfma_f32_16x16x32_bf16 v[28:31], v[140:143], v[206:209], v[28:31]
	v_mfma_f32_16x16x32_bf16 v[20:23], v[132:135], v[224:227], v[20:23]
	v_mfma_f32_16x16x32_bf16 v[12:15], v[140:143], v[224:227], v[12:15]
	s_setprio 0
	s_setprio 1
	v_mfma_f32_16x16x32_bf16 v[64:67], v[136:139], v[194:197], v[64:67]
	v_mfma_f32_16x16x32_bf16 v[60:63], v[144:147], v[194:197], v[60:63]
	v_mfma_f32_16x16x32_bf16 v[52:55], v[136:139], v[202:205], v[52:55]
	v_mfma_f32_16x16x32_bf16 v[44:47], v[144:147], v[202:205], v[44:47]
	v_mfma_f32_16x16x32_bf16 v[36:39], v[136:139], v[218:221], v[36:39]
	v_mfma_f32_16x16x32_bf16 v[28:31], v[144:147], v[218:221], v[28:31]
	v_mfma_f32_16x16x32_bf16 v[20:23], v[136:139], v[228:231], v[20:23]
	v_mfma_f32_16x16x32_bf16 v[12:15], v[144:147], v[228:231], v[12:15]
	s_setprio 0
	s_setprio 1
	v_mfma_f32_16x16x32_bf16 v[56:59], v[148:151], v[190:193], v[56:59]
	v_mfma_f32_16x16x32_bf16 v[48:51], v[164:167], v[190:193], v[48:51]
	v_mfma_f32_16x16x32_bf16 v[40:43], v[148:151], v[198:201], v[40:43]
	v_mfma_f32_16x16x32_bf16 v[32:35], v[164:167], v[198:201], v[32:35]
	v_mfma_f32_16x16x32_bf16 v[24:27], v[148:151], v[206:209], v[24:27]
	v_mfma_f32_16x16x32_bf16 v[16:19], v[164:167], v[206:209], v[16:19]
	v_mfma_f32_16x16x32_bf16 v[8:11], v[148:151], v[224:227], v[8:11]
	v_mfma_f32_16x16x32_bf16 v[4:7], v[164:167], v[224:227], v[4:7]
	s_setprio 0
	s_setprio 1
	v_mfma_f32_16x16x32_bf16 v[56:59], v[160:163], v[194:197], v[56:59]
	v_mfma_f32_16x16x32_bf16 v[48:51], v[174:177], v[194:197], v[48:51]
	v_mfma_f32_16x16x32_bf16 v[40:43], v[160:163], v[202:205], v[40:43]
	v_mfma_f32_16x16x32_bf16 v[32:35], v[174:177], v[202:205], v[32:35]
	v_mfma_f32_16x16x32_bf16 v[24:27], v[160:163], v[218:221], v[24:27]
	v_mfma_f32_16x16x32_bf16 v[16:19], v[174:177], v[218:221], v[16:19]
	v_mfma_f32_16x16x32_bf16 v[8:11], v[160:163], v[228:231], v[8:11]
	v_mfma_f32_16x16x32_bf16 v[4:7], v[174:177], v[228:231], v[4:7]
	s_setprio 0
	s_barrier
	s_add_i32 s40, 0, 0x18000
	s_add_i32 s41, 0, 0x1c000
	v_add_u32_e32 v144, s40, v170
	v_add_u32_e32 v173, s41, v170
	ds_read_b128 v[132:135], v144
	ds_read_b128 v[136:139], v144 offset:1024
	ds_read_b128 v[140:143], v144 offset:2048
	ds_read_b128 v[144:147], v144 offset:3072
	ds_read_b128 v[148:151], v173
	ds_read_b128 v[160:163], v173 offset:1024
	ds_read_b128 v[164:167], v173 offset:2048
	ds_read_b128 v[174:177], v173 offset:3072
	s_add_u32 s26, s46, 0xb0000
	s_addc_u32 s27, s47, 0
	s_mov_b32 m0, s51
	v_lshl_add_u64 v[210:211], s[26:27], 0, v[154:155]
	ds_read_b128 v[190:193], v172 offset:32768
	ds_read_b128 v[194:197], v172 offset:33792
	ds_read_b128 v[198:201], v172 offset:34816
	ds_read_b128 v[202:205], v172 offset:35840
	ds_read_b128 v[206:209], v172 offset:36864
	ds_read_b128 v[218:221], v172 offset:37888
	ds_read_b128 v[224:227], v172 offset:38912
	ds_read_b128 v[228:231], v172 offset:39936
	global_load_lds_dwordx4 v[210:211], off
	v_lshl_add_u64 v[210:211], s[26:27], 0, v[152:153]
	s_mov_b32 m0, s53
	s_nop 0
	global_load_lds_dwordx4 v[210:211], off
	s_waitcnt vmcnt(8)
	s_waitcnt lgkmcnt(0)
	s_barrier
	s_setprio 1
	s_waitcnt lgkmcnt(0)
	v_mfma_f32_16x16x32_bf16 v[128:131], v[132:135], v[190:193], v[128:131]
	v_mfma_f32_16x16x32_bf16 v[124:127], v[140:143], v[190:193], v[124:127]
	v_mfma_f32_16x16x32_bf16 v[120:123], v[132:135], v[198:201], v[120:123]
	v_mfma_f32_16x16x32_bf16 v[116:119], v[140:143], v[198:201], v[116:119]
	v_mfma_f32_16x16x32_bf16 v[96:99], v[132:135], v[206:209], v[96:99]
	v_mfma_f32_16x16x32_bf16 v[92:95], v[140:143], v[206:209], v[92:95]
	v_mfma_f32_16x16x32_bf16 v[84:87], v[132:135], v[224:227], v[84:87]
	v_mfma_f32_16x16x32_bf16 v[76:79], v[140:143], v[224:227], v[76:79]
	s_setprio 0
	s_setprio 1
	v_mfma_f32_16x16x32_bf16 v[128:131], v[136:139], v[194:197], v[128:131]
	v_mfma_f32_16x16x32_bf16 v[124:127], v[144:147], v[194:197], v[124:127]
	v_mfma_f32_16x16x32_bf16 v[120:123], v[136:139], v[202:205], v[120:123]
	v_mfma_f32_16x16x32_bf16 v[116:119], v[144:147], v[202:205], v[116:119]
	v_mfma_f32_16x16x32_bf16 v[96:99], v[136:139], v[218:221], v[96:99]
	v_mfma_f32_16x16x32_bf16 v[92:95], v[144:147], v[218:221], v[92:95]
	v_mfma_f32_16x16x32_bf16 v[84:87], v[136:139], v[228:231], v[84:87]
	v_mfma_f32_16x16x32_bf16 v[76:79], v[144:147], v[228:231], v[76:79]
	s_setprio 0
	s_setprio 1
	v_mfma_f32_16x16x32_bf16 v[112:115], v[148:151], v[190:193], v[112:115]
	v_mfma_f32_16x16x32_bf16 v[108:111], v[164:167], v[190:193], v[108:111]
	v_mfma_f32_16x16x32_bf16 v[104:107], v[148:151], v[198:201], v[104:107]
	v_mfma_f32_16x16x32_bf16 v[100:103], v[164:167], v[198:201], v[100:103]
	v_mfma_f32_16x16x32_bf16 v[88:91], v[148:151], v[206:209], v[88:91]
	v_mfma_f32_16x16x32_bf16 v[80:83], v[164:167], v[206:209], v[80:83]
	v_mfma_f32_16x16x32_bf16 v[72:75], v[148:151], v[224:227], v[72:75]
	v_mfma_f32_16x16x32_bf16 v[68:71], v[164:167], v[224:227], v[68:71]
	s_setprio 0
	s_setprio 1
	v_mfma_f32_16x16x32_bf16 v[112:115], v[160:163], v[194:197], v[112:115]
	v_mfma_f32_16x16x32_bf16 v[108:111], v[174:177], v[194:197], v[108:111]
	v_mfma_f32_16x16x32_bf16 v[104:107], v[160:163], v[202:205], v[104:107]
	v_mfma_f32_16x16x32_bf16 v[100:103], v[174:177], v[202:205], v[100:103]
	v_mfma_f32_16x16x32_bf16 v[88:91], v[160:163], v[218:221], v[88:91]
	v_mfma_f32_16x16x32_bf16 v[80:83], v[174:177], v[218:221], v[80:83]
	v_mfma_f32_16x16x32_bf16 v[72:75], v[160:163], v[228:231], v[72:75]
	v_mfma_f32_16x16x32_bf16 v[68:71], v[174:177], v[228:231], v[68:71]
	s_setprio 0
	s_barrier
	s_add_i32 s26, s40, s48
	v_lshl_add_u64 v[168:169], v[168:169], 0, s[94:95]
	s_mov_b32 m0, s26
	ds_read_b128 v[190:193], v172 offset:49152
	ds_read_b128 v[194:197], v172 offset:50176
	ds_read_b128 v[198:201], v172 offset:51200
	ds_read_b128 v[202:205], v172 offset:52224
	ds_read_b128 v[206:209], v172 offset:53248
	ds_read_b128 v[218:221], v172 offset:54272
	ds_read_b128 v[224:227], v172 offset:55296
	ds_read_b128 v[228:231], v172 offset:56320
	global_load_lds_dwordx4 v[168:169], off
	s_add_i32 m0, s26, 0x2000
	s_add_u32 s26, s44, 0xb0080
	v_lshl_add_u64 v[168:169], v[178:179], 0, s[94:95]
	s_addc_u32 s27, s45, 0
	s_add_i32 s40, s41, s48
	global_load_lds_dwordx4 v[168:169], off
	v_lshl_add_u64 v[168:169], s[26:27], 0, v[180:181]
	s_mov_b32 m0, s40
	s_nop 0
	global_load_lds_dwordx4 v[168:169], off
	v_lshl_add_u64 v[168:169], s[26:27], 0, v[0:1]
	s_add_i32 m0, s40, 0x2000
	s_nop 0
	global_load_lds_dwordx4 v[168:169], off
	v_lshl_add_u64 v[168:169], v[182:183], 0, s[94:95]
	s_mov_b32 m0, s54
	s_nop 0
	global_load_lds_dwordx4 v[168:169], off
	v_lshl_add_u64 v[168:169], v[184:185], 0, s[94:95]
	s_mov_b32 m0, s55
	s_nop 0
	global_load_lds_dwordx4 v[168:169], off
	s_waitcnt vmcnt(8)
	s_waitcnt lgkmcnt(0)
	s_barrier
	s_setprio 1
	s_waitcnt lgkmcnt(0)
	v_mfma_f32_16x16x32_bf16 v[64:67], v[132:135], v[190:193], v[64:67]
	v_mfma_f32_16x16x32_bf16 v[60:63], v[140:143], v[190:193], v[60:63]
	v_mfma_f32_16x16x32_bf16 v[52:55], v[132:135], v[198:201], v[52:55]
	v_mfma_f32_16x16x32_bf16 v[44:47], v[140:143], v[198:201], v[44:47]
	v_mfma_f32_16x16x32_bf16 v[36:39], v[132:135], v[206:209], v[36:39]
	v_mfma_f32_16x16x32_bf16 v[28:31], v[140:143], v[206:209], v[28:31]
	v_mfma_f32_16x16x32_bf16 v[20:23], v[132:135], v[224:227], v[20:23]
	v_mfma_f32_16x16x32_bf16 v[12:15], v[140:143], v[224:227], v[12:15]
	s_setprio 0
	s_setprio 1
	v_mfma_f32_16x16x32_bf16 v[64:67], v[136:139], v[194:197], v[64:67]
	v_mfma_f32_16x16x32_bf16 v[60:63], v[144:147], v[194:197], v[60:63]
	v_mfma_f32_16x16x32_bf16 v[52:55], v[136:139], v[202:205], v[52:55]
	v_mfma_f32_16x16x32_bf16 v[44:47], v[144:147], v[202:205], v[44:47]
	v_mfma_f32_16x16x32_bf16 v[36:39], v[136:139], v[218:221], v[36:39]
	v_mfma_f32_16x16x32_bf16 v[28:31], v[144:147], v[218:221], v[28:31]
	v_mfma_f32_16x16x32_bf16 v[20:23], v[136:139], v[228:231], v[20:23]
	v_mfma_f32_16x16x32_bf16 v[12:15], v[144:147], v[228:231], v[12:15]
	s_setprio 0
	s_setprio 1
	v_mfma_f32_16x16x32_bf16 v[56:59], v[148:151], v[190:193], v[56:59]
	v_mfma_f32_16x16x32_bf16 v[48:51], v[164:167], v[190:193], v[48:51]
	v_mfma_f32_16x16x32_bf16 v[40:43], v[148:151], v[198:201], v[40:43]
	v_mfma_f32_16x16x32_bf16 v[32:35], v[164:167], v[198:201], v[32:35]
	v_mfma_f32_16x16x32_bf16 v[24:27], v[148:151], v[206:209], v[24:27]
	v_mfma_f32_16x16x32_bf16 v[16:19], v[164:167], v[206:209], v[16:19]
	v_mfma_f32_16x16x32_bf16 v[8:11], v[148:151], v[224:227], v[8:11]
	v_mfma_f32_16x16x32_bf16 v[4:7], v[164:167], v[224:227], v[4:7]
	s_setprio 0
	s_setprio 1
	v_mfma_f32_16x16x32_bf16 v[56:59], v[160:163], v[194:197], v[56:59]
	v_mfma_f32_16x16x32_bf16 v[48:51], v[174:177], v[194:197], v[48:51]
	v_mfma_f32_16x16x32_bf16 v[40:43], v[160:163], v[202:205], v[40:43]
	v_mfma_f32_16x16x32_bf16 v[32:35], v[174:177], v[202:205], v[32:35]
	v_mfma_f32_16x16x32_bf16 v[24:27], v[160:163], v[218:221], v[24:27]
	v_mfma_f32_16x16x32_bf16 v[16:19], v[174:177], v[218:221], v[16:19]
	v_mfma_f32_16x16x32_bf16 v[8:11], v[160:163], v[228:231], v[8:11]
	v_mfma_f32_16x16x32_bf16 v[4:7], v[174:177], v[228:231], v[4:7]
	s_setprio 0
	s_barrier
	s_add_i32 s89, s89, 2
	s_add_u32 s69, s69, 0x100
	s_addc_u32 s88, s88, 0
	s_cmp_gt_u32 s89, 41
	s_mov_b64 s[26:27], s[36:37]
	s_cbranch_scc0 .LBB0_595
	s_and_b64 vcc, exec, s[16:17]
	s_cbranch_vccz .LBB0_598
	s_barrier

.LBB0_624:
	s_add_u32 s46, s44, 0x100
	s_addc_u32 s47, s45, 0
	s_add_i32 s40, 0, 0x10000
	s_cmp_eq_u32 s97, 40
	s_cselect_b32 s51, s13, s47
	s_cselect_b32 s50, s12, s46
	s_cselect_b32 s49, s37, s90
	s_cselect_b32 s48, s36, s89
	s_add_i32 s70, 0, 0x14000
	v_add_u32_e32 v144, s40, v187
	v_add_u32_e32 v170, s70, v187
	ds_read_b128 v[132:135], v144
	ds_read_b128 v[136:139], v144 offset:1024
	ds_read_b128 v[140:143], v144 offset:2048
	ds_read_b128 v[144:147], v144 offset:3072
	ds_read_b128 v[148:151], v170
	ds_read_b128 v[152:155], v170 offset:1024
	ds_read_b128 v[156:159], v170 offset:2048
	ds_read_b128 v[170:173], v170 offset:3072
	v_lshl_add_u64 v[178:179], s[44:45], 0, v[166:167]
	s_add_i32 m0, s54, 0xc000
	ds_read_b128 v[174:177], v194
	ds_read_b128 v[196:199], v194 offset:1024
	ds_read_b128 v[200:203], v194 offset:2048
	ds_read_b128 v[204:207], v194 offset:3072
	ds_read_b128 v[208:211], v194 offset:4096
	ds_read_b128 v[218:221], v194 offset:5120
	ds_read_b128 v[224:227], v194 offset:6144
	ds_read_b128 v[228:231], v194 offset:7168
	global_load_lds_dwordx4 v[178:179], off
	v_lshl_add_u64 v[178:179], s[44:45], 0, v[168:169]
	s_add_i32 m0, s54, 0xe000
	s_nop 0
	global_load_lds_dwordx4 v[178:179], off
	s_waitcnt vmcnt(8)
	s_waitcnt lgkmcnt(0)
	s_barrier
	s_setprio 1
	s_waitcnt lgkmcnt(0)
	v_mfma_f32_16x16x32_bf16 v[128:131], v[132:135], v[174:177], v[128:131]
	v_mfma_f32_16x16x32_bf16 v[124:127], v[140:143], v[174:177], v[124:127]
	v_mfma_f32_16x16x32_bf16 v[112:115], v[132:135], v[200:203], v[112:115]
	v_mfma_f32_16x16x32_bf16 v[108:111], v[140:143], v[200:203], v[108:111]
	v_mfma_f32_16x16x32_bf16 v[96:99], v[132:135], v[208:211], v[96:99]
	v_mfma_f32_16x16x32_bf16 v[92:95], v[140:143], v[208:211], v[92:95]
	v_mfma_f32_16x16x32_bf16 v[80:83], v[132:135], v[224:227], v[80:83]
	v_mfma_f32_16x16x32_bf16 v[76:79], v[140:143], v[224:227], v[76:79]
	s_setprio 0
	s_setprio 1
	v_mfma_f32_16x16x32_bf16 v[128:131], v[136:139], v[196:199], v[128:131]
	v_mfma_f32_16x16x32_bf16 v[124:127], v[144:147], v[196:199], v[124:127]
	v_mfma_f32_16x16x32_bf16 v[112:115], v[136:139], v[204:207], v[112:115]
	v_mfma_f32_16x16x32_bf16 v[108:111], v[144:147], v[204:207], v[108:111]
	v_mfma_f32_16x16x32_bf16 v[96:99], v[136:139], v[218:221], v[96:99]
	v_mfma_f32_16x16x32_bf16 v[92:95], v[144:147], v[218:221], v[92:95]
	v_mfma_f32_16x16x32_bf16 v[80:83], v[136:139], v[228:231], v[80:83]
	v_mfma_f32_16x16x32_bf16 v[76:79], v[144:147], v[228:231], v[76:79]
	s_setprio 0
	s_setprio 1
	v_mfma_f32_16x16x32_bf16 v[120:123], v[148:151], v[174:177], v[120:123]
	v_mfma_f32_16x16x32_bf16 v[116:119], v[156:159], v[174:177], v[116:119]
	v_mfma_f32_16x16x32_bf16 v[104:107], v[148:151], v[200:203], v[104:107]
	v_mfma_f32_16x16x32_bf16 v[100:103], v[156:159], v[200:203], v[100:103]
	v_mfma_f32_16x16x32_bf16 v[88:91], v[148:151], v[208:211], v[88:91]
	v_mfma_f32_16x16x32_bf16 v[84:87], v[156:159], v[208:211], v[84:87]
	v_mfma_f32_16x16x32_bf16 v[72:75], v[148:151], v[224:227], v[72:75]
	v_mfma_f32_16x16x32_bf16 v[68:71], v[156:159], v[224:227], v[68:71]
	s_setprio 0
	s_setprio 1
	v_mfma_f32_16x16x32_bf16 v[120:123], v[152:155], v[196:199], v[120:123]
	v_mfma_f32_16x16x32_bf16 v[116:119], v[170:173], v[196:199], v[116:119]
	v_mfma_f32_16x16x32_bf16 v[104:107], v[152:155], v[204:207], v[104:107]
	v_mfma_f32_16x16x32_bf16 v[100:103], v[170:173], v[204:207], v[100:103]
	v_mfma_f32_16x16x32_bf16 v[88:91], v[152:155], v[218:221], v[88:91]
	v_mfma_f32_16x16x32_bf16 v[84:87], v[170:173], v[218:221], v[84:87]
	v_mfma_f32_16x16x32_bf16 v[72:75], v[152:155], v[228:231], v[72:75]
	v_mfma_f32_16x16x32_bf16 v[68:71], v[170:173], v[228:231], v[68:71]
	s_setprio 0
	s_barrier
	s_add_i32 s40, s40, s53
	v_lshl_add_u64 v[178:179], s[48:49], 0, v[162:163]
	s_mov_b32 m0, s40
	ds_read_b128 v[174:177], v194 offset:16384
	ds_read_b128 v[196:199], v194 offset:17408
	ds_read_b128 v[200:203], v194 offset:18432
	ds_read_b128 v[204:207], v194 offset:19456
	ds_read_b128 v[208:211], v194 offset:20480
	ds_read_b128 v[218:221], v194 offset:21504
	ds_read_b128 v[224:227], v194 offset:22528
	ds_read_b128 v[228:231], v194 offset:23552
	global_load_lds_dwordx4 v[178:179], off
	s_add_i32 m0, s40, 0x2000
	s_add_u32 s40, s48, 0xb0000
	v_lshl_add_u64 v[182:183], s[48:49], 0, v[0:1]
	s_addc_u32 s41, s49, 0
	s_add_i32 s44, s70, s53
	global_load_lds_dwordx4 v[182:183], off
	v_lshl_add_u64 v[184:185], s[40:41], 0, v[162:163]
	s_mov_b32 m0, s44
	v_lshl_add_u64 v[190:191], s[50:51], 0, v[160:161]
	global_load_lds_dwordx4 v[184:185], off
	v_lshl_add_u64 v[184:185], s[40:41], 0, v[0:1]
	s_add_i32 m0, s44, 0x2000
	s_nop 0
	global_load_lds_dwordx4 v[184:185], off
	v_lshl_add_u64 v[184:185], s[50:51], 0, v[164:165]
	s_mov_b32 m0, s54
	s_nop 0
	global_load_lds_dwordx4 v[184:185], off
	s_mov_b32 m0, s55
	s_nop 0
	global_load_lds_dwordx4 v[190:191], off
	s_waitcnt vmcnt(8)
	s_waitcnt lgkmcnt(0)
	s_barrier
	s_setprio 1
	s_waitcnt lgkmcnt(0)
	v_mfma_f32_16x16x32_bf16 v[64:67], v[132:135], v[174:177], v[64:67]
	v_mfma_f32_16x16x32_bf16 v[60:63], v[140:143], v[174:177], v[60:63]
	v_mfma_f32_16x16x32_bf16 v[48:51], v[132:135], v[200:203], v[48:51]
	v_mfma_f32_16x16x32_bf16 v[44:47], v[140:143], v[200:203], v[44:47]
	v_mfma_f32_16x16x32_bf16 v[32:35], v[132:135], v[208:211], v[32:35]
	v_mfma_f32_16x16x32_bf16 v[28:31], v[140:143], v[208:211], v[28:31]
	v_mfma_f32_16x16x32_bf16 v[16:19], v[132:135], v[224:227], v[16:19]
	v_mfma_f32_16x16x32_bf16 v[12:15], v[140:143], v[224:227], v[12:15]
	s_setprio 0
	s_setprio 1
	v_mfma_f32_16x16x32_bf16 v[64:67], v[136:139], v[196:199], v[64:67]
	v_mfma_f32_16x16x32_bf16 v[60:63], v[144:147], v[196:199], v[60:63]
	v_mfma_f32_16x16x32_bf16 v[48:51], v[136:139], v[204:207], v[48:51]
	v_mfma_f32_16x16x32_bf16 v[44:47], v[144:147], v[204:207], v[44:47]
	v_mfma_f32_16x16x32_bf16 v[32:35], v[136:139], v[218:221], v[32:35]
	v_mfma_f32_16x16x32_bf16 v[28:31], v[144:147], v[218:221], v[28:31]
	v_mfma_f32_16x16x32_bf16 v[16:19], v[136:139], v[228:231], v[16:19]
	v_mfma_f32_16x16x32_bf16 v[12:15], v[144:147], v[228:231], v[12:15]
	s_setprio 0
	s_setprio 1
	v_mfma_f32_16x16x32_bf16 v[56:59], v[148:151], v[174:177], v[56:59]
	v_mfma_f32_16x16x32_bf16 v[52:55], v[156:159], v[174:177], v[52:55]
	v_mfma_f32_16x16x32_bf16 v[40:43], v[148:151], v[200:203], v[40:43]
	v_mfma_f32_16x16x32_bf16 v[36:39], v[156:159], v[200:203], v[36:39]
	v_mfma_f32_16x16x32_bf16 v[24:27], v[148:151], v[208:211], v[24:27]
	v_mfma_f32_16x16x32_bf16 v[20:23], v[156:159], v[208:211], v[20:23]
	v_mfma_f32_16x16x32_bf16 v[8:11], v[148:151], v[224:227], v[8:11]
	v_mfma_f32_16x16x32_bf16 v[4:7], v[156:159], v[224:227], v[4:7]
	s_setprio 0
	s_setprio 1
	v_mfma_f32_16x16x32_bf16 v[56:59], v[152:155], v[196:199], v[56:59]
	v_mfma_f32_16x16x32_bf16 v[52:55], v[170:173], v[196:199], v[52:55]
	v_mfma_f32_16x16x32_bf16 v[40:43], v[152:155], v[204:207], v[40:43]
	v_mfma_f32_16x16x32_bf16 v[36:39], v[170:173], v[204:207], v[36:39]
	v_mfma_f32_16x16x32_bf16 v[24:27], v[152:155], v[218:221], v[24:27]
	v_mfma_f32_16x16x32_bf16 v[20:23], v[170:173], v[218:221], v[20:23]
	v_mfma_f32_16x16x32_bf16 v[8:11], v[152:155], v[228:231], v[8:11]
	v_mfma_f32_16x16x32_bf16 v[4:7], v[170:173], v[228:231], v[4:7]
	s_setprio 0
	s_barrier
	s_add_i32 s44, 0, 0x18000
	s_add_i32 s45, 0, 0x1c000
	v_add_u32_e32 v144, s44, v187
	v_add_u32_e32 v170, s45, v187
	ds_read_b128 v[132:135], v144
	ds_read_b128 v[136:139], v144 offset:1024
	ds_read_b128 v[140:143], v144 offset:2048
	ds_read_b128 v[144:147], v144 offset:3072
	ds_read_b128 v[148:151], v170
	ds_read_b128 v[152:155], v170 offset:1024
	ds_read_b128 v[156:159], v170 offset:2048
	ds_read_b128 v[170:173], v170 offset:3072
	s_add_u32 s40, s50, 0xb0000
	s_addc_u32 s41, s51, 0
	s_mov_b32 m0, s58
	v_lshl_add_u64 v[232:233], s[40:41], 0, v[164:165]
	ds_read_b128 v[174:177], v194 offset:32768
	ds_read_b128 v[196:199], v194 offset:33792
	ds_read_b128 v[200:203], v194 offset:34816
	ds_read_b128 v[204:207], v194 offset:35840
	ds_read_b128 v[208:211], v194 offset:36864
	ds_read_b128 v[218:221], v194 offset:37888
	ds_read_b128 v[224:227], v194 offset:38912
	ds_read_b128 v[228:231], v194 offset:39936
	global_load_lds_dwordx4 v[232:233], off
	v_lshl_add_u64 v[232:233], s[40:41], 0, v[160:161]
	s_mov_b32 m0, s59
	s_nop 0
	global_load_lds_dwordx4 v[232:233], off
	s_waitcnt vmcnt(8)
	s_waitcnt lgkmcnt(0)
	s_barrier
	s_setprio 1
	s_waitcnt lgkmcnt(0)
	v_mfma_f32_16x16x32_bf16 v[128:131], v[132:135], v[174:177], v[128:131]
	v_mfma_f32_16x16x32_bf16 v[124:127], v[140:143], v[174:177], v[124:127]
	v_mfma_f32_16x16x32_bf16 v[112:115], v[132:135], v[200:203], v[112:115]
	v_mfma_f32_16x16x32_bf16 v[108:111], v[140:143], v[200:203], v[108:111]
	v_mfma_f32_16x16x32_bf16 v[96:99], v[132:135], v[208:211], v[96:99]
	v_mfma_f32_16x16x32_bf16 v[92:95], v[140:143], v[208:211], v[92:95]
	v_mfma_f32_16x16x32_bf16 v[80:83], v[132:135], v[224:227], v[80:83]
	v_mfma_f32_16x16x32_bf16 v[76:79], v[140:143], v[224:227], v[76:79]
	s_setprio 0
	s_setprio 1
	v_mfma_f32_16x16x32_bf16 v[128:131], v[136:139], v[196:199], v[128:131]
	v_mfma_f32_16x16x32_bf16 v[124:127], v[144:147], v[196:199], v[124:127]
	v_mfma_f32_16x16x32_bf16 v[112:115], v[136:139], v[204:207], v[112:115]
	v_mfma_f32_16x16x32_bf16 v[108:111], v[144:147], v[204:207], v[108:111]
	v_mfma_f32_16x16x32_bf16 v[96:99], v[136:139], v[218:221], v[96:99]
	v_mfma_f32_16x16x32_bf16 v[92:95], v[144:147], v[218:221], v[92:95]
	v_mfma_f32_16x16x32_bf16 v[80:83], v[136:139], v[228:231], v[80:83]
	v_mfma_f32_16x16x32_bf16 v[76:79], v[144:147], v[228:231], v[76:79]
	s_setprio 0
	s_setprio 1
	v_mfma_f32_16x16x32_bf16 v[120:123], v[148:151], v[174:177], v[120:123]
	v_mfma_f32_16x16x32_bf16 v[116:119], v[156:159], v[174:177], v[116:119]
	v_mfma_f32_16x16x32_bf16 v[104:107], v[148:151], v[200:203], v[104:107]
	v_mfma_f32_16x16x32_bf16 v[100:103], v[156:159], v[200:203], v[100:103]
	v_mfma_f32_16x16x32_bf16 v[88:91], v[148:151], v[208:211], v[88:91]
	v_mfma_f32_16x16x32_bf16 v[84:87], v[156:159], v[208:211], v[84:87]
	v_mfma_f32_16x16x32_bf16 v[72:75], v[148:151], v[224:227], v[72:75]
	v_mfma_f32_16x16x32_bf16 v[68:71], v[156:159], v[224:227], v[68:71]
	s_setprio 0
	s_setprio 1
	v_mfma_f32_16x16x32_bf16 v[120:123], v[152:155], v[196:199], v[120:123]
	v_mfma_f32_16x16x32_bf16 v[116:119], v[170:173], v[196:199], v[116:119]
	v_mfma_f32_16x16x32_bf16 v[104:107], v[152:155], v[204:207], v[104:107]
	v_mfma_f32_16x16x32_bf16 v[100:103], v[170:173], v[204:207], v[100:103]
	v_mfma_f32_16x16x32_bf16 v[88:91], v[152:155], v[218:221], v[88:91]
	v_mfma_f32_16x16x32_bf16 v[84:87], v[170:173], v[218:221], v[84:87]
	v_mfma_f32_16x16x32_bf16 v[72:75], v[152:155], v[228:231], v[72:75]
	v_mfma_f32_16x16x32_bf16 v[68:71], v[170:173], v[228:231], v[68:71]
	s_setprio 0
	s_barrier
	s_add_i32 s40, s44, s53
	v_lshl_add_u64 v[178:179], v[178:179], 0, s[94:95]
	s_mov_b32 m0, s40
	ds_read_b128 v[174:177], v194 offset:49152
	ds_read_b128 v[196:199], v194 offset:50176
	ds_read_b128 v[200:203], v194 offset:51200
	ds_read_b128 v[204:207], v194 offset:52224
	ds_read_b128 v[208:211], v194 offset:53248
	ds_read_b128 v[218:221], v194 offset:54272
	ds_read_b128 v[224:227], v194 offset:55296
	ds_read_b128 v[228:231], v194 offset:56320
	global_load_lds_dwordx4 v[178:179], off
	s_add_i32 m0, s40, 0x2000
	s_add_u32 s40, s48, 0xb0080
	v_lshl_add_u64 v[178:179], v[182:183], 0, s[94:95]
	s_addc_u32 s41, s49, 0
	s_add_i32 s44, s45, s53
	global_load_lds_dwordx4 v[178:179], off
	v_lshl_add_u64 v[178:179], s[40:41], 0, v[162:163]
	s_mov_b32 m0, s44
	s_nop 0
	global_load_lds_dwordx4 v[178:179], off
	v_lshl_add_u64 v[178:179], s[40:41], 0, v[0:1]
	s_add_i32 m0, s44, 0x2000
	s_nop 0
	global_load_lds_dwordx4 v[178:179], off
	v_lshl_add_u64 v[178:179], v[184:185], 0, s[94:95]
	s_mov_b32 m0, s64
	s_nop 0
	global_load_lds_dwordx4 v[178:179], off
	v_lshl_add_u64 v[178:179], v[190:191], 0, s[94:95]
	s_mov_b32 m0, s65
	s_nop 0
	global_load_lds_dwordx4 v[178:179], off
	s_waitcnt vmcnt(8)
	s_waitcnt lgkmcnt(0)
	s_barrier
	s_setprio 1
	s_waitcnt lgkmcnt(0)
	v_mfma_f32_16x16x32_bf16 v[64:67], v[132:135], v[174:177], v[64:67]
	v_mfma_f32_16x16x32_bf16 v[60:63], v[140:143], v[174:177], v[60:63]
	v_mfma_f32_16x16x32_bf16 v[48:51], v[132:135], v[200:203], v[48:51]
	v_mfma_f32_16x16x32_bf16 v[44:47], v[140:143], v[200:203], v[44:47]
	v_mfma_f32_16x16x32_bf16 v[32:35], v[132:135], v[208:211], v[32:35]
	v_mfma_f32_16x16x32_bf16 v[28:31], v[140:143], v[208:211], v[28:31]
	v_mfma_f32_16x16x32_bf16 v[16:19], v[132:135], v[224:227], v[16:19]
	v_mfma_f32_16x16x32_bf16 v[12:15], v[140:143], v[224:227], v[12:15]
	s_setprio 0
	s_setprio 1
	v_mfma_f32_16x16x32_bf16 v[64:67], v[136:139], v[196:199], v[64:67]
	v_mfma_f32_16x16x32_bf16 v[60:63], v[144:147], v[196:199], v[60:63]
	v_mfma_f32_16x16x32_bf16 v[48:51], v[136:139], v[204:207], v[48:51]
	v_mfma_f32_16x16x32_bf16 v[44:47], v[144:147], v[204:207], v[44:47]
	v_mfma_f32_16x16x32_bf16 v[32:35], v[136:139], v[218:221], v[32:35]
	v_mfma_f32_16x16x32_bf16 v[28:31], v[144:147], v[218:221], v[28:31]
	v_mfma_f32_16x16x32_bf16 v[16:19], v[136:139], v[228:231], v[16:19]
	v_mfma_f32_16x16x32_bf16 v[12:15], v[144:147], v[228:231], v[12:15]
	s_setprio 0
	s_setprio 1
	v_mfma_f32_16x16x32_bf16 v[56:59], v[148:151], v[174:177], v[56:59]
	v_mfma_f32_16x16x32_bf16 v[52:55], v[156:159], v[174:177], v[52:55]
	v_mfma_f32_16x16x32_bf16 v[40:43], v[148:151], v[200:203], v[40:43]
	v_mfma_f32_16x16x32_bf16 v[36:39], v[156:159], v[200:203], v[36:39]
	v_mfma_f32_16x16x32_bf16 v[24:27], v[148:151], v[208:211], v[24:27]
	v_mfma_f32_16x16x32_bf16 v[20:23], v[156:159], v[208:211], v[20:23]
	v_mfma_f32_16x16x32_bf16 v[8:11], v[148:151], v[224:227], v[8:11]
	v_mfma_f32_16x16x32_bf16 v[4:7], v[156:159], v[224:227], v[4:7]
	s_setprio 0
	s_setprio 1
	v_mfma_f32_16x16x32_bf16 v[56:59], v[152:155], v[196:199], v[56:59]
	v_mfma_f32_16x16x32_bf16 v[52:55], v[170:173], v[196:199], v[52:55]
	v_mfma_f32_16x16x32_bf16 v[40:43], v[152:155], v[204:207], v[40:43]
	v_mfma_f32_16x16x32_bf16 v[36:39], v[170:173], v[204:207], v[36:39]
	v_mfma_f32_16x16x32_bf16 v[24:27], v[152:155], v[218:221], v[24:27]
	v_mfma_f32_16x16x32_bf16 v[20:23], v[170:173], v[218:221], v[20:23]
	v_mfma_f32_16x16x32_bf16 v[8:11], v[152:155], v[228:231], v[8:11]
	v_mfma_f32_16x16x32_bf16 v[4:7], v[170:173], v[228:231], v[4:7]
	s_setprio 0
	s_barrier
	s_add_i32 s97, s97, 2
	s_add_u32 s89, s89, 0x100
	s_addc_u32 s90, s90, 0
	s_cmp_gt_u32 s97, 41
	s_mov_b64 s[44:45], s[46:47]
	s_cbranch_scc0 .LBB0_624
	s_and_b64 vcc, exec, s[18:19]
	s_cbranch_vccz .LBB0_627
	s_barrier

.LBB0_668:
	s_add_u32 s36, s26, 0x100
	s_addc_u32 s37, s27, 0
	s_add_i32 s40, 0, 0x10000
	s_cmp_eq_u32 s69, 40
	s_cselect_b32 s47, s11, s37
	s_cselect_b32 s46, s10, s36
	s_cselect_b32 s45, s19, s68
	s_cselect_b32 s44, s18, s65
	s_add_i32 s41, 0, 0x14000
	v_add_u32_e32 v144, s40, v187
	v_add_u32_e32 v160, s41, v187
	ds_read_b128 v[132:135], v144
	ds_read_b128 v[136:139], v144 offset:1024
	ds_read_b128 v[140:143], v144 offset:2048
	ds_read_b128 v[144:147], v144 offset:3072
	ds_read_b128 v[148:151], v160
	ds_read_b128 v[152:155], v160 offset:1024
	ds_read_b128 v[156:159], v160 offset:2048
	ds_read_b128 v[160:163], v160 offset:3072
	v_lshl_add_u64 v[182:183], s[26:27], 0, v[196:197]
	s_add_i32 m0, s49, 0xc000
	ds_read_b128 v[164:167], v229
	ds_read_b128 v[168:171], v229 offset:1024
	ds_read_b128 v[172:175], v229 offset:2048
	ds_read_b128 v[176:179], v229 offset:3072
	ds_read_b128 v[200:203], v229 offset:4096
	ds_read_b128 v[204:207], v229 offset:5120
	ds_read_b128 v[208:211], v229 offset:6144
	ds_read_b128 v[218:221], v229 offset:7168
	global_load_lds_dwordx4 v[182:183], off
	v_lshl_add_u64 v[182:183], s[26:27], 0, v[198:199]
	s_add_i32 m0, s49, 0xe000
	s_nop 0
	global_load_lds_dwordx4 v[182:183], off
	s_waitcnt vmcnt(8)
	s_waitcnt lgkmcnt(0)
	s_barrier
	s_setprio 1
	s_waitcnt lgkmcnt(0)
	v_mfma_f32_16x16x32_bf16 v[128:131], v[132:135], v[164:167], v[128:131]
	v_mfma_f32_16x16x32_bf16 v[124:127], v[140:143], v[164:167], v[124:127]
	v_mfma_f32_16x16x32_bf16 v[112:115], v[132:135], v[172:175], v[112:115]
	v_mfma_f32_16x16x32_bf16 v[108:111], v[140:143], v[172:175], v[108:111]
	v_mfma_f32_16x16x32_bf16 v[96:99], v[132:135], v[200:203], v[96:99]
	v_mfma_f32_16x16x32_bf16 v[92:95], v[140:143], v[200:203], v[92:95]
	v_mfma_f32_16x16x32_bf16 v[80:83], v[132:135], v[208:211], v[80:83]
	v_mfma_f32_16x16x32_bf16 v[76:79], v[140:143], v[208:211], v[76:79]
	s_setprio 0
	s_setprio 1
	v_mfma_f32_16x16x32_bf16 v[128:131], v[136:139], v[168:171], v[128:131]
	v_mfma_f32_16x16x32_bf16 v[124:127], v[144:147], v[168:171], v[124:127]
	v_mfma_f32_16x16x32_bf16 v[112:115], v[136:139], v[176:179], v[112:115]
	v_mfma_f32_16x16x32_bf16 v[108:111], v[144:147], v[176:179], v[108:111]
	v_mfma_f32_16x16x32_bf16 v[96:99], v[136:139], v[204:207], v[96:99]
	v_mfma_f32_16x16x32_bf16 v[92:95], v[144:147], v[204:207], v[92:95]
	v_mfma_f32_16x16x32_bf16 v[80:83], v[136:139], v[218:221], v[80:83]
	v_mfma_f32_16x16x32_bf16 v[76:79], v[144:147], v[218:221], v[76:79]
	s_setprio 0
	s_setprio 1
	v_mfma_f32_16x16x32_bf16 v[120:123], v[148:151], v[164:167], v[120:123]
	v_mfma_f32_16x16x32_bf16 v[116:119], v[156:159], v[164:167], v[116:119]
	v_mfma_f32_16x16x32_bf16 v[104:107], v[148:151], v[172:175], v[104:107]
	v_mfma_f32_16x16x32_bf16 v[100:103], v[156:159], v[172:175], v[100:103]
	v_mfma_f32_16x16x32_bf16 v[88:91], v[148:151], v[200:203], v[88:91]
	v_mfma_f32_16x16x32_bf16 v[84:87], v[156:159], v[200:203], v[84:87]
	v_mfma_f32_16x16x32_bf16 v[72:75], v[148:151], v[208:211], v[72:75]
	v_mfma_f32_16x16x32_bf16 v[68:71], v[156:159], v[208:211], v[68:71]
	s_setprio 0
	s_setprio 1
	v_mfma_f32_16x16x32_bf16 v[120:123], v[152:155], v[168:171], v[120:123]
	v_mfma_f32_16x16x32_bf16 v[116:119], v[160:163], v[168:171], v[116:119]
	v_mfma_f32_16x16x32_bf16 v[104:107], v[152:155], v[176:179], v[104:107]
	v_mfma_f32_16x16x32_bf16 v[100:103], v[160:163], v[176:179], v[100:103]
	v_mfma_f32_16x16x32_bf16 v[88:91], v[152:155], v[204:207], v[88:91]
	v_mfma_f32_16x16x32_bf16 v[84:87], v[160:163], v[204:207], v[84:87]
	v_mfma_f32_16x16x32_bf16 v[72:75], v[152:155], v[218:221], v[72:75]
	v_mfma_f32_16x16x32_bf16 v[68:71], v[160:163], v[218:221], v[68:71]
	s_setprio 0
	s_barrier
	s_add_i32 s26, s40, s48
	v_lshl_add_u64 v[182:183], s[44:45], 0, v[192:193]
	s_mov_b32 m0, s26
	ds_read_b128 v[164:167], v229 offset:16384
	ds_read_b128 v[168:171], v229 offset:17408
	ds_read_b128 v[172:175], v229 offset:18432
	ds_read_b128 v[176:179], v229 offset:19456
	ds_read_b128 v[200:203], v229 offset:20480
	ds_read_b128 v[204:207], v229 offset:21504
	ds_read_b128 v[208:211], v229 offset:22528
	ds_read_b128 v[218:221], v229 offset:23552
	global_load_lds_dwordx4 v[182:183], off
	s_add_i32 m0, s26, 0x2000
	s_add_u32 s26, s44, 0xb0000
	v_lshl_add_u64 v[184:185], s[44:45], 0, v[0:1]
	s_addc_u32 s27, s45, 0
	s_add_i32 s40, s41, s48
	global_load_lds_dwordx4 v[184:185], off
	v_lshl_add_u64 v[224:225], s[26:27], 0, v[192:193]
	s_mov_b32 m0, s40
	v_lshl_add_u64 v[230:231], s[46:47], 0, v[190:191]
	global_load_lds_dwordx4 v[224:225], off
	v_lshl_add_u64 v[224:225], s[26:27], 0, v[0:1]
	s_add_i32 m0, s40, 0x2000
	s_nop 0
	global_load_lds_dwordx4 v[224:225], off
	v_lshl_add_u64 v[224:225], s[46:47], 0, v[194:195]
	s_mov_b32 m0, s49
	s_nop 0
	global_load_lds_dwordx4 v[224:225], off
	s_mov_b32 m0, s50
	s_nop 0
	global_load_lds_dwordx4 v[230:231], off
	s_waitcnt vmcnt(8)
	s_waitcnt lgkmcnt(0)
	s_barrier
	s_setprio 1
	s_waitcnt lgkmcnt(0)
	v_mfma_f32_16x16x32_bf16 v[64:67], v[132:135], v[164:167], v[64:67]
	v_mfma_f32_16x16x32_bf16 v[60:63], v[140:143], v[164:167], v[60:63]
	v_mfma_f32_16x16x32_bf16 v[48:51], v[132:135], v[172:175], v[48:51]
	v_mfma_f32_16x16x32_bf16 v[44:47], v[140:143], v[172:175], v[44:47]
	v_mfma_f32_16x16x32_bf16 v[32:35], v[132:135], v[200:203], v[32:35]
	v_mfma_f32_16x16x32_bf16 v[28:31], v[140:143], v[200:203], v[28:31]
	v_mfma_f32_16x16x32_bf16 v[16:19], v[132:135], v[208:211], v[16:19]
	v_mfma_f32_16x16x32_bf16 v[12:15], v[140:143], v[208:211], v[12:15]
	s_setprio 0
	s_setprio 1
	v_mfma_f32_16x16x32_bf16 v[64:67], v[136:139], v[168:171], v[64:67]
	v_mfma_f32_16x16x32_bf16 v[60:63], v[144:147], v[168:171], v[60:63]
	v_mfma_f32_16x16x32_bf16 v[48:51], v[136:139], v[176:179], v[48:51]
	v_mfma_f32_16x16x32_bf16 v[44:47], v[144:147], v[176:179], v[44:47]
	v_mfma_f32_16x16x32_bf16 v[32:35], v[136:139], v[204:207], v[32:35]
	v_mfma_f32_16x16x32_bf16 v[28:31], v[144:147], v[204:207], v[28:31]
	v_mfma_f32_16x16x32_bf16 v[16:19], v[136:139], v[218:221], v[16:19]
	v_mfma_f32_16x16x32_bf16 v[12:15], v[144:147], v[218:221], v[12:15]
	s_setprio 0
	s_setprio 1
	v_mfma_f32_16x16x32_bf16 v[56:59], v[148:151], v[164:167], v[56:59]
	v_mfma_f32_16x16x32_bf16 v[52:55], v[156:159], v[164:167], v[52:55]
	v_mfma_f32_16x16x32_bf16 v[40:43], v[148:151], v[172:175], v[40:43]
	v_mfma_f32_16x16x32_bf16 v[36:39], v[156:159], v[172:175], v[36:39]
	v_mfma_f32_16x16x32_bf16 v[24:27], v[148:151], v[200:203], v[24:27]
	v_mfma_f32_16x16x32_bf16 v[20:23], v[156:159], v[200:203], v[20:23]
	v_mfma_f32_16x16x32_bf16 v[8:11], v[148:151], v[208:211], v[8:11]
	v_mfma_f32_16x16x32_bf16 v[4:7], v[156:159], v[208:211], v[4:7]
	s_setprio 0
	s_setprio 1
	v_mfma_f32_16x16x32_bf16 v[56:59], v[152:155], v[168:171], v[56:59]
	v_mfma_f32_16x16x32_bf16 v[52:55], v[160:163], v[168:171], v[52:55]
	v_mfma_f32_16x16x32_bf16 v[40:43], v[152:155], v[176:179], v[40:43]
	v_mfma_f32_16x16x32_bf16 v[36:39], v[160:163], v[176:179], v[36:39]
	v_mfma_f32_16x16x32_bf16 v[24:27], v[152:155], v[204:207], v[24:27]
	v_mfma_f32_16x16x32_bf16 v[20:23], v[160:163], v[204:207], v[20:23]
	v_mfma_f32_16x16x32_bf16 v[8:11], v[152:155], v[218:221], v[8:11]
	v_mfma_f32_16x16x32_bf16 v[4:7], v[160:163], v[218:221], v[4:7]
	s_setprio 0
	s_barrier
	s_add_i32 s40, 0, 0x18000
	s_add_i32 s41, 0, 0x1c000
	v_add_u32_e32 v144, s40, v187
	v_add_u32_e32 v160, s41, v187
	ds_read_b128 v[132:135], v144
	ds_read_b128 v[136:139], v144 offset:1024
	ds_read_b128 v[140:143], v144 offset:2048
	ds_read_b128 v[144:147], v144 offset:3072
	ds_read_b128 v[148:151], v160
	ds_read_b128 v[152:155], v160 offset:1024
	ds_read_b128 v[156:159], v160 offset:2048
	ds_read_b128 v[160:163], v160 offset:3072
	s_add_u32 s26, s46, 0xb0000
	s_addc_u32 s27, s47, 0
	s_mov_b32 m0, s51
	v_lshl_add_u64 v[232:233], s[26:27], 0, v[194:195]
	ds_read_b128 v[164:167], v229 offset:32768
	ds_read_b128 v[168:171], v229 offset:33792
	ds_read_b128 v[172:175], v229 offset:34816
	ds_read_b128 v[176:179], v229 offset:35840
	ds_read_b128 v[200:203], v229 offset:36864
	ds_read_b128 v[204:207], v229 offset:37888
	ds_read_b128 v[208:211], v229 offset:38912
	ds_read_b128 v[218:221], v229 offset:39936
	global_load_lds_dwordx4 v[232:233], off
	v_lshl_add_u64 v[232:233], s[26:27], 0, v[190:191]
	s_mov_b32 m0, s53
	s_nop 0
	global_load_lds_dwordx4 v[232:233], off
	s_waitcnt vmcnt(8)
	s_waitcnt lgkmcnt(0)
	s_barrier
	s_setprio 1
	s_waitcnt lgkmcnt(0)
	v_mfma_f32_16x16x32_bf16 v[128:131], v[132:135], v[164:167], v[128:131]
	v_mfma_f32_16x16x32_bf16 v[124:127], v[140:143], v[164:167], v[124:127]
	v_mfma_f32_16x16x32_bf16 v[112:115], v[132:135], v[172:175], v[112:115]
	v_mfma_f32_16x16x32_bf16 v[108:111], v[140:143], v[172:175], v[108:111]
	v_mfma_f32_16x16x32_bf16 v[96:99], v[132:135], v[200:203], v[96:99]
	v_mfma_f32_16x16x32_bf16 v[92:95], v[140:143], v[200:203], v[92:95]
	v_mfma_f32_16x16x32_bf16 v[80:83], v[132:135], v[208:211], v[80:83]
	v_mfma_f32_16x16x32_bf16 v[76:79], v[140:143], v[208:211], v[76:79]
	s_setprio 0
	s_setprio 1
	v_mfma_f32_16x16x32_bf16 v[128:131], v[136:139], v[168:171], v[128:131]
	v_mfma_f32_16x16x32_bf16 v[124:127], v[144:147], v[168:171], v[124:127]
	v_mfma_f32_16x16x32_bf16 v[112:115], v[136:139], v[176:179], v[112:115]
	v_mfma_f32_16x16x32_bf16 v[108:111], v[144:147], v[176:179], v[108:111]
	v_mfma_f32_16x16x32_bf16 v[96:99], v[136:139], v[204:207], v[96:99]
	v_mfma_f32_16x16x32_bf16 v[92:95], v[144:147], v[204:207], v[92:95]
	v_mfma_f32_16x16x32_bf16 v[80:83], v[136:139], v[218:221], v[80:83]
	v_mfma_f32_16x16x32_bf16 v[76:79], v[144:147], v[218:221], v[76:79]
	s_setprio 0
	s_setprio 1
	v_mfma_f32_16x16x32_bf16 v[120:123], v[148:151], v[164:167], v[120:123]
	v_mfma_f32_16x16x32_bf16 v[116:119], v[156:159], v[164:167], v[116:119]
	v_mfma_f32_16x16x32_bf16 v[104:107], v[148:151], v[172:175], v[104:107]
	v_mfma_f32_16x16x32_bf16 v[100:103], v[156:159], v[172:175], v[100:103]
	v_mfma_f32_16x16x32_bf16 v[88:91], v[148:151], v[200:203], v[88:91]
	v_mfma_f32_16x16x32_bf16 v[84:87], v[156:159], v[200:203], v[84:87]
	v_mfma_f32_16x16x32_bf16 v[72:75], v[148:151], v[208:211], v[72:75]
	v_mfma_f32_16x16x32_bf16 v[68:71], v[156:159], v[208:211], v[68:71]
	s_setprio 0
	s_setprio 1
	v_mfma_f32_16x16x32_bf16 v[120:123], v[152:155], v[168:171], v[120:123]
	v_mfma_f32_16x16x32_bf16 v[116:119], v[160:163], v[168:171], v[116:119]
	v_mfma_f32_16x16x32_bf16 v[104:107], v[152:155], v[176:179], v[104:107]
	v_mfma_f32_16x16x32_bf16 v[100:103], v[160:163], v[176:179], v[100:103]
	v_mfma_f32_16x16x32_bf16 v[88:91], v[152:155], v[204:207], v[88:91]
	v_mfma_f32_16x16x32_bf16 v[84:87], v[160:163], v[204:207], v[84:87]
	v_mfma_f32_16x16x32_bf16 v[72:75], v[152:155], v[218:221], v[72:75]
	v_mfma_f32_16x16x32_bf16 v[68:71], v[160:163], v[218:221], v[68:71]
	s_setprio 0
	s_barrier
	s_add_i32 s26, s40, s48
	v_lshl_add_u64 v[182:183], v[182:183], 0, s[94:95]
	s_mov_b32 m0, s26
	ds_read_b128 v[164:167], v229 offset:49152
	ds_read_b128 v[168:171], v229 offset:50176
	ds_read_b128 v[172:175], v229 offset:51200
	ds_read_b128 v[176:179], v229 offset:52224
	ds_read_b128 v[200:203], v229 offset:53248
	ds_read_b128 v[204:207], v229 offset:54272
	ds_read_b128 v[208:211], v229 offset:55296
	ds_read_b128 v[218:221], v229 offset:56320
	global_load_lds_dwordx4 v[182:183], off
	s_add_i32 m0, s26, 0x2000
	s_add_u32 s26, s44, 0xb0080
	v_lshl_add_u64 v[182:183], v[184:185], 0, s[94:95]
	s_addc_u32 s27, s45, 0
	s_add_i32 s40, s41, s48
	global_load_lds_dwordx4 v[182:183], off
	v_lshl_add_u64 v[182:183], s[26:27], 0, v[192:193]
	s_mov_b32 m0, s40
	s_nop 0
	global_load_lds_dwordx4 v[182:183], off
	v_lshl_add_u64 v[182:183], s[26:27], 0, v[0:1]
	s_add_i32 m0, s40, 0x2000
	s_nop 0
	global_load_lds_dwordx4 v[182:183], off
	v_lshl_add_u64 v[182:183], v[224:225], 0, s[94:95]
	s_mov_b32 m0, s54
	s_nop 0
	global_load_lds_dwordx4 v[182:183], off
	v_lshl_add_u64 v[182:183], v[230:231], 0, s[94:95]
	s_mov_b32 m0, s55
	s_nop 0
	global_load_lds_dwordx4 v[182:183], off
	s_waitcnt vmcnt(8)
	s_waitcnt lgkmcnt(0)
	s_barrier
	s_setprio 1
	s_waitcnt lgkmcnt(0)
	v_mfma_f32_16x16x32_bf16 v[64:67], v[132:135], v[164:167], v[64:67]
	v_mfma_f32_16x16x32_bf16 v[60:63], v[140:143], v[164:167], v[60:63]
	v_mfma_f32_16x16x32_bf16 v[48:51], v[132:135], v[172:175], v[48:51]
	v_mfma_f32_16x16x32_bf16 v[44:47], v[140:143], v[172:175], v[44:47]
	v_mfma_f32_16x16x32_bf16 v[32:35], v[132:135], v[200:203], v[32:35]
	v_mfma_f32_16x16x32_bf16 v[28:31], v[140:143], v[200:203], v[28:31]
	v_mfma_f32_16x16x32_bf16 v[16:19], v[132:135], v[208:211], v[16:19]
	v_mfma_f32_16x16x32_bf16 v[12:15], v[140:143], v[208:211], v[12:15]
	s_setprio 0
	s_setprio 1
	v_mfma_f32_16x16x32_bf16 v[64:67], v[136:139], v[168:171], v[64:67]
	v_mfma_f32_16x16x32_bf16 v[60:63], v[144:147], v[168:171], v[60:63]
	v_mfma_f32_16x16x32_bf16 v[48:51], v[136:139], v[176:179], v[48:51]
	v_mfma_f32_16x16x32_bf16 v[44:47], v[144:147], v[176:179], v[44:47]
	v_mfma_f32_16x16x32_bf16 v[32:35], v[136:139], v[204:207], v[32:35]
	v_mfma_f32_16x16x32_bf16 v[28:31], v[144:147], v[204:207], v[28:31]
	v_mfma_f32_16x16x32_bf16 v[16:19], v[136:139], v[218:221], v[16:19]
	v_mfma_f32_16x16x32_bf16 v[12:15], v[144:147], v[218:221], v[12:15]
	s_setprio 0
	s_setprio 1
	v_mfma_f32_16x16x32_bf16 v[56:59], v[148:151], v[164:167], v[56:59]
	v_mfma_f32_16x16x32_bf16 v[52:55], v[156:159], v[164:167], v[52:55]
	v_mfma_f32_16x16x32_bf16 v[40:43], v[148:151], v[172:175], v[40:43]
	v_mfma_f32_16x16x32_bf16 v[36:39], v[156:159], v[172:175], v[36:39]
	v_mfma_f32_16x16x32_bf16 v[24:27], v[148:151], v[200:203], v[24:27]
	v_mfma_f32_16x16x32_bf16 v[20:23], v[156:159], v[200:203], v[20:23]
	v_mfma_f32_16x16x32_bf16 v[8:11], v[148:151], v[208:211], v[8:11]
	v_mfma_f32_16x16x32_bf16 v[4:7], v[156:159], v[208:211], v[4:7]
	s_setprio 0
	s_setprio 1
	v_mfma_f32_16x16x32_bf16 v[56:59], v[152:155], v[168:171], v[56:59]
	v_mfma_f32_16x16x32_bf16 v[52:55], v[160:163], v[168:171], v[52:55]
	v_mfma_f32_16x16x32_bf16 v[40:43], v[152:155], v[176:179], v[40:43]
	v_mfma_f32_16x16x32_bf16 v[36:39], v[160:163], v[176:179], v[36:39]
	v_mfma_f32_16x16x32_bf16 v[24:27], v[152:155], v[204:207], v[24:27]
	v_mfma_f32_16x16x32_bf16 v[20:23], v[160:163], v[204:207], v[20:23]
	v_mfma_f32_16x16x32_bf16 v[8:11], v[152:155], v[218:221], v[8:11]
	v_mfma_f32_16x16x32_bf16 v[4:7], v[160:163], v[218:221], v[4:7]
	s_setprio 0
	s_barrier
	s_add_i32 s69, s69, 2
	s_add_u32 s65, s65, 0x100
	s_addc_u32 s68, s68, 0
	s_cmp_gt_u32 s69, 41
	s_mov_b64 s[26:27], s[36:37]
	s_cbranch_scc0 .LBB0_668
	s_and_b64 vcc, exec, s[14:15]
	s_cbranch_vccz .LBB0_671
	s_barrier
